# pooling: 256 per-(output,tap) window masks replaced by 3 per-lane window-class weights; out-of-range border rows zeroed once per run instead
# speedup vs baseline: 1.0016x; 1.0016x over previous
; __device__ __forceinline__ void phase_mixer(const Params& p, LAS unsigned char* lds, int l, bool with_ctx, int G, int tid, int wave, int lane, int rep_attn, int rep_pool) {
;     ...
;     const int grp = lane >> 4, lo = 1 << grp, hi = lo - 1;
; #pragma unroll 1
;     for (int rp = 0; rp < rep_pool; ++rp)
; #pragma unroll 1
;     for (int run = gw; run < nrun; run += NGW) {
;         const int tok0 = run * 16; const bool isl = tok0 < ML;
;         const int base = isl ? (tok0 & ~(SEQ - 1)) : (ML + ((tok0 - ML) & ~(CT - 1))), len = isl ? SEQ : CT, t0 = tok0 - base;
;         u32x4 w[31];
; #pragma unroll
;         for (int i = 0; i < 31; ++i) { const int tt = min(max(t0 - 8 + i, 0), len - 1); w[i] = *(const u32x4*)(PB + (size_t)(base + tt) * PBW + 8 * lane); }
; #pragma unroll
;         for (int o = 0; o < 16; ++o) {
;             const int t = t0 + o, st = max(t - lo, 0), en = min(t + hi + 1, len);
;             float acc[8];
; #pragma unroll
;             for (int e = 0; e < 8; ++e) acc[e] = 0.f;
; #pragma unroll
;             for (int i = 0; i < 16; ++i) { const int tt = t + i - 8; const float wt = (tt >= st && tt < en) ? 1.f : 0.f; const u32x4 ww = w[o + i];
.LBB0_306:
	v_readlane_b32 s4, v254, 22
	s_add_i32 s6, s87, s4
	s_and_b64 s[4:5], s[36:37], exec
	s_movk_i32 s4, 0x880
	s_cselect_b32 s7, s4, 0x800
	s_cmp_ge_i32 s6, s7
	s_cbranch_scc1 .LBB0_309
	v_lshlrev_b32_e32 v156, 4, v168
	v_lshlrev_b32_e64 v167, v106, 1
	v_cmp_le_u32_e32 vcc, 2, v167
	v_cndmask_b32_e64 v228, 0, 1.0, vcc
	v_cmp_le_u32_e32 vcc, 4, v167
	v_cndmask_b32_e64 v230, 0, 1.0, vcc
	v_cmp_le_u32_e32 vcc, 8, v167
	v_cndmask_b32_e64 v232, 0, 1.0, vcc
	v_mov_b32_e32 v234, 1.0
	v_lshl_add_u64 v[124:125], s[0:1], 0, v[156:157]
	v_lshl_add_u64 v[126:127], s[26:27], 0, v[156:157]
.LBB0_308:
	s_lshl_b32 s4, s6, 4
	s_cmpk_lt_i32 s6, 0x800
	s_movk_i32 s0, 0x1000
	s_cselect_b32 s9, s0, 0x100
	s_movk_i32 s0, 0xf000
	s_cselect_b32 s0, s0, 0x7fffff00
	s_and_b32 s1, s0, s4
	s_sub_i32 s8, s4, s1
	v_mov_b32_e32 v238, -1
	v_mov_b32_e32 v242, -1
	s_cmp_lg_u32 s8, 0
	s_cbranch_scc1 .Lpool_f_ok
	v_mov_b32_e32 v238, 0
.Lpool_f_ok:
	s_add_i32 s0, s9, -16
	s_cmp_lg_u32 s8, s0
	s_cbranch_scc1 .Lpool_b_ok
	v_mov_b32_e32 v242, 0
.Lpool_b_ok:
	s_add_i32 s0, s8, -8
	s_add_i32 s5, s9, -1
	s_max_i32 s10, s0, 0
	s_min_u32 s10, s10, s5
	s_add_i32 s10, s10, s1
	s_waitcnt vmcnt(0)
	v_mad_i64_i32 v[0:1], s[10:11], s10, v223, v[124:125]
	s_add_i32 s33, s8, -7
	s_max_i32 s10, s33, 0
	s_min_u32 s10, s10, s5
	s_add_i32 s10, s10, s1
	global_load_dwordx4 v[84:87], v[0:1], off
	v_mad_i64_i32 v[0:1], s[10:11], s10, v223, v[124:125]
	s_add_i32 s25, s8, -6
	s_max_i32 s10, s25, 0
	s_min_u32 s10, s10, s5
	s_add_i32 s10, s10, s1
	global_load_dwordx4 v[88:91], v[0:1], off
	v_mad_i64_i32 v[0:1], s[10:11], s10, v223, v[124:125]
	s_add_i32 s24, s8, -5
	s_max_i32 s10, s24, 0
	s_min_u32 s10, s10, s5
	s_add_i32 s10, s10, s1
	global_load_dwordx4 v[92:95], v[0:1], off
	v_mad_i64_i32 v[0:1], s[10:11], s10, v223, v[124:125]
	s_add_i32 s30, s8, -4
	s_max_i32 s10, s30, 0
	s_min_u32 s10, s10, s5
	s_add_i32 s10, s10, s1
	global_load_dwordx4 v[96:99], v[0:1], off
	v_mad_i64_i32 v[0:1], s[10:11], s10, v223, v[124:125]
	s_add_i32 s29, s8, -3
	s_max_i32 s10, s29, 0
	s_min_u32 s10, s10, s5
	s_add_i32 s10, s10, s1
	global_load_dwordx4 v[100:103], v[0:1], off
	v_mad_i64_i32 v[0:1], s[10:11], s10, v223, v[124:125]
	s_add_i32 s28, s8, -2
	s_max_i32 s10, s28, 0
	s_min_u32 s10, s10, s5
	s_add_i32 s10, s10, s1
	global_load_dwordx4 v[104:107], v[0:1], off
	v_mad_i64_i32 v[0:1], s[10:11], s10, v223, v[124:125]
	s_add_i32 s27, s8, -1
	s_max_i32 s10, s27, 0
	s_min_u32 s10, s10, s5
	s_add_i32 s10, s10, s1
	global_load_dwordx4 v[108:111], v[0:1], off
	v_mad_i64_i32 v[0:1], s[10:11], s10, v223, v[124:125]
	s_max_i32 s10, s8, 0
	s_min_u32 s10, s10, s5
	s_add_i32 s10, s10, s1
	global_load_dwordx4 v[112:115], v[0:1], off
	v_mad_i64_i32 v[0:1], s[10:11], s10, v223, v[124:125]
	s_or_b32 s26, s8, 1
	s_max_i32 s10, s26, 0
	s_min_u32 s10, s10, s5
	s_add_i32 s10, s10, s1
	global_load_dwordx4 v[80:83], v[0:1], off
	v_mad_i64_i32 v[0:1], s[10:11], s10, v223, v[124:125]
	s_or_b32 s23, s8, 2
	s_max_i32 s10, s23, 0
	s_min_u32 s10, s10, s5
	s_add_i32 s10, s10, s1
	global_load_dwordx4 v[116:119], v[0:1], off
	v_mad_i64_i32 v[0:1], s[10:11], s10, v223, v[124:125]
	s_or_b32 s22, s8, 3
	s_max_i32 s10, s22, 0
	s_min_u32 s10, s10, s5
	s_add_i32 s10, s10, s1
	global_load_dwordx4 v[120:123], v[0:1], off
	v_mad_i64_i32 v[0:1], s[10:11], s10, v223, v[124:125]
	s_or_b32 s21, s8, 4
	s_max_i32 s10, s21, 0
	s_min_u32 s10, s10, s5
	s_add_i32 s10, s10, s1
	global_load_dwordx4 v[60:63], v[0:1], off
	v_mad_i64_i32 v[0:1], s[10:11], s10, v223, v[124:125]
	s_or_b32 s20, s8, 5
	s_max_i32 s10, s20, 0
	s_min_u32 s10, s10, s5
	s_add_i32 s10, s10, s1
	global_load_dwordx4 v[64:67], v[0:1], off
	v_mad_i64_i32 v[0:1], s[10:11], s10, v223, v[124:125]
	s_or_b32 s19, s8, 6
	s_max_i32 s10, s19, 0
	s_min_u32 s10, s10, s5
	s_add_i32 s10, s10, s1
	global_load_dwordx4 v[68:71], v[0:1], off
	v_mad_i64_i32 v[0:1], s[10:11], s10, v223, v[124:125]
	s_or_b32 s10, s8, 7
	s_max_i32 s11, s10, 0
	s_min_u32 s11, s11, s5
	s_add_i32 s11, s11, s1
	global_load_dwordx4 v[72:75], v[0:1], off
	v_mad_i64_i32 v[0:1], s[12:13], s11, v223, v[124:125]
	s_or_b32 s11, s8, 8
	s_max_i32 s12, s11, 0
	s_min_u32 s12, s12, s5
	s_add_i32 s12, s12, s1
	global_load_dwordx4 v[76:79], v[0:1], off
	v_mad_i64_i32 v[0:1], s[12:13], s12, v223, v[124:125]
	s_or_b32 s12, s8, 9
	s_max_i32 s13, s12, 0
	s_min_u32 s13, s13, s5
	s_add_i32 s13, s13, s1
	global_load_dwordx4 v[56:59], v[0:1], off
	v_mad_i64_i32 v[0:1], s[14:15], s13, v223, v[124:125]
	s_or_b32 s13, s8, 10
	s_max_i32 s14, s13, 0
	s_min_u32 s14, s14, s5
	s_add_i32 s14, s14, s1
	global_load_dwordx4 v[52:55], v[0:1], off
	v_mad_i64_i32 v[0:1], s[14:15], s14, v223, v[124:125]
	s_or_b32 s14, s8, 11
	s_max_i32 s15, s14, 0
	s_min_u32 s15, s15, s5
	s_add_i32 s15, s15, s1
	global_load_dwordx4 v[48:51], v[0:1], off
	v_mad_i64_i32 v[0:1], s[16:17], s15, v223, v[124:125]
	s_or_b32 s15, s8, 12
	s_max_i32 s16, s15, 0
	s_min_u32 s16, s16, s5
	s_add_i32 s16, s16, s1
	global_load_dwordx4 v[44:47], v[0:1], off
	v_mad_i64_i32 v[0:1], s[16:17], s16, v223, v[124:125]
	s_or_b32 s17, s8, 13
	s_max_i32 s16, s17, 0
	s_min_u32 s16, s16, s5
	s_add_i32 s16, s16, s1
	global_load_dwordx4 v[40:43], v[0:1], off
	v_mad_i64_i32 v[0:1], s[62:63], s16, v223, v[124:125]
	s_or_b32 s16, s8, 14
	s_max_i32 s18, s16, 0
	s_min_u32 s18, s18, s5
	s_add_i32 s18, s18, s1
	global_load_dwordx4 v[36:39], v[0:1], off
	v_mad_i64_i32 v[0:1], s[62:63], s18, v223, v[124:125]
	s_or_b32 s18, s8, 15
	s_max_i32 s53, s18, 0
	s_min_u32 s53, s53, s5
	s_add_i32 s53, s53, s1
	global_load_dwordx4 v[32:35], v[0:1], off
	v_mad_i64_i32 v[0:1], s[62:63], s53, v223, v[124:125]
	s_max_i32 s53, s8, -16
	s_add_i32 s53, s53, 16
	s_min_u32 s53, s53, s5
	s_add_i32 s53, s53, s1
	global_load_dwordx4 v[28:31], v[0:1], off
	v_mad_i64_i32 v[0:1], s[62:63], s53, v223, v[124:125]
	s_max_i32 s53, s8, 0xffffffef
	s_add_i32 s53, s53, 17
	s_min_u32 s53, s53, s5
	s_add_i32 s53, s53, s1
	global_load_dwordx4 v[24:27], v[0:1], off
	v_mad_i64_i32 v[0:1], s[62:63], s53, v223, v[124:125]
	s_max_i32 s53, s8, 0xffffffee
	s_add_i32 s53, s53, 18
	s_min_u32 s53, s53, s5
	s_add_i32 s53, s53, s1
	global_load_dwordx4 v[20:23], v[0:1], off
	v_mad_i64_i32 v[0:1], s[62:63], s53, v223, v[124:125]
	s_max_i32 s53, s8, 0xffffffed
	s_add_i32 s53, s53, 19
	s_min_u32 s53, s53, s5
	s_add_i32 s53, s53, s1
	global_load_dwordx4 v[16:19], v[0:1], off
	v_mad_i64_i32 v[0:1], s[62:63], s53, v223, v[124:125]
	s_max_i32 s53, s8, 0xffffffec
	s_add_i32 s53, s53, 20
	s_min_u32 s53, s53, s5
	s_add_i32 s53, s53, s1
	global_load_dwordx4 v[12:15], v[0:1], off
	v_mad_i64_i32 v[0:1], s[62:63], s53, v223, v[124:125]
	s_max_i32 s53, s8, 0xffffffeb
	s_add_i32 s53, s53, 21
	s_min_u32 s53, s53, s5
	s_add_i32 s53, s53, s1
	global_load_dwordx4 v[8:11], v[0:1], off
	v_mad_i64_i32 v[0:1], s[62:63], s53, v223, v[124:125]
	s_max_i32 s53, s8, 0xffffffea
	s_add_i32 s53, s53, 22
	v_sub_u32_e32 v128, s8, v167
	v_or_b32_e32 v129, s8, v167
	s_min_u32 s5, s53, s5
	v_max_i32_e32 v135, 0, v128
	v_min_i32_e32 v156, s9, v129
	s_add_i32 s5, s5, s1
	s_waitcnt vmcnt(28)
; __device__ __forceinline__ float bf_lo(unsigned w) { return __uint_as_float(w << 16); }
; __device__ __forceinline__ float bf_hi(unsigned w) { return __uint_as_float(w & 0xffff0000u); }
; __device__ __forceinline__ void phase_mixer(const Params& p, LAS unsigned char* lds, int l, bool with_ctx, int G, int tid, int wave, int lane, int rep_attn, int rep_pool) {
;     ...
;         for (int o = 0; o < 16; ++o) {
;             const int t = t0 + o, st = max(t - lo, 0), en = min(t + hi + 1, len);
;             float acc[8];
; #pragma unroll
;             for (int e = 0; e < 8; ++e) acc[e] = 0.f;
; #pragma unroll
;             for (int i = 0; i < 16; ++i) { const int tt = t + i - 8; const float wt = (tt >= st && tt < en) ? 1.f : 0.f; const u32x4 ww = w[o + i];
;                 acc[0] += wt * bf_lo(ww.x); acc[1] += wt * bf_hi(ww.x); acc[2] += wt * bf_lo(ww.y); acc[3] += wt * bf_hi(ww.y);
;                 acc[4] += wt * bf_lo(ww.z); acc[5] += wt * bf_hi(ww.z); acc[6] += wt * bf_lo(ww.w); acc[7] += wt * bf_hi(ww.w); }
	v_and_b32_e32 v84, v238, v84
	v_and_b32_e32 v85, v238, v85
	v_and_b32_e32 v86, v238, v86
	v_and_b32_e32 v87, v238, v87
	v_lshlrev_b32_e32 v136, 16, v84
	v_and_b32_e32 v137, 0xffff0000, v84
	v_pk_fma_f32 v[136:137], v[232:233], v[136:137], 0 op_sel_hi:[0,1,0]
	s_waitcnt vmcnt(27)
	v_and_b32_e32 v88, v238, v88
	v_and_b32_e32 v89, v238, v89
	v_and_b32_e32 v90, v238, v90
	v_and_b32_e32 v91, v238, v91
	v_lshlrev_b32_e32 v204, 16, v88
	v_and_b32_e32 v205, 0xffff0000, v88
	v_pk_fma_f32 v[136:137], v[232:233], v[204:205], v[136:137] op_sel_hi:[0,1,1]
	s_waitcnt vmcnt(26)
	v_and_b32_e32 v92, v238, v92
	v_and_b32_e32 v93, v238, v93
	v_and_b32_e32 v94, v238, v94
	v_and_b32_e32 v95, v238, v95
	v_lshlrev_b32_e32 v196, 16, v92
	v_and_b32_e32 v197, 0xffff0000, v92
	v_lshlrev_b32_e32 v84, 16, v85
	v_and_b32_e32 v85, 0xffff0000, v85
	v_pk_fma_f32 v[136:137], v[232:233], v[196:197], v[136:137] op_sel_hi:[0,1,1]
	s_waitcnt vmcnt(25)
	v_and_b32_e32 v96, v238, v96
	v_and_b32_e32 v97, v238, v97
	v_and_b32_e32 v98, v238, v98
	v_and_b32_e32 v99, v238, v99
	v_lshlrev_b32_e32 v190, 16, v96
	v_and_b32_e32 v191, 0xffff0000, v96
	v_pk_fma_f32 v[84:85], v[232:233], v[84:85], 0 op_sel_hi:[0,1,0]
	v_lshlrev_b32_e32 v206, 16, v89
	v_and_b32_e32 v207, 0xffff0000, v89
	v_pk_fma_f32 v[136:137], v[232:233], v[190:191], v[136:137] op_sel_hi:[0,1,1]
	s_waitcnt vmcnt(24)
	v_and_b32_e32 v100, v238, v100
	v_and_b32_e32 v101, v238, v101
	v_and_b32_e32 v102, v238, v102
	v_and_b32_e32 v103, v238, v103
	v_lshlrev_b32_e32 v182, 16, v100
	v_and_b32_e32 v183, 0xffff0000, v100
	v_pk_fma_f32 v[84:85], v[232:233], v[206:207], v[84:85] op_sel_hi:[0,1,1]
	v_lshlrev_b32_e32 v198, 16, v93
	v_and_b32_e32 v199, 0xffff0000, v93
	v_pk_fma_f32 v[138:139], v[230:231], v[182:183], v[136:137] op_sel_hi:[0,1,1]
	s_waitcnt vmcnt(23)
	v_and_b32_e32 v104, v238, v104
	v_and_b32_e32 v105, v238, v105
	v_and_b32_e32 v106, v238, v106
	v_and_b32_e32 v107, v238, v107
	v_lshlrev_b32_e32 v136, 16, v104
	v_and_b32_e32 v137, 0xffff0000, v104
	v_pk_fma_f32 v[84:85], v[232:233], v[198:199], v[84:85] op_sel_hi:[0,1,1]
	v_lshlrev_b32_e32 v192, 16, v97
	v_and_b32_e32 v193, 0xffff0000, v97
	v_pk_fma_f32 v[138:139], v[230:231], v[136:137], v[138:139] op_sel_hi:[0,1,1]
	s_waitcnt vmcnt(22)
	v_and_b32_e32 v108, v238, v108
	v_and_b32_e32 v109, v238, v109
	v_and_b32_e32 v110, v238, v110
	v_and_b32_e32 v111, v238, v111
	v_lshlrev_b32_e32 v148, 16, v108
	v_and_b32_e32 v149, 0xffff0000, v108
	v_pk_fma_f32 v[84:85], v[232:233], v[192:193], v[84:85] op_sel_hi:[0,1,1]
	v_lshlrev_b32_e32 v184, 16, v101
	v_and_b32_e32 v185, 0xffff0000, v101
	v_pk_fma_f32 v[152:153], v[228:229], v[148:149], v[138:139] op_sel_hi:[0,1,1]
	v_pk_fma_f32 v[84:85], v[230:231], v[184:185], v[84:85] op_sel_hi:[0,1,1]
	v_lshlrev_b32_e32 v138, 16, v105
	v_and_b32_e32 v139, 0xffff0000, v105
	v_pk_fma_f32 v[84:85], v[230:231], v[138:139], v[84:85] op_sel_hi:[0,1,1]
	v_lshlrev_b32_e32 v150, 16, v109
	v_and_b32_e32 v151, 0xffff0000, v109
	v_pk_fma_f32 v[154:155], v[228:229], v[150:151], v[84:85] op_sel_hi:[0,1,1]
	v_lshlrev_b32_e32 v84, 16, v86
	v_and_b32_e32 v85, 0xffff0000, v86
	v_pk_fma_f32 v[84:85], v[232:233], v[84:85], 0 op_sel_hi:[0,1,0]
	v_lshlrev_b32_e32 v208, 16, v90
	v_and_b32_e32 v209, 0xffff0000, v90
	v_pk_fma_f32 v[84:85], v[232:233], v[208:209], v[84:85] op_sel_hi:[0,1,1]
	v_lshlrev_b32_e32 v200, 16, v94
	v_and_b32_e32 v201, 0xffff0000, v94
	v_pk_fma_f32 v[84:85], v[232:233], v[200:201], v[84:85] op_sel_hi:[0,1,1]
	v_lshlrev_b32_e32 v108, 16, v98
	v_and_b32_e32 v109, 0xffff0000, v98
	v_pk_fma_f32 v[84:85], v[232:233], v[108:109], v[84:85] op_sel_hi:[0,1,1]
	v_lshlrev_b32_e32 v186, 16, v102
	v_and_b32_e32 v187, 0xffff0000, v102
	v_pk_fma_f32 v[84:85], v[230:231], v[186:187], v[84:85] op_sel_hi:[0,1,1]
	v_lshlrev_b32_e32 v178, 16, v106
	v_and_b32_e32 v179, 0xffff0000, v106
	v_pk_fma_f32 v[84:85], v[230:231], v[178:179], v[84:85] op_sel_hi:[0,1,1]
	v_lshlrev_b32_e32 v174, 16, v110
	v_and_b32_e32 v175, 0xffff0000, v110
	v_pk_fma_f32 v[96:97], v[228:229], v[174:175], v[84:85] op_sel_hi:[0,1,1]
	v_lshlrev_b32_e32 v84, 16, v87
	v_and_b32_e32 v85, 0xffff0000, v87
	v_pk_fma_f32 v[84:85], v[232:233], v[84:85], 0 op_sel_hi:[0,1,0]
	v_lshlrev_b32_e32 v210, 16, v91
	v_and_b32_e32 v211, 0xffff0000, v91
	v_pk_fma_f32 v[84:85], v[232:233], v[210:211], v[84:85] op_sel_hi:[0,1,1]
	v_lshlrev_b32_e32 v202, 16, v95
	v_and_b32_e32 v203, 0xffff0000, v95
	v_pk_fma_f32 v[84:85], v[232:233], v[202:203], v[84:85] op_sel_hi:[0,1,1]
	v_lshlrev_b32_e32 v194, 16, v99
	v_and_b32_e32 v195, 0xffff0000, v99
	v_pk_fma_f32 v[84:85], v[232:233], v[194:195], v[84:85] op_sel_hi:[0,1,1]
	v_lshlrev_b32_e32 v188, 16, v103
	v_and_b32_e32 v189, 0xffff0000, v103
	v_pk_fma_f32 v[84:85], v[230:231], v[188:189], v[84:85] op_sel_hi:[0,1,1]
	v_lshlrev_b32_e32 v180, 16, v107
	v_and_b32_e32 v181, 0xffff0000, v107
	v_pk_fma_f32 v[84:85], v[230:231], v[180:181], v[84:85] op_sel_hi:[0,1,1]
	v_lshlrev_b32_e32 v176, 16, v111
	v_and_b32_e32 v177, 0xffff0000, v111
	v_pk_fma_f32 v[172:173], v[228:229], v[176:177], v[84:85] op_sel_hi:[0,1,1]
	v_sub_u32_e32 v84, v156, v135
	s_waitcnt vmcnt(18)
; __device__ __forceinline__ unsigned cvt_pk_bf16(float lo, float hi) { const f32x2 v = (f32x2){lo, hi}; return __builtin_bit_cast(unsigned, __builtin_convertvector(v, bf16v2)); }
; __device__ __forceinline__ float bf_lo(unsigned w) { return __uint_as_float(w << 16); }
; __device__ __forceinline__ float bf_hi(unsigned w) { return __uint_as_float(w & 0xffff0000u); }
; __device__ __forceinline__ void phase_mixer(const Params& p, LAS unsigned char* lds, int l, bool with_ctx, int G, int tid, int wave, int lane, int rep_attn, int rep_pool) {
;     ...
;         for (int o = 0; o < 16; ++o) {
;             const int t = t0 + o, st = max(t - lo, 0), en = min(t + hi + 1, len);
;             float acc[8];
; #pragma unroll
;             for (int e = 0; e < 8; ++e) acc[e] = 0.f;
; #pragma unroll
;             for (int i = 0; i < 16; ++i) { const int tt = t + i - 8; const float wt = (tt >= st && tt < en) ? 1.f : 0.f; const u32x4 ww = w[o + i];
;                 acc[0] += wt * bf_lo(ww.x); acc[1] += wt * bf_hi(ww.x); acc[2] += wt * bf_lo(ww.y); acc[3] += wt * bf_hi(ww.y);
;                 acc[4] += wt * bf_lo(ww.z); acc[5] += wt * bf_hi(ww.z); acc[6] += wt * bf_lo(ww.w); acc[7] += wt * bf_hi(ww.w); }
;             const float ic = 1.f / (float)(en - st);
;             const u32x4 sw = w[o + 8];
;             u32x4 ov; ov.x = cvt_pk_bf16(acc[0] * ic - bf_lo(sw.x), acc[1] * ic - bf_hi(sw.x)); ov.y = cvt_pk_bf16(acc[2] * ic - bf_lo(sw.y), acc[3] * ic - bf_hi(sw.y));
;             ov.z = cvt_pk_bf16(acc[4] * ic - bf_lo(sw.z), acc[5] * ic - bf_hi(sw.z)); ov.w = cvt_pk_bf16(acc[6] * ic - bf_lo(sw.w), acc[7] * ic - bf_hi(sw.w));
;             *(u32x4*)(MIX + (size_t)(tok0 + o) * DM + 8 * lane) = ov;
	v_lshlrev_b32_e32 v100, 16, v122
	v_and_b32_e32 v101, 0xffff0000, v122
	v_cvt_f32_i32_e32 v84, v84
	v_lshlrev_b32_e32 v104, 16, v120
	v_and_b32_e32 v105, 0xffff0000, v120
	v_and_b32_e32 v112, v238, v112
	v_and_b32_e32 v113, v238, v113
	v_and_b32_e32 v114, v238, v114
	v_and_b32_e32 v115, v238, v115
	v_lshlrev_b32_e32 v146, 16, v112
	v_div_scale_f32 v85, s[0:1], v84, v84, 1.0
	v_rcp_f32_e32 v86, v85
	v_and_b32_e32 v147, 0xffff0000, v112
	v_lshlrev_b32_e32 v132, 16, v116
	v_and_b32_e32 v133, 0xffff0000, v116
	v_fma_f32 v87, -v85, v86, 1.0
	v_fmac_f32_e32 v86, v87, v86
	v_div_scale_f32 v87, vcc, 1.0, v84, 1.0
	v_mul_f32_e32 v88, v87, v86
	v_fma_f32 v89, -v85, v88, v87
	v_fmac_f32_e32 v88, v89, v86
	v_fma_f32 v85, -v85, v88, v87
	v_div_fmas_f32 v85, v85, v86, v88
	v_div_fixup_f32 v156, v85, v84, 1.0
	v_pk_fma_f32 v[84:85], v[234:235], v[146:147], v[152:153] op_sel_hi:[0,1,1]
	v_lshlrev_b32_e32 v152, 16, v80
	v_and_b32_e32 v153, 0xffff0000, v80
	v_pk_fma_f32 v[84:85], v[234:235], v[152:153], v[84:85] op_sel_hi:[0,1,1]
	v_pk_fma_f32 v[84:85], v[228:229], v[132:133], v[84:85] op_sel_hi:[0,1,1]
	v_lshlrev_b32_e32 v144, 16, v113
	v_and_b32_e32 v145, 0xffff0000, v113
	v_pk_fma_f32 v[84:85], v[230:231], v[104:105], v[84:85] op_sel_hi:[0,1,1]
	s_waitcnt vmcnt(17)
	v_lshlrev_b32_e32 v112, 16, v60
	v_and_b32_e32 v113, 0xffff0000, v60
	v_pk_fma_f32 v[84:85], v[230:231], v[112:113], v[84:85] op_sel_hi:[0,1,1]
	s_waitcnt vmcnt(16)
	v_lshlrev_b32_e32 v92, 16, v64
	v_and_b32_e32 v93, 0xffff0000, v64
	v_pk_fma_f32 v[84:85], v[232:233], v[92:93], v[84:85] op_sel_hi:[0,1,1]
	s_waitcnt vmcnt(15)
	v_lshlrev_b32_e32 v88, 16, v68
	v_and_b32_e32 v89, 0xffff0000, v68
	v_pk_fma_f32 v[84:85], v[232:233], v[88:89], v[84:85] op_sel_hi:[0,1,1]
	s_waitcnt vmcnt(14)
	v_lshlrev_b32_e32 v86, 16, v72
	v_and_b32_e32 v87, 0xffff0000, v72
	v_pk_fma_f32 v[90:91], v[232:233], v[86:87], v[84:85] op_sel_hi:[0,1,1]
	s_waitcnt vmcnt(13)
	v_lshlrev_b32_e32 v84, 16, v76
	v_and_b32_e32 v85, 0xffff0000, v76
	v_pk_fma_f32 v[90:91], v[232:233], v[84:85], v[90:91] op_sel_hi:[0,1,1]
	v_pk_fma_f32 v[90:91], v[156:157], v[90:91], v[152:153] op_sel_hi:[0,1,1] neg_lo:[0,0,1] neg_hi:[0,0,1]
	v_cvt_pk_bf16_f32 v60, v90, v91
	v_pk_fma_f32 v[90:91], v[234:235], v[144:145], v[154:155] op_sel_hi:[0,1,1]
	v_lshlrev_b32_e32 v154, 16, v81
	v_and_b32_e32 v155, 0xffff0000, v81
	v_lshlrev_b32_e32 v130, 16, v117
	v_and_b32_e32 v131, 0xffff0000, v117
	v_pk_fma_f32 v[80:81], v[234:235], v[154:155], v[90:91] op_sel_hi:[0,1,1]
	v_lshlrev_b32_e32 v102, 16, v121
	v_and_b32_e32 v103, 0xffff0000, v121
	v_pk_fma_f32 v[80:81], v[228:229], v[130:131], v[80:81] op_sel_hi:[0,1,1]
	v_lshlrev_b32_e32 v142, 16, v114
	v_and_b32_e32 v143, 0xffff0000, v114
	v_lshlrev_b32_e32 v140, 16, v115
	v_and_b32_e32 v141, 0xffff0000, v115
	v_pk_fma_f32 v[80:81], v[230:231], v[102:103], v[80:81] op_sel_hi:[0,1,1]
	v_lshlrev_b32_e32 v114, 16, v61
	v_and_b32_e32 v115, 0xffff0000, v61
	v_pk_fma_f32 v[80:81], v[230:231], v[114:115], v[80:81] op_sel_hi:[0,1,1]
	v_lshlrev_b32_e32 v94, 16, v65
	v_and_b32_e32 v95, 0xffff0000, v65
	v_pk_fma_f32 v[64:65], v[232:233], v[94:95], v[80:81] op_sel_hi:[0,1,1]
	v_lshlrev_b32_e32 v80, 16, v69
	v_and_b32_e32 v81, 0xffff0000, v69
	v_pk_fma_f32 v[64:65], v[232:233], v[80:81], v[64:65] op_sel_hi:[0,1,1]
	v_lshlrev_b32_e32 v72, 16, v73
	v_and_b32_e32 v73, 0xffff0000, v73
	v_pk_fma_f32 v[68:69], v[232:233], v[72:73], v[64:65] op_sel_hi:[0,1,1]
	v_lshlrev_b32_e32 v64, 16, v77
	v_and_b32_e32 v65, 0xffff0000, v77
	v_pk_fma_f32 v[68:69], v[232:233], v[64:65], v[68:69] op_sel_hi:[0,1,1]
	v_pk_fma_f32 v[68:69], v[156:157], v[68:69], v[154:155] op_sel_hi:[0,1,1] neg_lo:[0,0,1] neg_hi:[0,0,1]
	v_cvt_pk_bf16_f32 v61, v68, v69
	v_pk_fma_f32 v[68:69], v[234:235], v[142:143], v[96:97] op_sel_hi:[0,1,1]
	v_lshlrev_b32_e32 v170, 16, v82
	v_and_b32_e32 v171, 0xffff0000, v82
	v_lshlrev_b32_e32 v128, 16, v118
	v_and_b32_e32 v129, 0xffff0000, v118
	v_pk_fma_f32 v[68:69], v[234:235], v[170:171], v[68:69] op_sel_hi:[0,1,1]
	v_pk_fma_f32 v[68:69], v[228:229], v[128:129], v[68:69] op_sel_hi:[0,1,1]
	v_pk_fma_f32 v[68:69], v[230:231], v[100:101], v[68:69] op_sel_hi:[0,1,1]
	v_lshlrev_b32_e32 v116, 16, v62
	v_and_b32_e32 v117, 0xffff0000, v62
	v_pk_fma_f32 v[68:69], v[230:231], v[116:117], v[68:69] op_sel_hi:[0,1,1]
	v_lshlrev_b32_e32 v96, 16, v66
	v_and_b32_e32 v97, 0xffff0000, v66
	v_pk_fma_f32 v[68:69], v[232:233], v[96:97], v[68:69] op_sel_hi:[0,1,1]
	v_lshlrev_b32_e32 v90, 16, v70
	v_and_b32_e32 v91, 0xffff0000, v70
	v_pk_fma_f32 v[68:69], v[232:233], v[90:91], v[68:69] op_sel_hi:[0,1,1]
	v_lshlrev_b32_e32 v76, 16, v74
	v_and_b32_e32 v77, 0xffff0000, v74
	v_pk_fma_f32 v[224:225], v[232:233], v[76:77], v[68:69] op_sel_hi:[0,1,1]
	v_lshlrev_b32_e32 v68, 16, v78
	v_and_b32_e32 v69, 0xffff0000, v78
	v_pk_fma_f32 v[224:225], v[232:233], v[68:69], v[224:225] op_sel_hi:[0,1,1]
	v_pk_fma_f32 v[224:225], v[156:157], v[224:225], v[170:171] op_sel_hi:[0,1,1] neg_lo:[0,0,1] neg_hi:[0,0,1]
	v_cvt_pk_bf16_f32 v62, v224, v225
	v_pk_fma_f32 v[224:225], v[234:235], v[140:141], v[172:173] op_sel_hi:[0,1,1]
	v_lshlrev_b32_e32 v172, 16, v83
	v_and_b32_e32 v173, 0xffff0000, v83
	v_lshlrev_b32_e32 v118, 16, v119
	v_and_b32_e32 v119, 0xffff0000, v119
	v_pk_fma_f32 v[82:83], v[234:235], v[172:173], v[224:225] op_sel_hi:[0,1,1]
	v_lshlrev_b32_e32 v98, 16, v123
	v_and_b32_e32 v99, 0xffff0000, v123
	v_pk_fma_f32 v[82:83], v[228:229], v[118:119], v[82:83] op_sel_hi:[0,1,1]
	v_pk_fma_f32 v[82:83], v[230:231], v[98:99], v[82:83] op_sel_hi:[0,1,1]
	v_lshlrev_b32_e32 v134, 16, v63
	v_and_b32_e32 v135, 0xffff0000, v63
	v_pk_fma_f32 v[82:83], v[230:231], v[134:135], v[82:83] op_sel_hi:[0,1,1]
	v_lshlrev_b32_e32 v110, 16, v67
	v_and_b32_e32 v111, 0xffff0000, v67
	v_pk_fma_f32 v[66:67], v[232:233], v[110:111], v[82:83] op_sel_hi:[0,1,1]
	v_lshlrev_b32_e32 v82, 16, v71
	v_and_b32_e32 v83, 0xffff0000, v71
	v_pk_fma_f32 v[66:67], v[232:233], v[82:83], v[66:67] op_sel_hi:[0,1,1]
	v_lshlrev_b32_e32 v70, 16, v75
	v_and_b32_e32 v71, 0xffff0000, v75
	v_pk_fma_f32 v[74:75], v[232:233], v[70:71], v[66:67] op_sel_hi:[0,1,1]
	v_lshlrev_b32_e32 v66, 16, v79
	v_and_b32_e32 v67, 0xffff0000, v79
	global_load_dwordx4 v[4:7], v[0:1], off
	v_mad_i64_i32 v[0:1], s[62:63], s5, v223, v[124:125]
	v_pk_fma_f32 v[74:75], v[232:233], v[66:67], v[74:75] op_sel_hi:[0,1,1]
	s_ashr_i32 s5, s4, 31
	v_pk_fma_f32 v[74:75], v[156:157], v[74:75], v[172:173] op_sel_hi:[0,1,1] neg_lo:[0,0,1] neg_hi:[0,0,1]
	s_lshl_b64 s[0:1], s[4:5], 11
	v_cvt_pk_bf16_f32 v63, v74, v75
	v_lshl_add_u64 v[74:75], v[126:127], 0, s[0:1]
	global_load_dwordx4 v[0:3], v[0:1], off
	s_add_i32 s5, s8, 16
	global_store_dwordx4 v[74:75], v[60:63], off
	s_cmpk_lg_u32 s52, 0x800
	s_cbranch_scc1 .Lpool_std
	s_cmpk_ge_i32 s6, 0x800
	s_cbranch_scc1 .Lpool_last
	s_and_b32 s32, s6, 0x407
	s_cmpk_eq_i32 s32, 0x400
	s_cbranch_scc0 .Lpool_last
	s_sub_i32 s6, s6, 0x400
	s_lshr_b32 s6, s6, 3
	s_add_i32 s6, s6, 0x800
	s_branch .Lpool_next_done

; __device__ __forceinline__ unsigned cvt_pk_bf16(float lo, float hi) { const f32x2 v = (f32x2){lo, hi}; return __builtin_bit_cast(unsigned, __builtin_convertvector(v, bf16v2)); }
; __device__ __forceinline__ float bf_lo(unsigned w) { return __uint_as_float(w << 16); }
; __device__ __forceinline__ float bf_hi(unsigned w) { return __uint_as_float(w & 0xffff0000u); }
; __device__ __forceinline__ void phase_mixer(const Params& p, LAS unsigned char* lds, int l, bool with_ctx, int G, int tid, int wave, int lane, int rep_attn, int rep_pool) {
;     ...
;         for (int o = 0; o < 16; ++o) {
;             const int t = t0 + o, st = max(t - lo, 0), en = min(t + hi + 1, len);
;             float acc[8];
; #pragma unroll
;             for (int e = 0; e < 8; ++e) acc[e] = 0.f;
; #pragma unroll
;             for (int i = 0; i < 16; ++i) { const int tt = t + i - 8; const float wt = (tt >= st && tt < en) ? 1.f : 0.f; const u32x4 ww = w[o + i];
;                 acc[0] += wt * bf_lo(ww.x); acc[1] += wt * bf_hi(ww.x); acc[2] += wt * bf_lo(ww.y); acc[3] += wt * bf_hi(ww.y);
;                 acc[4] += wt * bf_lo(ww.z); acc[5] += wt * bf_hi(ww.z); acc[6] += wt * bf_lo(ww.w); acc[7] += wt * bf_hi(ww.w); }
;             const float ic = 1.f / (float)(en - st);
;             const u32x4 sw = w[o + 8];
;             u32x4 ov; ov.x = cvt_pk_bf16(acc[0] * ic - bf_lo(sw.x), acc[1] * ic - bf_hi(sw.x)); ov.y = cvt_pk_bf16(acc[2] * ic - bf_lo(sw.y), acc[3] * ic - bf_hi(sw.y));
;             ov.z = cvt_pk_bf16(acc[4] * ic - bf_lo(sw.z), acc[5] * ic - bf_hi(sw.z)); ov.w = cvt_pk_bf16(acc[6] * ic - bf_lo(sw.w), acc[7] * ic - bf_hi(sw.w));
;             *(u32x4*)(MIX + (size_t)(tok0 + o) * DM + 8 * lane) = ov;
.Lpool_next_done:
	s_nop 0
	v_sub_u32_e32 v60, s26, v167
	v_add_u32_e32 v61, s26, v167
	v_max_i32_e32 v75, 0, v60
	v_min_i32_e32 v79, s9, v61
	v_pk_fma_f32 v[62:63], v[232:233], v[204:205], 0 op_sel_hi:[0,1,0]
	v_pk_fma_f32 v[62:63], v[232:233], v[196:197], v[62:63] op_sel_hi:[0,1,1]
	v_pk_fma_f32 v[62:63], v[232:233], v[190:191], v[62:63] op_sel_hi:[0,1,1]
	v_pk_fma_f32 v[62:63], v[232:233], v[182:183], v[62:63] op_sel_hi:[0,1,1]
	v_pk_fma_f32 v[62:63], v[230:231], v[136:137], v[62:63] op_sel_hi:[0,1,1]
	v_pk_fma_f32 v[62:63], v[230:231], v[148:149], v[62:63] op_sel_hi:[0,1,1]
	v_pk_fma_f32 v[216:217], v[228:229], v[146:147], v[62:63] op_sel_hi:[0,1,1]
	v_pk_fma_f32 v[62:63], v[232:233], v[206:207], 0 op_sel_hi:[0,1,0]
	v_pk_fma_f32 v[62:63], v[232:233], v[198:199], v[62:63] op_sel_hi:[0,1,1]
	v_pk_fma_f32 v[62:63], v[232:233], v[192:193], v[62:63] op_sel_hi:[0,1,1]
	v_pk_fma_f32 v[62:63], v[232:233], v[184:185], v[62:63] op_sel_hi:[0,1,1]
	v_pk_fma_f32 v[62:63], v[230:231], v[138:139], v[62:63] op_sel_hi:[0,1,1]
	v_pk_fma_f32 v[62:63], v[230:231], v[150:151], v[62:63] op_sel_hi:[0,1,1]
	v_pk_fma_f32 v[214:215], v[228:229], v[144:145], v[62:63] op_sel_hi:[0,1,1]
	v_pk_fma_f32 v[62:63], v[232:233], v[208:209], 0 op_sel_hi:[0,1,0]
	v_pk_fma_f32 v[60:61], v[232:233], v[210:211], 0 op_sel_hi:[0,1,0]
	v_pk_fma_f32 v[62:63], v[232:233], v[200:201], v[62:63] op_sel_hi:[0,1,1]
	v_pk_fma_f32 v[60:61], v[232:233], v[202:203], v[60:61] op_sel_hi:[0,1,1]
	v_pk_fma_f32 v[62:63], v[232:233], v[108:109], v[62:63] op_sel_hi:[0,1,1]
	v_pk_fma_f32 v[60:61], v[232:233], v[194:195], v[60:61] op_sel_hi:[0,1,1]
	v_pk_fma_f32 v[62:63], v[232:233], v[186:187], v[62:63] op_sel_hi:[0,1,1]
	v_pk_fma_f32 v[60:61], v[232:233], v[188:189], v[60:61] op_sel_hi:[0,1,1]
	v_pk_fma_f32 v[62:63], v[230:231], v[178:179], v[62:63] op_sel_hi:[0,1,1]
	v_pk_fma_f32 v[60:61], v[230:231], v[180:181], v[60:61] op_sel_hi:[0,1,1]
	v_pk_fma_f32 v[62:63], v[230:231], v[174:175], v[62:63] op_sel_hi:[0,1,1]
	v_pk_fma_f32 v[60:61], v[230:231], v[176:177], v[60:61] op_sel_hi:[0,1,1]
	v_pk_fma_f32 v[62:63], v[228:229], v[142:143], v[62:63] op_sel_hi:[0,1,1]
	v_pk_fma_f32 v[106:107], v[228:229], v[140:141], v[60:61] op_sel_hi:[0,1,1]
	v_sub_u32_e32 v60, v79, v75
	v_cvt_f32_i32_e32 v60, v60
	s_nop 0
	v_div_scale_f32 v61, s[0:1], v60, v60, 1.0
	v_rcp_f32_e32 v75, v61
	s_or_b32 s0, s4, 1
	s_ashr_i32 s1, s0, 31
	s_lshl_b64 s[0:1], s[0:1], 11
	v_fma_f32 v78, -v61, v75, 1.0
	v_fmac_f32_e32 v75, v78, v75
	v_div_scale_f32 v78, vcc, 1.0, v60, 1.0
	v_mul_f32_e32 v79, v78, v75
	v_fma_f32 v121, -v61, v79, v78
	v_fmac_f32_e32 v79, v121, v75
	v_fma_f32 v61, -v61, v79, v78
	v_div_fmas_f32 v61, v61, v75, v79
	v_div_fixup_f32 v78, v61, v60, 1.0
	v_pk_fma_f32 v[60:61], v[234:235], v[152:153], v[216:217] op_sel_hi:[0,1,1]
	v_pk_fma_f32 v[214:215], v[234:235], v[154:155], v[214:215] op_sel_hi:[0,1,1]
	v_pk_fma_f32 v[60:61], v[234:235], v[132:133], v[60:61] op_sel_hi:[0,1,1]
	v_pk_fma_f32 v[214:215], v[234:235], v[130:131], v[214:215] op_sel_hi:[0,1,1]
	v_pk_fma_f32 v[60:61], v[228:229], v[104:105], v[60:61] op_sel_hi:[0,1,1]
	v_pk_fma_f32 v[214:215], v[228:229], v[102:103], v[214:215] op_sel_hi:[0,1,1]
	v_pk_fma_f32 v[60:61], v[230:231], v[112:113], v[60:61] op_sel_hi:[0,1,1]
	v_pk_fma_f32 v[214:215], v[230:231], v[114:115], v[214:215] op_sel_hi:[0,1,1]
	v_pk_fma_f32 v[62:63], v[234:235], v[170:171], v[62:63] op_sel_hi:[0,1,1]
	v_pk_fma_f32 v[106:107], v[234:235], v[172:173], v[106:107] op_sel_hi:[0,1,1]
	v_pk_fma_f32 v[60:61], v[230:231], v[92:93], v[60:61] op_sel_hi:[0,1,1]
	v_pk_fma_f32 v[214:215], v[230:231], v[94:95], v[214:215] op_sel_hi:[0,1,1]
	v_pk_fma_f32 v[62:63], v[234:235], v[128:129], v[62:63] op_sel_hi:[0,1,1]
	v_pk_fma_f32 v[106:107], v[234:235], v[118:119], v[106:107] op_sel_hi:[0,1,1]
	v_pk_fma_f32 v[60:61], v[232:233], v[88:89], v[60:61] op_sel_hi:[0,1,1]
	v_pk_fma_f32 v[214:215], v[232:233], v[80:81], v[214:215] op_sel_hi:[0,1,1]
	v_pk_fma_f32 v[62:63], v[228:229], v[100:101], v[62:63] op_sel_hi:[0,1,1]
	v_pk_fma_f32 v[106:107], v[228:229], v[98:99], v[106:107] op_sel_hi:[0,1,1]
	v_pk_fma_f32 v[60:61], v[232:233], v[86:87], v[60:61] op_sel_hi:[0,1,1]
	v_pk_fma_f32 v[214:215], v[232:233], v[72:73], v[214:215] op_sel_hi:[0,1,1]
	v_pk_fma_f32 v[62:63], v[230:231], v[116:117], v[62:63] op_sel_hi:[0,1,1]
	v_pk_fma_f32 v[106:107], v[230:231], v[134:135], v[106:107] op_sel_hi:[0,1,1]
	v_pk_fma_f32 v[216:217], v[232:233], v[84:85], v[60:61] op_sel_hi:[0,1,1]
	s_waitcnt vmcnt(15)
; __device__ __forceinline__ unsigned cvt_pk_bf16(float lo, float hi) { const f32x2 v = (f32x2){lo, hi}; return __builtin_bit_cast(unsigned, __builtin_convertvector(v, bf16v2)); }
; __device__ __forceinline__ float bf_lo(unsigned w) { return __uint_as_float(w << 16); }
; __device__ __forceinline__ float bf_hi(unsigned w) { return __uint_as_float(w & 0xffff0000u); }
; __device__ __forceinline__ void phase_mixer(const Params& p, LAS unsigned char* lds, int l, bool with_ctx, int G, int tid, int wave, int lane, int rep_attn, int rep_pool) {
;     ...
;         for (int o = 0; o < 16; ++o) {
;             const int t = t0 + o, st = max(t - lo, 0), en = min(t + hi + 1, len);
;             float acc[8];
; #pragma unroll
;             for (int e = 0; e < 8; ++e) acc[e] = 0.f;
; #pragma unroll
;             for (int i = 0; i < 16; ++i) { const int tt = t + i - 8; const float wt = (tt >= st && tt < en) ? 1.f : 0.f; const u32x4 ww = w[o + i];
;                 acc[0] += wt * bf_lo(ww.x); acc[1] += wt * bf_hi(ww.x); acc[2] += wt * bf_lo(ww.y); acc[3] += wt * bf_hi(ww.y);
;                 acc[4] += wt * bf_lo(ww.z); acc[5] += wt * bf_hi(ww.z); acc[6] += wt * bf_lo(ww.w); acc[7] += wt * bf_hi(ww.w); }
;             const float ic = 1.f / (float)(en - st);
;             const u32x4 sw = w[o + 8];
;             u32x4 ov; ov.x = cvt_pk_bf16(acc[0] * ic - bf_lo(sw.x), acc[1] * ic - bf_hi(sw.x)); ov.y = cvt_pk_bf16(acc[2] * ic - bf_lo(sw.y), acc[3] * ic - bf_hi(sw.y));
;             ov.z = cvt_pk_bf16(acc[4] * ic - bf_lo(sw.z), acc[5] * ic - bf_hi(sw.z)); ov.w = cvt_pk_bf16(acc[6] * ic - bf_lo(sw.w), acc[7] * ic - bf_hi(sw.w));
;             *(u32x4*)(MIX + (size_t)(tok0 + o) * DM + 8 * lane) = ov;
	v_lshlrev_b32_e32 v60, 16, v56
	v_and_b32_e32 v61, 0xffff0000, v56
	v_pk_fma_f32 v[214:215], v[232:233], v[64:65], v[214:215] op_sel_hi:[0,1,1]
	v_lshlrev_b32_e32 v56, 16, v57
	v_and_b32_e32 v57, 0xffff0000, v57
	v_pk_fma_f32 v[62:63], v[230:231], v[96:97], v[62:63] op_sel_hi:[0,1,1]
	v_pk_fma_f32 v[106:107], v[230:231], v[110:111], v[106:107] op_sel_hi:[0,1,1]
	v_pk_fma_f32 v[214:215], v[232:233], v[56:57], v[214:215] op_sel_hi:[0,1,1]
	v_pk_fma_f32 v[62:63], v[232:233], v[90:91], v[62:63] op_sel_hi:[0,1,1]
	v_pk_fma_f32 v[106:107], v[232:233], v[82:83], v[106:107] op_sel_hi:[0,1,1]
	v_pk_fma_f32 v[214:215], v[78:79], v[214:215], v[130:131] op_sel_hi:[0,1,1] neg_lo:[0,0,1] neg_hi:[0,0,1]
	v_pk_fma_f32 v[62:63], v[232:233], v[76:77], v[62:63] op_sel_hi:[0,1,1]
	v_pk_fma_f32 v[106:107], v[232:233], v[70:71], v[106:107] op_sel_hi:[0,1,1]
	v_cvt_pk_bf16_f32 v225, v214, v215
	v_pk_fma_f32 v[214:215], v[232:233], v[68:69], v[62:63] op_sel_hi:[0,1,1]
	v_lshlrev_b32_e32 v62, 16, v58
	v_and_b32_e32 v63, 0xffff0000, v58
	v_pk_fma_f32 v[106:107], v[232:233], v[66:67], v[106:107] op_sel_hi:[0,1,1]
	v_lshlrev_b32_e32 v58, 16, v59
	v_and_b32_e32 v59, 0xffff0000, v59
	v_pk_fma_f32 v[216:217], v[232:233], v[60:61], v[216:217] op_sel_hi:[0,1,1]
	v_pk_fma_f32 v[214:215], v[232:233], v[62:63], v[214:215] op_sel_hi:[0,1,1]
	v_pk_fma_f32 v[74:75], v[232:233], v[58:59], v[106:107] op_sel_hi:[0,1,1]
	v_pk_fma_f32 v[216:217], v[78:79], v[216:217], v[132:133] op_sel_hi:[0,1,1] neg_lo:[0,0,1] neg_hi:[0,0,1]
	v_pk_fma_f32 v[214:215], v[78:79], v[214:215], v[128:129] op_sel_hi:[0,1,1] neg_lo:[0,0,1] neg_hi:[0,0,1]
	v_pk_fma_f32 v[74:75], v[78:79], v[74:75], v[118:119] op_sel_hi:[0,1,1] neg_lo:[0,0,1] neg_hi:[0,0,1]
	v_cvt_pk_bf16_f32 v224, v216, v217
	v_cvt_pk_bf16_f32 v226, v214, v215
	v_cvt_pk_bf16_f32 v227, v74, v75
	v_lshl_add_u64 v[74:75], v[126:127], 0, s[0:1]
	global_store_dwordx4 v[74:75], v[224:227], off
	v_sub_u32_e32 v74, s23, v167
	v_add_u32_e32 v75, s23, v167
	v_max_i32_e32 v107, 0, v74
	v_min_i32_e32 v121, s9, v75
	v_pk_fma_f32 v[78:79], v[232:233], v[196:197], 0 op_sel_hi:[0,1,0]
	v_pk_fma_f32 v[78:79], v[232:233], v[190:191], v[78:79] op_sel_hi:[0,1,1]
	v_pk_fma_f32 v[78:79], v[232:233], v[182:183], v[78:79] op_sel_hi:[0,1,1]
	v_pk_fma_f32 v[78:79], v[232:233], v[136:137], v[78:79] op_sel_hi:[0,1,1]
	v_pk_fma_f32 v[78:79], v[230:231], v[148:149], v[78:79] op_sel_hi:[0,1,1]
	v_pk_fma_f32 v[78:79], v[230:231], v[146:147], v[78:79] op_sel_hi:[0,1,1]
	v_pk_fma_f32 v[212:213], v[228:229], v[152:153], v[78:79] op_sel_hi:[0,1,1]
	v_pk_fma_f32 v[78:79], v[232:233], v[198:199], 0 op_sel_hi:[0,1,0]
	v_pk_fma_f32 v[78:79], v[232:233], v[192:193], v[78:79] op_sel_hi:[0,1,1]
	v_pk_fma_f32 v[78:79], v[232:233], v[184:185], v[78:79] op_sel_hi:[0,1,1]
	v_pk_fma_f32 v[78:79], v[232:233], v[138:139], v[78:79] op_sel_hi:[0,1,1]
	v_pk_fma_f32 v[78:79], v[230:231], v[150:151], v[78:79] op_sel_hi:[0,1,1]
	v_pk_fma_f32 v[78:79], v[230:231], v[144:145], v[78:79] op_sel_hi:[0,1,1]
	v_pk_fma_f32 v[210:211], v[228:229], v[154:155], v[78:79] op_sel_hi:[0,1,1]
	v_pk_fma_f32 v[78:79], v[232:233], v[200:201], 0 op_sel_hi:[0,1,0]
	v_pk_fma_f32 v[74:75], v[232:233], v[202:203], 0 op_sel_hi:[0,1,0]
	v_pk_fma_f32 v[78:79], v[232:233], v[108:109], v[78:79] op_sel_hi:[0,1,1]
	v_pk_fma_f32 v[74:75], v[232:233], v[194:195], v[74:75] op_sel_hi:[0,1,1]
	v_pk_fma_f32 v[78:79], v[232:233], v[186:187], v[78:79] op_sel_hi:[0,1,1]
	v_pk_fma_f32 v[74:75], v[232:233], v[188:189], v[74:75] op_sel_hi:[0,1,1]
	v_pk_fma_f32 v[78:79], v[232:233], v[178:179], v[78:79] op_sel_hi:[0,1,1]
	v_pk_fma_f32 v[74:75], v[232:233], v[180:181], v[74:75] op_sel_hi:[0,1,1]
	v_pk_fma_f32 v[78:79], v[230:231], v[174:175], v[78:79] op_sel_hi:[0,1,1]
	v_pk_fma_f32 v[74:75], v[230:231], v[176:177], v[74:75] op_sel_hi:[0,1,1]
	v_pk_fma_f32 v[78:79], v[230:231], v[142:143], v[78:79] op_sel_hi:[0,1,1]
	v_pk_fma_f32 v[74:75], v[230:231], v[140:141], v[74:75] op_sel_hi:[0,1,1]
	v_pk_fma_f32 v[122:123], v[228:229], v[172:173], v[74:75] op_sel_hi:[0,1,1]
	v_sub_u32_e32 v74, v121, v107
	v_pk_fma_f32 v[78:79], v[228:229], v[170:171], v[78:79] op_sel_hi:[0,1,1]
	v_cvt_f32_i32_e32 v74, v74
	v_pk_fma_f32 v[210:211], v[234:235], v[130:131], v[210:211] op_sel_hi:[0,1,1]
	v_div_scale_f32 v75, s[0:1], v74, v74, 1.0
	v_rcp_f32_e32 v107, v75
	v_pk_fma_f32 v[210:211], v[234:235], v[102:103], v[210:211] op_sel_hi:[0,1,1]
	v_pk_fma_f32 v[210:211], v[228:229], v[114:115], v[210:211] op_sel_hi:[0,1,1]
	v_pk_fma_f32 v[210:211], v[230:231], v[94:95], v[210:211] op_sel_hi:[0,1,1]
	v_fma_f32 v120, -v75, v107, 1.0
	v_fmac_f32_e32 v107, v120, v107
	v_div_scale_f32 v120, vcc, 1.0, v74, 1.0
	v_mul_f32_e32 v121, v120, v107
	v_fma_f32 v160, -v75, v121, v120
	v_fmac_f32_e32 v121, v160, v107
	v_fma_f32 v75, -v75, v121, v120
	v_div_fmas_f32 v75, v75, v107, v121
	v_div_fixup_f32 v120, v75, v74, 1.0
	v_pk_fma_f32 v[74:75], v[234:235], v[132:133], v[212:213] op_sel_hi:[0,1,1]
	v_pk_fma_f32 v[74:75], v[234:235], v[104:105], v[74:75] op_sel_hi:[0,1,1]
	v_pk_fma_f32 v[74:75], v[228:229], v[112:113], v[74:75] op_sel_hi:[0,1,1]
	v_pk_fma_f32 v[74:75], v[230:231], v[92:93], v[74:75] op_sel_hi:[0,1,1]
	v_pk_fma_f32 v[78:79], v[234:235], v[128:129], v[78:79] op_sel_hi:[0,1,1]
	v_pk_fma_f32 v[122:123], v[234:235], v[118:119], v[122:123] op_sel_hi:[0,1,1]
	v_pk_fma_f32 v[74:75], v[230:231], v[88:89], v[74:75] op_sel_hi:[0,1,1]
	v_pk_fma_f32 v[210:211], v[230:231], v[80:81], v[210:211] op_sel_hi:[0,1,1]
	v_pk_fma_f32 v[78:79], v[234:235], v[100:101], v[78:79] op_sel_hi:[0,1,1]
	v_pk_fma_f32 v[122:123], v[234:235], v[98:99], v[122:123] op_sel_hi:[0,1,1]
	v_pk_fma_f32 v[74:75], v[232:233], v[86:87], v[74:75] op_sel_hi:[0,1,1]
	v_pk_fma_f32 v[210:211], v[232:233], v[72:73], v[210:211] op_sel_hi:[0,1,1]
	v_pk_fma_f32 v[78:79], v[228:229], v[116:117], v[78:79] op_sel_hi:[0,1,1]
	v_pk_fma_f32 v[122:123], v[228:229], v[134:135], v[122:123] op_sel_hi:[0,1,1]
	v_pk_fma_f32 v[74:75], v[232:233], v[84:85], v[74:75] op_sel_hi:[0,1,1]
	v_pk_fma_f32 v[210:211], v[232:233], v[64:65], v[210:211] op_sel_hi:[0,1,1]
	v_pk_fma_f32 v[78:79], v[230:231], v[96:97], v[78:79] op_sel_hi:[0,1,1]
	v_pk_fma_f32 v[122:123], v[230:231], v[110:111], v[122:123] op_sel_hi:[0,1,1]
	v_pk_fma_f32 v[212:213], v[232:233], v[60:61], v[74:75] op_sel_hi:[0,1,1]
	s_waitcnt vmcnt(15)
; __device__ __forceinline__ unsigned cvt_pk_bf16(float lo, float hi) { const f32x2 v = (f32x2){lo, hi}; return __builtin_bit_cast(unsigned, __builtin_convertvector(v, bf16v2)); }
; __device__ __forceinline__ float bf_lo(unsigned w) { return __uint_as_float(w << 16); }
; __device__ __forceinline__ float bf_hi(unsigned w) { return __uint_as_float(w & 0xffff0000u); }
; __device__ __forceinline__ void phase_mixer(const Params& p, LAS unsigned char* lds, int l, bool with_ctx, int G, int tid, int wave, int lane, int rep_attn, int rep_pool) {
;     ...
;         for (int o = 0; o < 16; ++o) {
;             const int t = t0 + o, st = max(t - lo, 0), en = min(t + hi + 1, len);
;             float acc[8];
; #pragma unroll
;             for (int e = 0; e < 8; ++e) acc[e] = 0.f;
; #pragma unroll
;             for (int i = 0; i < 16; ++i) { const int tt = t + i - 8; const float wt = (tt >= st && tt < en) ? 1.f : 0.f; const u32x4 ww = w[o + i];
;                 acc[0] += wt * bf_lo(ww.x); acc[1] += wt * bf_hi(ww.x); acc[2] += wt * bf_lo(ww.y); acc[3] += wt * bf_hi(ww.y);
;                 acc[4] += wt * bf_lo(ww.z); acc[5] += wt * bf_hi(ww.z); acc[6] += wt * bf_lo(ww.w); acc[7] += wt * bf_hi(ww.w); }
;             const float ic = 1.f / (float)(en - st);
;             const u32x4 sw = w[o + 8];
;             u32x4 ov; ov.x = cvt_pk_bf16(acc[0] * ic - bf_lo(sw.x), acc[1] * ic - bf_hi(sw.x)); ov.y = cvt_pk_bf16(acc[2] * ic - bf_lo(sw.y), acc[3] * ic - bf_hi(sw.y));
;             ov.z = cvt_pk_bf16(acc[4] * ic - bf_lo(sw.z), acc[5] * ic - bf_hi(sw.z)); ov.w = cvt_pk_bf16(acc[6] * ic - bf_lo(sw.w), acc[7] * ic - bf_hi(sw.w));
;             *(u32x4*)(MIX + (size_t)(tok0 + o) * DM + 8 * lane) = ov;
	v_lshlrev_b32_e32 v74, 16, v52
	v_and_b32_e32 v75, 0xffff0000, v52
	v_pk_fma_f32 v[210:211], v[232:233], v[56:57], v[210:211] op_sel_hi:[0,1,1]
	v_lshlrev_b32_e32 v52, 16, v53
	v_and_b32_e32 v53, 0xffff0000, v53
	v_pk_fma_f32 v[78:79], v[230:231], v[90:91], v[78:79] op_sel_hi:[0,1,1]
	v_pk_fma_f32 v[122:123], v[230:231], v[82:83], v[122:123] op_sel_hi:[0,1,1]
	v_pk_fma_f32 v[212:213], v[232:233], v[74:75], v[212:213] op_sel_hi:[0,1,1]
	v_pk_fma_f32 v[210:211], v[232:233], v[52:53], v[210:211] op_sel_hi:[0,1,1]
	v_pk_fma_f32 v[78:79], v[232:233], v[76:77], v[78:79] op_sel_hi:[0,1,1]
	v_pk_fma_f32 v[122:123], v[232:233], v[70:71], v[122:123] op_sel_hi:[0,1,1]
	v_pk_fma_f32 v[212:213], v[120:121], v[212:213], v[104:105] op_sel_hi:[0,1,1] neg_lo:[0,0,1] neg_hi:[0,0,1]
	v_pk_fma_f32 v[210:211], v[120:121], v[210:211], v[102:103] op_sel_hi:[0,1,1] neg_lo:[0,0,1] neg_hi:[0,0,1]
	v_pk_fma_f32 v[78:79], v[232:233], v[68:69], v[78:79] op_sel_hi:[0,1,1]
	v_pk_fma_f32 v[122:123], v[232:233], v[66:67], v[122:123] op_sel_hi:[0,1,1]
	v_cvt_pk_bf16_f32 v212, v212, v213
	v_cvt_pk_bf16_f32 v213, v210, v211
	v_pk_fma_f32 v[210:211], v[232:233], v[62:63], v[78:79] op_sel_hi:[0,1,1]
	v_lshlrev_b32_e32 v78, 16, v54
	v_and_b32_e32 v79, 0xffff0000, v54
	v_pk_fma_f32 v[122:123], v[232:233], v[58:59], v[122:123] op_sel_hi:[0,1,1]
	v_lshlrev_b32_e32 v54, 16, v55
	v_and_b32_e32 v55, 0xffff0000, v55
	s_or_b32 s0, s4, 2
	v_pk_fma_f32 v[210:211], v[232:233], v[78:79], v[210:211] op_sel_hi:[0,1,1]
	v_pk_fma_f32 v[106:107], v[232:233], v[54:55], v[122:123] op_sel_hi:[0,1,1]
	s_ashr_i32 s1, s0, 31
	v_pk_fma_f32 v[210:211], v[120:121], v[210:211], v[100:101] op_sel_hi:[0,1,1] neg_lo:[0,0,1] neg_hi:[0,0,1]
	v_pk_fma_f32 v[106:107], v[120:121], v[106:107], v[98:99] op_sel_hi:[0,1,1] neg_lo:[0,0,1] neg_hi:[0,0,1]
	s_lshl_b64 s[0:1], s[0:1], 11
	v_cvt_pk_bf16_f32 v214, v210, v211
	v_cvt_pk_bf16_f32 v215, v106, v107
	v_lshl_add_u64 v[106:107], v[126:127], 0, s[0:1]
	global_store_dwordx4 v[106:107], v[212:215], off
	v_sub_u32_e32 v106, s22, v167
	v_add_u32_e32 v107, s22, v167
	v_max_i32_e32 v121, 0, v106
	v_min_i32_e32 v123, s9, v107
	v_pk_fma_f32 v[190:191], v[232:233], v[190:191], 0 op_sel_hi:[0,1,0]
	v_pk_fma_f32 v[190:191], v[232:233], v[182:183], v[190:191] op_sel_hi:[0,1,1]
	v_pk_fma_f32 v[190:191], v[232:233], v[136:137], v[190:191] op_sel_hi:[0,1,1]
	v_pk_fma_f32 v[190:191], v[232:233], v[148:149], v[190:191] op_sel_hi:[0,1,1]
	v_pk_fma_f32 v[190:191], v[230:231], v[146:147], v[190:191] op_sel_hi:[0,1,1]
	v_pk_fma_f32 v[190:191], v[230:231], v[152:153], v[190:191] op_sel_hi:[0,1,1]
	v_pk_fma_f32 v[208:209], v[228:229], v[132:133], v[190:191] op_sel_hi:[0,1,1]
	v_pk_fma_f32 v[190:191], v[232:233], v[192:193], 0 op_sel_hi:[0,1,0]
	v_pk_fma_f32 v[108:109], v[232:233], v[108:109], 0 op_sel_hi:[0,1,0]
	v_pk_fma_f32 v[106:107], v[232:233], v[194:195], 0 op_sel_hi:[0,1,0]
	v_pk_fma_f32 v[190:191], v[232:233], v[184:185], v[190:191] op_sel_hi:[0,1,1]
	v_pk_fma_f32 v[108:109], v[232:233], v[186:187], v[108:109] op_sel_hi:[0,1,1]
	v_pk_fma_f32 v[106:107], v[232:233], v[188:189], v[106:107] op_sel_hi:[0,1,1]
	v_pk_fma_f32 v[190:191], v[232:233], v[138:139], v[190:191] op_sel_hi:[0,1,1]
	v_pk_fma_f32 v[108:109], v[232:233], v[178:179], v[108:109] op_sel_hi:[0,1,1]
	v_pk_fma_f32 v[106:107], v[232:233], v[180:181], v[106:107] op_sel_hi:[0,1,1]
	v_pk_fma_f32 v[190:191], v[232:233], v[150:151], v[190:191] op_sel_hi:[0,1,1]
	v_pk_fma_f32 v[108:109], v[232:233], v[174:175], v[108:109] op_sel_hi:[0,1,1]
	v_pk_fma_f32 v[106:107], v[232:233], v[176:177], v[106:107] op_sel_hi:[0,1,1]
	v_pk_fma_f32 v[190:191], v[230:231], v[144:145], v[190:191] op_sel_hi:[0,1,1]
	v_pk_fma_f32 v[108:109], v[230:231], v[142:143], v[108:109] op_sel_hi:[0,1,1]
	v_pk_fma_f32 v[106:107], v[230:231], v[140:141], v[106:107] op_sel_hi:[0,1,1]
	v_pk_fma_f32 v[190:191], v[230:231], v[154:155], v[190:191] op_sel_hi:[0,1,1]
	v_pk_fma_f32 v[108:109], v[230:231], v[170:171], v[108:109] op_sel_hi:[0,1,1]
	v_pk_fma_f32 v[106:107], v[230:231], v[172:173], v[106:107] op_sel_hi:[0,1,1]
	v_pk_fma_f32 v[206:207], v[228:229], v[130:131], v[190:191] op_sel_hi:[0,1,1]
	v_pk_fma_f32 v[108:109], v[228:229], v[128:129], v[108:109] op_sel_hi:[0,1,1]
	v_pk_fma_f32 v[190:191], v[228:229], v[118:119], v[106:107] op_sel_hi:[0,1,1]
	v_sub_u32_e32 v106, v123, v121
	v_cvt_f32_i32_e32 v106, v106
	v_pk_fma_f32 v[206:207], v[234:235], v[102:103], v[206:207] op_sel_hi:[0,1,1]
	v_div_scale_f32 v107, s[0:1], v106, v106, 1.0
	v_rcp_f32_e32 v121, v107
	v_pk_fma_f32 v[206:207], v[234:235], v[114:115], v[206:207] op_sel_hi:[0,1,1]
	v_pk_fma_f32 v[206:207], v[228:229], v[94:95], v[206:207] op_sel_hi:[0,1,1]
	v_pk_fma_f32 v[206:207], v[230:231], v[80:81], v[206:207] op_sel_hi:[0,1,1]
	v_fma_f32 v122, -v107, v121, 1.0
	v_fmac_f32_e32 v121, v122, v121
	v_div_scale_f32 v122, vcc, 1.0, v106, 1.0
	v_mul_f32_e32 v123, v122, v121
	v_fma_f32 v160, -v107, v123, v122
	v_fmac_f32_e32 v123, v160, v121
	v_fma_f32 v107, -v107, v123, v122
	v_div_fmas_f32 v107, v107, v121, v123
	v_div_fixup_f32 v122, v107, v106, 1.0
	v_pk_fma_f32 v[106:107], v[234:235], v[104:105], v[208:209] op_sel_hi:[0,1,1]
	v_pk_fma_f32 v[106:107], v[234:235], v[112:113], v[106:107] op_sel_hi:[0,1,1]
	v_pk_fma_f32 v[106:107], v[228:229], v[92:93], v[106:107] op_sel_hi:[0,1,1]
	v_pk_fma_f32 v[106:107], v[230:231], v[88:89], v[106:107] op_sel_hi:[0,1,1]
	v_pk_fma_f32 v[108:109], v[234:235], v[100:101], v[108:109] op_sel_hi:[0,1,1]
	v_pk_fma_f32 v[190:191], v[234:235], v[98:99], v[190:191] op_sel_hi:[0,1,1]
	v_pk_fma_f32 v[106:107], v[230:231], v[86:87], v[106:107] op_sel_hi:[0,1,1]
	v_pk_fma_f32 v[206:207], v[230:231], v[72:73], v[206:207] op_sel_hi:[0,1,1]
	v_pk_fma_f32 v[108:109], v[234:235], v[116:117], v[108:109] op_sel_hi:[0,1,1]
	v_pk_fma_f32 v[190:191], v[234:235], v[134:135], v[190:191] op_sel_hi:[0,1,1]
	v_pk_fma_f32 v[106:107], v[232:233], v[84:85], v[106:107] op_sel_hi:[0,1,1]
	v_pk_fma_f32 v[206:207], v[232:233], v[64:65], v[206:207] op_sel_hi:[0,1,1]
	v_pk_fma_f32 v[108:109], v[228:229], v[96:97], v[108:109] op_sel_hi:[0,1,1]
	v_pk_fma_f32 v[190:191], v[228:229], v[110:111], v[190:191] op_sel_hi:[0,1,1]
	v_pk_fma_f32 v[106:107], v[232:233], v[60:61], v[106:107] op_sel_hi:[0,1,1]
	v_pk_fma_f32 v[206:207], v[232:233], v[56:57], v[206:207] op_sel_hi:[0,1,1]
	v_pk_fma_f32 v[108:109], v[230:231], v[90:91], v[108:109] op_sel_hi:[0,1,1]
	v_pk_fma_f32 v[190:191], v[230:231], v[82:83], v[190:191] op_sel_hi:[0,1,1]
	v_pk_fma_f32 v[208:209], v[232:233], v[74:75], v[106:107] op_sel_hi:[0,1,1]
	s_waitcnt vmcnt(15)
; __device__ __forceinline__ unsigned cvt_pk_bf16(float lo, float hi) { const f32x2 v = (f32x2){lo, hi}; return __builtin_bit_cast(unsigned, __builtin_convertvector(v, bf16v2)); }
; __device__ __forceinline__ float bf_lo(unsigned w) { return __uint_as_float(w << 16); }
; __device__ __forceinline__ float bf_hi(unsigned w) { return __uint_as_float(w & 0xffff0000u); }
; __device__ __forceinline__ void phase_mixer(const Params& p, LAS unsigned char* lds, int l, bool with_ctx, int G, int tid, int wave, int lane, int rep_attn, int rep_pool) {
;     ...
;         for (int o = 0; o < 16; ++o) {
;             const int t = t0 + o, st = max(t - lo, 0), en = min(t + hi + 1, len);
;             float acc[8];
; #pragma unroll
;             for (int e = 0; e < 8; ++e) acc[e] = 0.f;
; #pragma unroll
;             for (int i = 0; i < 16; ++i) { const int tt = t + i - 8; const float wt = (tt >= st && tt < en) ? 1.f : 0.f; const u32x4 ww = w[o + i];
;                 acc[0] += wt * bf_lo(ww.x); acc[1] += wt * bf_hi(ww.x); acc[2] += wt * bf_lo(ww.y); acc[3] += wt * bf_hi(ww.y);
;                 acc[4] += wt * bf_lo(ww.z); acc[5] += wt * bf_hi(ww.z); acc[6] += wt * bf_lo(ww.w); acc[7] += wt * bf_hi(ww.w); }
;             const float ic = 1.f / (float)(en - st);
;             const u32x4 sw = w[o + 8];
;             u32x4 ov; ov.x = cvt_pk_bf16(acc[0] * ic - bf_lo(sw.x), acc[1] * ic - bf_hi(sw.x)); ov.y = cvt_pk_bf16(acc[2] * ic - bf_lo(sw.y), acc[3] * ic - bf_hi(sw.y));
;             ov.z = cvt_pk_bf16(acc[4] * ic - bf_lo(sw.z), acc[5] * ic - bf_hi(sw.z)); ov.w = cvt_pk_bf16(acc[6] * ic - bf_lo(sw.w), acc[7] * ic - bf_hi(sw.w));
;             *(u32x4*)(MIX + (size_t)(tok0 + o) * DM + 8 * lane) = ov;
	v_lshlrev_b32_e32 v106, 16, v48
	v_and_b32_e32 v107, 0xffff0000, v48
	v_pk_fma_f32 v[206:207], v[232:233], v[52:53], v[206:207] op_sel_hi:[0,1,1]
	v_lshlrev_b32_e32 v48, 16, v49
	v_and_b32_e32 v49, 0xffff0000, v49
	v_pk_fma_f32 v[108:109], v[230:231], v[76:77], v[108:109] op_sel_hi:[0,1,1]
	v_pk_fma_f32 v[190:191], v[230:231], v[70:71], v[190:191] op_sel_hi:[0,1,1]
	v_pk_fma_f32 v[208:209], v[232:233], v[106:107], v[208:209] op_sel_hi:[0,1,1]
	v_pk_fma_f32 v[206:207], v[232:233], v[48:49], v[206:207] op_sel_hi:[0,1,1]
	v_pk_fma_f32 v[108:109], v[232:233], v[68:69], v[108:109] op_sel_hi:[0,1,1]
	v_pk_fma_f32 v[190:191], v[232:233], v[66:67], v[190:191] op_sel_hi:[0,1,1]
	v_pk_fma_f32 v[208:209], v[122:123], v[208:209], v[112:113] op_sel_hi:[0,1,1] neg_lo:[0,0,1] neg_hi:[0,0,1]
	v_pk_fma_f32 v[206:207], v[122:123], v[206:207], v[114:115] op_sel_hi:[0,1,1] neg_lo:[0,0,1] neg_hi:[0,0,1]
	v_pk_fma_f32 v[108:109], v[232:233], v[62:63], v[108:109] op_sel_hi:[0,1,1]
	v_pk_fma_f32 v[190:191], v[232:233], v[58:59], v[190:191] op_sel_hi:[0,1,1]
	v_cvt_pk_bf16_f32 v208, v208, v209
	v_cvt_pk_bf16_f32 v209, v206, v207
	v_pk_fma_f32 v[206:207], v[232:233], v[78:79], v[108:109] op_sel_hi:[0,1,1]
	v_lshlrev_b32_e32 v108, 16, v50
	v_and_b32_e32 v109, 0xffff0000, v50
	v_pk_fma_f32 v[190:191], v[232:233], v[54:55], v[190:191] op_sel_hi:[0,1,1]
	v_lshlrev_b32_e32 v50, 16, v51
	v_and_b32_e32 v51, 0xffff0000, v51
	s_or_b32 s0, s4, 3
	v_pk_fma_f32 v[206:207], v[232:233], v[108:109], v[206:207] op_sel_hi:[0,1,1]
	v_pk_fma_f32 v[120:121], v[232:233], v[50:51], v[190:191] op_sel_hi:[0,1,1]
	s_ashr_i32 s1, s0, 31
	v_pk_fma_f32 v[206:207], v[122:123], v[206:207], v[116:117] op_sel_hi:[0,1,1] neg_lo:[0,0,1] neg_hi:[0,0,1]
	v_pk_fma_f32 v[120:121], v[122:123], v[120:121], v[134:135] op_sel_hi:[0,1,1] neg_lo:[0,0,1] neg_hi:[0,0,1]
	s_lshl_b64 s[0:1], s[0:1], 11
	v_cvt_pk_bf16_f32 v210, v206, v207
	v_cvt_pk_bf16_f32 v211, v120, v121
	v_lshl_add_u64 v[120:121], v[126:127], 0, s[0:1]
	global_store_dwordx4 v[120:121], v[208:211], off
	v_sub_u32_e32 v120, s21, v167
	v_add_u32_e32 v121, s21, v167
	v_max_i32_e32 v160, 0, v120
	v_min_i32_e32 v161, s9, v121
	v_pk_fma_f32 v[122:123], v[232:233], v[182:183], 0 op_sel_hi:[0,1,0]
	v_pk_fma_f32 v[122:123], v[232:233], v[136:137], v[122:123] op_sel_hi:[0,1,1]
	v_pk_fma_f32 v[122:123], v[232:233], v[148:149], v[122:123] op_sel_hi:[0,1,1]
	v_pk_fma_f32 v[122:123], v[232:233], v[146:147], v[122:123] op_sel_hi:[0,1,1]
	v_pk_fma_f32 v[122:123], v[230:231], v[152:153], v[122:123] op_sel_hi:[0,1,1]
	v_pk_fma_f32 v[122:123], v[230:231], v[132:133], v[122:123] op_sel_hi:[0,1,1]
	v_pk_fma_f32 v[204:205], v[228:229], v[104:105], v[122:123] op_sel_hi:[0,1,1]
	v_pk_fma_f32 v[122:123], v[232:233], v[184:185], 0 op_sel_hi:[0,1,0]
	v_pk_fma_f32 v[122:123], v[232:233], v[138:139], v[122:123] op_sel_hi:[0,1,1]
	v_pk_fma_f32 v[122:123], v[232:233], v[150:151], v[122:123] op_sel_hi:[0,1,1]
	v_pk_fma_f32 v[122:123], v[232:233], v[144:145], v[122:123] op_sel_hi:[0,1,1]
	v_pk_fma_f32 v[122:123], v[230:231], v[154:155], v[122:123] op_sel_hi:[0,1,1]
	v_pk_fma_f32 v[122:123], v[230:231], v[130:131], v[122:123] op_sel_hi:[0,1,1]
	v_pk_fma_f32 v[202:203], v[228:229], v[102:103], v[122:123] op_sel_hi:[0,1,1]
	v_pk_fma_f32 v[122:123], v[232:233], v[186:187], 0 op_sel_hi:[0,1,0]
	v_pk_fma_f32 v[120:121], v[232:233], v[188:189], 0 op_sel_hi:[0,1,0]
	v_pk_fma_f32 v[122:123], v[232:233], v[178:179], v[122:123] op_sel_hi:[0,1,1]
	v_pk_fma_f32 v[120:121], v[232:233], v[180:181], v[120:121] op_sel_hi:[0,1,1]
	v_pk_fma_f32 v[122:123], v[232:233], v[174:175], v[122:123] op_sel_hi:[0,1,1]
	v_pk_fma_f32 v[120:121], v[232:233], v[176:177], v[120:121] op_sel_hi:[0,1,1]
	v_pk_fma_f32 v[122:123], v[232:233], v[142:143], v[122:123] op_sel_hi:[0,1,1]
	v_pk_fma_f32 v[120:121], v[232:233], v[140:141], v[120:121] op_sel_hi:[0,1,1]
	v_pk_fma_f32 v[122:123], v[230:231], v[170:171], v[122:123] op_sel_hi:[0,1,1]
	v_pk_fma_f32 v[120:121], v[230:231], v[172:173], v[120:121] op_sel_hi:[0,1,1]
	v_pk_fma_f32 v[122:123], v[230:231], v[128:129], v[122:123] op_sel_hi:[0,1,1]
	v_pk_fma_f32 v[120:121], v[230:231], v[118:119], v[120:121] op_sel_hi:[0,1,1]
	v_pk_fma_f32 v[184:185], v[228:229], v[98:99], v[120:121] op_sel_hi:[0,1,1]
	v_sub_u32_e32 v120, v161, v160
	v_pk_fma_f32 v[122:123], v[228:229], v[100:101], v[122:123] op_sel_hi:[0,1,1]
	v_cvt_f32_i32_e32 v120, v120
	v_pk_fma_f32 v[202:203], v[234:235], v[114:115], v[202:203] op_sel_hi:[0,1,1]
	v_div_scale_f32 v121, s[0:1], v120, v120, 1.0
	v_rcp_f32_e32 v160, v121
	v_pk_fma_f32 v[202:203], v[234:235], v[94:95], v[202:203] op_sel_hi:[0,1,1]
	v_pk_fma_f32 v[202:203], v[228:229], v[80:81], v[202:203] op_sel_hi:[0,1,1]
	v_pk_fma_f32 v[202:203], v[230:231], v[72:73], v[202:203] op_sel_hi:[0,1,1]
	v_fma_f32 v161, -v121, v160, 1.0
	v_fmac_f32_e32 v160, v161, v160
	v_div_scale_f32 v161, vcc, 1.0, v120, 1.0
	v_mul_f32_e32 v182, v161, v160
	v_fma_f32 v183, -v121, v182, v161
	v_fmac_f32_e32 v182, v183, v160
	v_fma_f32 v121, -v121, v182, v161
	v_div_fmas_f32 v121, v121, v160, v182
	v_div_fixup_f32 v182, v121, v120, 1.0
	v_pk_fma_f32 v[120:121], v[234:235], v[112:113], v[204:205] op_sel_hi:[0,1,1]
	v_pk_fma_f32 v[120:121], v[234:235], v[92:93], v[120:121] op_sel_hi:[0,1,1]
	v_pk_fma_f32 v[120:121], v[228:229], v[88:89], v[120:121] op_sel_hi:[0,1,1]
	v_pk_fma_f32 v[120:121], v[230:231], v[86:87], v[120:121] op_sel_hi:[0,1,1]
	v_pk_fma_f32 v[122:123], v[234:235], v[116:117], v[122:123] op_sel_hi:[0,1,1]
	v_pk_fma_f32 v[184:185], v[234:235], v[134:135], v[184:185] op_sel_hi:[0,1,1]
	v_pk_fma_f32 v[120:121], v[230:231], v[84:85], v[120:121] op_sel_hi:[0,1,1]
	v_pk_fma_f32 v[202:203], v[230:231], v[64:65], v[202:203] op_sel_hi:[0,1,1]
	v_pk_fma_f32 v[122:123], v[234:235], v[96:97], v[122:123] op_sel_hi:[0,1,1]
	v_pk_fma_f32 v[184:185], v[234:235], v[110:111], v[184:185] op_sel_hi:[0,1,1]
	v_pk_fma_f32 v[120:121], v[232:233], v[60:61], v[120:121] op_sel_hi:[0,1,1]
	v_pk_fma_f32 v[202:203], v[232:233], v[56:57], v[202:203] op_sel_hi:[0,1,1]
	v_pk_fma_f32 v[122:123], v[228:229], v[90:91], v[122:123] op_sel_hi:[0,1,1]
	v_pk_fma_f32 v[184:185], v[228:229], v[82:83], v[184:185] op_sel_hi:[0,1,1]
	v_pk_fma_f32 v[120:121], v[232:233], v[74:75], v[120:121] op_sel_hi:[0,1,1]
	v_pk_fma_f32 v[202:203], v[232:233], v[52:53], v[202:203] op_sel_hi:[0,1,1]
	v_pk_fma_f32 v[122:123], v[230:231], v[76:77], v[122:123] op_sel_hi:[0,1,1]
	v_pk_fma_f32 v[184:185], v[230:231], v[70:71], v[184:185] op_sel_hi:[0,1,1]
	v_pk_fma_f32 v[204:205], v[232:233], v[106:107], v[120:121] op_sel_hi:[0,1,1]
	s_waitcnt vmcnt(15)
; __device__ __forceinline__ unsigned cvt_pk_bf16(float lo, float hi) { const f32x2 v = (f32x2){lo, hi}; return __builtin_bit_cast(unsigned, __builtin_convertvector(v, bf16v2)); }
; __device__ __forceinline__ float bf_lo(unsigned w) { return __uint_as_float(w << 16); }
; __device__ __forceinline__ float bf_hi(unsigned w) { return __uint_as_float(w & 0xffff0000u); }
; __device__ __forceinline__ void phase_mixer(const Params& p, LAS unsigned char* lds, int l, bool with_ctx, int G, int tid, int wave, int lane, int rep_attn, int rep_pool) {
;     ...
;         for (int o = 0; o < 16; ++o) {
;             const int t = t0 + o, st = max(t - lo, 0), en = min(t + hi + 1, len);
;             float acc[8];
; #pragma unroll
;             for (int e = 0; e < 8; ++e) acc[e] = 0.f;
; #pragma unroll
;             for (int i = 0; i < 16; ++i) { const int tt = t + i - 8; const float wt = (tt >= st && tt < en) ? 1.f : 0.f; const u32x4 ww = w[o + i];
;                 acc[0] += wt * bf_lo(ww.x); acc[1] += wt * bf_hi(ww.x); acc[2] += wt * bf_lo(ww.y); acc[3] += wt * bf_hi(ww.y);
;                 acc[4] += wt * bf_lo(ww.z); acc[5] += wt * bf_hi(ww.z); acc[6] += wt * bf_lo(ww.w); acc[7] += wt * bf_hi(ww.w); }
;             const float ic = 1.f / (float)(en - st);
;             const u32x4 sw = w[o + 8];
;             u32x4 ov; ov.x = cvt_pk_bf16(acc[0] * ic - bf_lo(sw.x), acc[1] * ic - bf_hi(sw.x)); ov.y = cvt_pk_bf16(acc[2] * ic - bf_lo(sw.y), acc[3] * ic - bf_hi(sw.y));
;             ov.z = cvt_pk_bf16(acc[4] * ic - bf_lo(sw.z), acc[5] * ic - bf_hi(sw.z)); ov.w = cvt_pk_bf16(acc[6] * ic - bf_lo(sw.w), acc[7] * ic - bf_hi(sw.w));
;             *(u32x4*)(MIX + (size_t)(tok0 + o) * DM + 8 * lane) = ov;
	v_lshlrev_b32_e32 v120, 16, v44
	v_and_b32_e32 v121, 0xffff0000, v44
	v_pk_fma_f32 v[202:203], v[232:233], v[48:49], v[202:203] op_sel_hi:[0,1,1]
	v_lshlrev_b32_e32 v44, 16, v45
	v_and_b32_e32 v45, 0xffff0000, v45
	v_pk_fma_f32 v[122:123], v[230:231], v[68:69], v[122:123] op_sel_hi:[0,1,1]
	v_pk_fma_f32 v[184:185], v[230:231], v[66:67], v[184:185] op_sel_hi:[0,1,1]
	v_pk_fma_f32 v[204:205], v[232:233], v[120:121], v[204:205] op_sel_hi:[0,1,1]
	v_pk_fma_f32 v[202:203], v[232:233], v[44:45], v[202:203] op_sel_hi:[0,1,1]
	v_pk_fma_f32 v[122:123], v[232:233], v[62:63], v[122:123] op_sel_hi:[0,1,1]
	v_pk_fma_f32 v[184:185], v[232:233], v[58:59], v[184:185] op_sel_hi:[0,1,1]
	v_pk_fma_f32 v[204:205], v[182:183], v[204:205], v[92:93] op_sel_hi:[0,1,1] neg_lo:[0,0,1] neg_hi:[0,0,1]
	v_pk_fma_f32 v[202:203], v[182:183], v[202:203], v[94:95] op_sel_hi:[0,1,1] neg_lo:[0,0,1] neg_hi:[0,0,1]
	v_pk_fma_f32 v[122:123], v[232:233], v[78:79], v[122:123] op_sel_hi:[0,1,1]
	v_pk_fma_f32 v[184:185], v[232:233], v[54:55], v[184:185] op_sel_hi:[0,1,1]
	v_cvt_pk_bf16_f32 v204, v204, v205
	v_cvt_pk_bf16_f32 v205, v202, v203
	v_pk_fma_f32 v[202:203], v[232:233], v[108:109], v[122:123] op_sel_hi:[0,1,1]
	v_lshlrev_b32_e32 v122, 16, v46
	v_and_b32_e32 v123, 0xffff0000, v46
	v_pk_fma_f32 v[184:185], v[232:233], v[50:51], v[184:185] op_sel_hi:[0,1,1]
	v_lshlrev_b32_e32 v46, 16, v47
	v_and_b32_e32 v47, 0xffff0000, v47
	s_or_b32 s0, s4, 4
	v_pk_fma_f32 v[202:203], v[232:233], v[122:123], v[202:203] op_sel_hi:[0,1,1]
	v_pk_fma_f32 v[184:185], v[232:233], v[46:47], v[184:185] op_sel_hi:[0,1,1]
	s_ashr_i32 s1, s0, 31
	v_sub_u32_e32 v156, s20, v167
	v_add_u32_e32 v160, s20, v167
	v_pk_fma_f32 v[202:203], v[182:183], v[202:203], v[96:97] op_sel_hi:[0,1,1] neg_lo:[0,0,1] neg_hi:[0,0,1]
	v_pk_fma_f32 v[182:183], v[182:183], v[184:185], v[110:111] op_sel_hi:[0,1,1] neg_lo:[0,0,1] neg_hi:[0,0,1]
	s_lshl_b64 s[0:1], s[0:1], 11
	v_max_i32_e32 v161, 0, v156
	v_min_i32_e32 v160, s9, v160
	v_cvt_pk_bf16_f32 v207, v182, v183
	v_lshl_add_u64 v[182:183], v[126:127], 0, s[0:1]
	v_cvt_pk_bf16_f32 v206, v202, v203
	global_store_dwordx4 v[182:183], v[204:207], off
	v_pk_fma_f32 v[138:139], v[232:233], v[138:139], 0 op_sel_hi:[0,1,0]
	v_pk_fma_f32 v[138:139], v[232:233], v[150:151], v[138:139] op_sel_hi:[0,1,1]
	v_pk_fma_f32 v[138:139], v[232:233], v[144:145], v[138:139] op_sel_hi:[0,1,1]
	v_pk_fma_f32 v[138:139], v[232:233], v[154:155], v[138:139] op_sel_hi:[0,1,1]
	v_pk_fma_f32 v[138:139], v[230:231], v[130:131], v[138:139] op_sel_hi:[0,1,1]
	v_pk_fma_f32 v[138:139], v[230:231], v[102:103], v[138:139] op_sel_hi:[0,1,1]
	v_pk_fma_f32 v[136:137], v[232:233], v[136:137], 0 op_sel_hi:[0,1,0]
	v_pk_fma_f32 v[198:199], v[228:229], v[114:115], v[138:139] op_sel_hi:[0,1,1]
	v_pk_fma_f32 v[138:139], v[232:233], v[178:179], 0 op_sel_hi:[0,1,0]
	v_pk_fma_f32 v[178:179], v[232:233], v[180:181], 0 op_sel_hi:[0,1,0]
	v_pk_fma_f32 v[136:137], v[232:233], v[148:149], v[136:137] op_sel_hi:[0,1,1]
	v_pk_fma_f32 v[138:139], v[232:233], v[174:175], v[138:139] op_sel_hi:[0,1,1]
	v_pk_fma_f32 v[178:179], v[232:233], v[176:177], v[178:179] op_sel_hi:[0,1,1]
	v_pk_fma_f32 v[136:137], v[232:233], v[146:147], v[136:137] op_sel_hi:[0,1,1]
	v_pk_fma_f32 v[138:139], v[232:233], v[142:143], v[138:139] op_sel_hi:[0,1,1]
	v_pk_fma_f32 v[178:179], v[232:233], v[140:141], v[178:179] op_sel_hi:[0,1,1]
	v_pk_fma_f32 v[136:137], v[232:233], v[152:153], v[136:137] op_sel_hi:[0,1,1]
	v_pk_fma_f32 v[138:139], v[232:233], v[170:171], v[138:139] op_sel_hi:[0,1,1]
	v_pk_fma_f32 v[178:179], v[232:233], v[172:173], v[178:179] op_sel_hi:[0,1,1]
	v_pk_fma_f32 v[136:137], v[230:231], v[132:133], v[136:137] op_sel_hi:[0,1,1]
	v_pk_fma_f32 v[138:139], v[230:231], v[128:129], v[138:139] op_sel_hi:[0,1,1]
	v_pk_fma_f32 v[178:179], v[230:231], v[118:119], v[178:179] op_sel_hi:[0,1,1]
	v_pk_fma_f32 v[136:137], v[230:231], v[104:105], v[136:137] op_sel_hi:[0,1,1]
	v_pk_fma_f32 v[138:139], v[230:231], v[100:101], v[138:139] op_sel_hi:[0,1,1]
	v_pk_fma_f32 v[178:179], v[230:231], v[98:99], v[178:179] op_sel_hi:[0,1,1]
	v_pk_fma_f32 v[136:137], v[228:229], v[112:113], v[136:137] op_sel_hi:[0,1,1]
	v_pk_fma_f32 v[138:139], v[228:229], v[116:117], v[138:139] op_sel_hi:[0,1,1]
	v_pk_fma_f32 v[180:181], v[228:229], v[134:135], v[178:179] op_sel_hi:[0,1,1]
	v_sub_u32_e32 v160, v160, v161
	v_cvt_f32_i32_e32 v160, v160
	v_div_scale_f32 v161, s[0:1], v160, v160, 1.0
	v_rcp_f32_e32 v178, v161
	s_or_b32 s0, s4, 5
	s_ashr_i32 s1, s0, 31
	s_lshl_b64 s[0:1], s[0:1], 11
	v_fma_f32 v179, -v161, v178, 1.0
	v_fmac_f32_e32 v178, v179, v178
	v_div_scale_f32 v179, vcc, 1.0, v160, 1.0
	v_mul_f32_e32 v183, v179, v178
	v_fma_f32 v185, -v161, v183, v179
	v_fmac_f32_e32 v183, v185, v178
	v_pk_fma_f32 v[136:137], v[234:235], v[92:93], v[136:137] op_sel_hi:[0,1,1]
	v_pk_fma_f32 v[198:199], v[234:235], v[94:95], v[198:199] op_sel_hi:[0,1,1]
	v_pk_fma_f32 v[136:137], v[234:235], v[88:89], v[136:137] op_sel_hi:[0,1,1]
	v_pk_fma_f32 v[198:199], v[234:235], v[80:81], v[198:199] op_sel_hi:[0,1,1]
	v_pk_fma_f32 v[136:137], v[228:229], v[86:87], v[136:137] op_sel_hi:[0,1,1]
	v_pk_fma_f32 v[198:199], v[228:229], v[72:73], v[198:199] op_sel_hi:[0,1,1]
	v_pk_fma_f32 v[136:137], v[230:231], v[84:85], v[136:137] op_sel_hi:[0,1,1]
	v_pk_fma_f32 v[198:199], v[230:231], v[64:65], v[198:199] op_sel_hi:[0,1,1]
	v_pk_fma_f32 v[138:139], v[234:235], v[96:97], v[138:139] op_sel_hi:[0,1,1]
	v_pk_fma_f32 v[180:181], v[234:235], v[110:111], v[180:181] op_sel_hi:[0,1,1]
	v_pk_fma_f32 v[136:137], v[230:231], v[60:61], v[136:137] op_sel_hi:[0,1,1]
	v_pk_fma_f32 v[198:199], v[230:231], v[56:57], v[198:199] op_sel_hi:[0,1,1]
	v_pk_fma_f32 v[138:139], v[234:235], v[90:91], v[138:139] op_sel_hi:[0,1,1]
	v_pk_fma_f32 v[180:181], v[234:235], v[82:83], v[180:181] op_sel_hi:[0,1,1]
	v_pk_fma_f32 v[136:137], v[232:233], v[74:75], v[136:137] op_sel_hi:[0,1,1]
	v_pk_fma_f32 v[198:199], v[232:233], v[52:53], v[198:199] op_sel_hi:[0,1,1]
	v_pk_fma_f32 v[138:139], v[228:229], v[76:77], v[138:139] op_sel_hi:[0,1,1]
	v_pk_fma_f32 v[180:181], v[228:229], v[70:71], v[180:181] op_sel_hi:[0,1,1]
	v_fma_f32 v161, -v161, v183, v179
	v_pk_fma_f32 v[136:137], v[232:233], v[106:107], v[136:137] op_sel_hi:[0,1,1]
	v_pk_fma_f32 v[198:199], v[232:233], v[48:49], v[198:199] op_sel_hi:[0,1,1]
	v_pk_fma_f32 v[138:139], v[230:231], v[68:69], v[138:139] op_sel_hi:[0,1,1]
	v_pk_fma_f32 v[180:181], v[230:231], v[66:67], v[180:181] op_sel_hi:[0,1,1]
	v_div_fmas_f32 v161, v161, v178, v183
	v_pk_fma_f32 v[200:201], v[232:233], v[120:121], v[136:137] op_sel_hi:[0,1,1]
	s_waitcnt vmcnt(15)
; __device__ __forceinline__ unsigned cvt_pk_bf16(float lo, float hi) { const f32x2 v = (f32x2){lo, hi}; return __builtin_bit_cast(unsigned, __builtin_convertvector(v, bf16v2)); }
; __device__ __forceinline__ float bf_lo(unsigned w) { return __uint_as_float(w << 16); }
; __device__ __forceinline__ float bf_hi(unsigned w) { return __uint_as_float(w & 0xffff0000u); }
; __device__ __forceinline__ void phase_mixer(const Params& p, LAS unsigned char* lds, int l, bool with_ctx, int G, int tid, int wave, int lane, int rep_attn, int rep_pool) {
;     ...
;         for (int o = 0; o < 16; ++o) {
;             const int t = t0 + o, st = max(t - lo, 0), en = min(t + hi + 1, len);
;             float acc[8];
; #pragma unroll
;             for (int e = 0; e < 8; ++e) acc[e] = 0.f;
; #pragma unroll
;             for (int i = 0; i < 16; ++i) { const int tt = t + i - 8; const float wt = (tt >= st && tt < en) ? 1.f : 0.f; const u32x4 ww = w[o + i];
;                 acc[0] += wt * bf_lo(ww.x); acc[1] += wt * bf_hi(ww.x); acc[2] += wt * bf_lo(ww.y); acc[3] += wt * bf_hi(ww.y);
;                 acc[4] += wt * bf_lo(ww.z); acc[5] += wt * bf_hi(ww.z); acc[6] += wt * bf_lo(ww.w); acc[7] += wt * bf_hi(ww.w); }
;             const float ic = 1.f / (float)(en - st);
;             const u32x4 sw = w[o + 8];
;             u32x4 ov; ov.x = cvt_pk_bf16(acc[0] * ic - bf_lo(sw.x), acc[1] * ic - bf_hi(sw.x)); ov.y = cvt_pk_bf16(acc[2] * ic - bf_lo(sw.y), acc[3] * ic - bf_hi(sw.y));
;             ov.z = cvt_pk_bf16(acc[4] * ic - bf_lo(sw.z), acc[5] * ic - bf_hi(sw.z)); ov.w = cvt_pk_bf16(acc[6] * ic - bf_lo(sw.w), acc[7] * ic - bf_hi(sw.w));
;             *(u32x4*)(MIX + (size_t)(tok0 + o) * DM + 8 * lane) = ov;
	v_lshlrev_b32_e32 v136, 16, v40
	v_and_b32_e32 v137, 0xffff0000, v40
	v_pk_fma_f32 v[198:199], v[232:233], v[44:45], v[198:199] op_sel_hi:[0,1,1]
	v_lshlrev_b32_e32 v40, 16, v41
	v_and_b32_e32 v41, 0xffff0000, v41
	v_pk_fma_f32 v[138:139], v[230:231], v[62:63], v[138:139] op_sel_hi:[0,1,1]
	v_pk_fma_f32 v[180:181], v[230:231], v[58:59], v[180:181] op_sel_hi:[0,1,1]
	v_div_fixup_f32 v178, v161, v160, 1.0
	v_pk_fma_f32 v[200:201], v[232:233], v[136:137], v[200:201] op_sel_hi:[0,1,1]
	v_pk_fma_f32 v[198:199], v[232:233], v[40:41], v[198:199] op_sel_hi:[0,1,1]
	v_pk_fma_f32 v[138:139], v[232:233], v[78:79], v[138:139] op_sel_hi:[0,1,1]
	v_pk_fma_f32 v[180:181], v[232:233], v[54:55], v[180:181] op_sel_hi:[0,1,1]
	v_pk_fma_f32 v[200:201], v[178:179], v[200:201], v[88:89] op_sel_hi:[0,1,1] neg_lo:[0,0,1] neg_hi:[0,0,1]
	v_pk_fma_f32 v[198:199], v[178:179], v[198:199], v[80:81] op_sel_hi:[0,1,1] neg_lo:[0,0,1] neg_hi:[0,0,1]
	v_pk_fma_f32 v[138:139], v[232:233], v[108:109], v[138:139] op_sel_hi:[0,1,1]
	v_pk_fma_f32 v[180:181], v[232:233], v[50:51], v[180:181] op_sel_hi:[0,1,1]
	v_cvt_pk_bf16_f32 v200, v200, v201
	v_cvt_pk_bf16_f32 v201, v198, v199
	v_pk_fma_f32 v[198:199], v[232:233], v[122:123], v[138:139] op_sel_hi:[0,1,1]
	v_lshlrev_b32_e32 v138, 16, v42
	v_and_b32_e32 v139, 0xffff0000, v42
	v_pk_fma_f32 v[180:181], v[232:233], v[46:47], v[180:181] op_sel_hi:[0,1,1]
	v_lshlrev_b32_e32 v42, 16, v43
	v_and_b32_e32 v43, 0xffff0000, v43
	v_pk_fma_f32 v[198:199], v[232:233], v[138:139], v[198:199] op_sel_hi:[0,1,1]
	v_pk_fma_f32 v[180:181], v[232:233], v[42:43], v[180:181] op_sel_hi:[0,1,1]
	v_sub_u32_e32 v156, s19, v167
	v_add_u32_e32 v160, s19, v167
	v_pk_fma_f32 v[198:199], v[178:179], v[198:199], v[90:91] op_sel_hi:[0,1,1] neg_lo:[0,0,1] neg_hi:[0,0,1]
	v_pk_fma_f32 v[178:179], v[178:179], v[180:181], v[82:83] op_sel_hi:[0,1,1] neg_lo:[0,0,1] neg_hi:[0,0,1]
	v_max_i32_e32 v161, 0, v156
	v_min_i32_e32 v160, s9, v160
	v_cvt_pk_bf16_f32 v203, v178, v179
	v_lshl_add_u64 v[178:179], v[126:127], 0, s[0:1]
	v_cvt_pk_bf16_f32 v202, v198, v199
	global_store_dwordx4 v[178:179], v[200:203], off
	v_pk_fma_f32 v[150:151], v[232:233], v[150:151], 0 op_sel_hi:[0,1,0]
	v_pk_fma_f32 v[150:151], v[232:233], v[144:145], v[150:151] op_sel_hi:[0,1,1]
	v_pk_fma_f32 v[150:151], v[232:233], v[154:155], v[150:151] op_sel_hi:[0,1,1]
	v_pk_fma_f32 v[150:151], v[232:233], v[130:131], v[150:151] op_sel_hi:[0,1,1]
	v_pk_fma_f32 v[150:151], v[230:231], v[102:103], v[150:151] op_sel_hi:[0,1,1]
	v_pk_fma_f32 v[150:151], v[230:231], v[114:115], v[150:151] op_sel_hi:[0,1,1]
	v_pk_fma_f32 v[148:149], v[232:233], v[148:149], 0 op_sel_hi:[0,1,0]
	v_pk_fma_f32 v[194:195], v[228:229], v[94:95], v[150:151] op_sel_hi:[0,1,1]
	v_pk_fma_f32 v[150:151], v[232:233], v[174:175], 0 op_sel_hi:[0,1,0]
	v_pk_fma_f32 v[174:175], v[232:233], v[176:177], 0 op_sel_hi:[0,1,0]
	v_pk_fma_f32 v[148:149], v[232:233], v[146:147], v[148:149] op_sel_hi:[0,1,1]
	v_pk_fma_f32 v[150:151], v[232:233], v[142:143], v[150:151] op_sel_hi:[0,1,1]
	v_pk_fma_f32 v[174:175], v[232:233], v[140:141], v[174:175] op_sel_hi:[0,1,1]
	v_pk_fma_f32 v[148:149], v[232:233], v[152:153], v[148:149] op_sel_hi:[0,1,1]
	v_pk_fma_f32 v[150:151], v[232:233], v[170:171], v[150:151] op_sel_hi:[0,1,1]
	v_pk_fma_f32 v[174:175], v[232:233], v[172:173], v[174:175] op_sel_hi:[0,1,1]
	v_pk_fma_f32 v[148:149], v[232:233], v[132:133], v[148:149] op_sel_hi:[0,1,1]
	v_pk_fma_f32 v[150:151], v[232:233], v[128:129], v[150:151] op_sel_hi:[0,1,1]
	v_pk_fma_f32 v[174:175], v[232:233], v[118:119], v[174:175] op_sel_hi:[0,1,1]
	v_pk_fma_f32 v[148:149], v[230:231], v[104:105], v[148:149] op_sel_hi:[0,1,1]
	v_pk_fma_f32 v[150:151], v[230:231], v[100:101], v[150:151] op_sel_hi:[0,1,1]
	v_pk_fma_f32 v[174:175], v[230:231], v[98:99], v[174:175] op_sel_hi:[0,1,1]
	v_pk_fma_f32 v[148:149], v[230:231], v[112:113], v[148:149] op_sel_hi:[0,1,1]
	v_pk_fma_f32 v[150:151], v[230:231], v[116:117], v[150:151] op_sel_hi:[0,1,1]
	v_pk_fma_f32 v[174:175], v[230:231], v[134:135], v[174:175] op_sel_hi:[0,1,1]
	v_pk_fma_f32 v[148:149], v[228:229], v[92:93], v[148:149] op_sel_hi:[0,1,1]
	v_pk_fma_f32 v[150:151], v[228:229], v[96:97], v[150:151] op_sel_hi:[0,1,1]
	v_pk_fma_f32 v[176:177], v[228:229], v[110:111], v[174:175] op_sel_hi:[0,1,1]
	v_sub_u32_e32 v160, v160, v161
	v_cvt_f32_i32_e32 v160, v160
	v_div_scale_f32 v161, s[0:1], v160, v160, 1.0
	v_rcp_f32_e32 v174, v161
	s_or_b32 s0, s4, 6
	s_ashr_i32 s1, s0, 31
	s_lshl_b64 s[0:1], s[0:1], 11
	v_fma_f32 v175, -v161, v174, 1.0
	v_fmac_f32_e32 v174, v175, v174
	v_div_scale_f32 v175, vcc, 1.0, v160, 1.0
	v_mul_f32_e32 v179, v175, v174
	v_fma_f32 v181, -v161, v179, v175
	v_fmac_f32_e32 v179, v181, v174
	v_pk_fma_f32 v[148:149], v[234:235], v[88:89], v[148:149] op_sel_hi:[0,1,1]
	v_pk_fma_f32 v[194:195], v[234:235], v[80:81], v[194:195] op_sel_hi:[0,1,1]
	v_pk_fma_f32 v[148:149], v[234:235], v[86:87], v[148:149] op_sel_hi:[0,1,1]
	v_pk_fma_f32 v[194:195], v[234:235], v[72:73], v[194:195] op_sel_hi:[0,1,1]
	v_pk_fma_f32 v[148:149], v[228:229], v[84:85], v[148:149] op_sel_hi:[0,1,1]
	v_pk_fma_f32 v[194:195], v[228:229], v[64:65], v[194:195] op_sel_hi:[0,1,1]
	v_pk_fma_f32 v[148:149], v[230:231], v[60:61], v[148:149] op_sel_hi:[0,1,1]
	v_pk_fma_f32 v[194:195], v[230:231], v[56:57], v[194:195] op_sel_hi:[0,1,1]
	v_pk_fma_f32 v[150:151], v[234:235], v[90:91], v[150:151] op_sel_hi:[0,1,1]
	v_pk_fma_f32 v[176:177], v[234:235], v[82:83], v[176:177] op_sel_hi:[0,1,1]
	v_pk_fma_f32 v[148:149], v[230:231], v[74:75], v[148:149] op_sel_hi:[0,1,1]
	v_pk_fma_f32 v[194:195], v[230:231], v[52:53], v[194:195] op_sel_hi:[0,1,1]
	v_pk_fma_f32 v[150:151], v[234:235], v[76:77], v[150:151] op_sel_hi:[0,1,1]
	v_pk_fma_f32 v[176:177], v[234:235], v[70:71], v[176:177] op_sel_hi:[0,1,1]
	v_pk_fma_f32 v[148:149], v[232:233], v[106:107], v[148:149] op_sel_hi:[0,1,1]
	v_pk_fma_f32 v[194:195], v[232:233], v[48:49], v[194:195] op_sel_hi:[0,1,1]
	v_pk_fma_f32 v[150:151], v[228:229], v[68:69], v[150:151] op_sel_hi:[0,1,1]
	v_pk_fma_f32 v[176:177], v[228:229], v[66:67], v[176:177] op_sel_hi:[0,1,1]
	v_fma_f32 v161, -v161, v179, v175
	v_pk_fma_f32 v[148:149], v[232:233], v[120:121], v[148:149] op_sel_hi:[0,1,1]
	v_pk_fma_f32 v[194:195], v[232:233], v[44:45], v[194:195] op_sel_hi:[0,1,1]
	v_pk_fma_f32 v[150:151], v[230:231], v[62:63], v[150:151] op_sel_hi:[0,1,1]
	v_pk_fma_f32 v[176:177], v[230:231], v[58:59], v[176:177] op_sel_hi:[0,1,1]
	v_div_fmas_f32 v161, v161, v174, v179
	v_pk_fma_f32 v[196:197], v[232:233], v[136:137], v[148:149] op_sel_hi:[0,1,1]
	s_waitcnt vmcnt(15)
; __device__ __forceinline__ unsigned cvt_pk_bf16(float lo, float hi) { const f32x2 v = (f32x2){lo, hi}; return __builtin_bit_cast(unsigned, __builtin_convertvector(v, bf16v2)); }
; __device__ __forceinline__ float bf_lo(unsigned w) { return __uint_as_float(w << 16); }
; __device__ __forceinline__ float bf_hi(unsigned w) { return __uint_as_float(w & 0xffff0000u); }
; __device__ __forceinline__ void phase_mixer(const Params& p, LAS unsigned char* lds, int l, bool with_ctx, int G, int tid, int wave, int lane, int rep_attn, int rep_pool) {
;     ...
;         for (int o = 0; o < 16; ++o) {
;             const int t = t0 + o, st = max(t - lo, 0), en = min(t + hi + 1, len);
;             float acc[8];
; #pragma unroll
;             for (int e = 0; e < 8; ++e) acc[e] = 0.f;
; #pragma unroll
;             for (int i = 0; i < 16; ++i) { const int tt = t + i - 8; const float wt = (tt >= st && tt < en) ? 1.f : 0.f; const u32x4 ww = w[o + i];
;                 acc[0] += wt * bf_lo(ww.x); acc[1] += wt * bf_hi(ww.x); acc[2] += wt * bf_lo(ww.y); acc[3] += wt * bf_hi(ww.y);
;                 acc[4] += wt * bf_lo(ww.z); acc[5] += wt * bf_hi(ww.z); acc[6] += wt * bf_lo(ww.w); acc[7] += wt * bf_hi(ww.w); }
;             const float ic = 1.f / (float)(en - st);
;             const u32x4 sw = w[o + 8];
;             u32x4 ov; ov.x = cvt_pk_bf16(acc[0] * ic - bf_lo(sw.x), acc[1] * ic - bf_hi(sw.x)); ov.y = cvt_pk_bf16(acc[2] * ic - bf_lo(sw.y), acc[3] * ic - bf_hi(sw.y));
;             ov.z = cvt_pk_bf16(acc[4] * ic - bf_lo(sw.z), acc[5] * ic - bf_hi(sw.z)); ov.w = cvt_pk_bf16(acc[6] * ic - bf_lo(sw.w), acc[7] * ic - bf_hi(sw.w));
;             *(u32x4*)(MIX + (size_t)(tok0 + o) * DM + 8 * lane) = ov;
	v_lshlrev_b32_e32 v148, 16, v36
	v_and_b32_e32 v149, 0xffff0000, v36
	v_pk_fma_f32 v[194:195], v[232:233], v[40:41], v[194:195] op_sel_hi:[0,1,1]
	v_lshlrev_b32_e32 v36, 16, v37
	v_and_b32_e32 v37, 0xffff0000, v37
	v_pk_fma_f32 v[150:151], v[230:231], v[78:79], v[150:151] op_sel_hi:[0,1,1]
	v_pk_fma_f32 v[176:177], v[230:231], v[54:55], v[176:177] op_sel_hi:[0,1,1]
	v_div_fixup_f32 v174, v161, v160, 1.0
	v_pk_fma_f32 v[196:197], v[232:233], v[148:149], v[196:197] op_sel_hi:[0,1,1]
	v_pk_fma_f32 v[194:195], v[232:233], v[36:37], v[194:195] op_sel_hi:[0,1,1]
	v_pk_fma_f32 v[150:151], v[232:233], v[108:109], v[150:151] op_sel_hi:[0,1,1]
	v_pk_fma_f32 v[176:177], v[232:233], v[50:51], v[176:177] op_sel_hi:[0,1,1]
	v_pk_fma_f32 v[196:197], v[174:175], v[196:197], v[86:87] op_sel_hi:[0,1,1] neg_lo:[0,0,1] neg_hi:[0,0,1]
	v_pk_fma_f32 v[194:195], v[174:175], v[194:195], v[72:73] op_sel_hi:[0,1,1] neg_lo:[0,0,1] neg_hi:[0,0,1]
	v_pk_fma_f32 v[150:151], v[232:233], v[122:123], v[150:151] op_sel_hi:[0,1,1]
	v_pk_fma_f32 v[176:177], v[232:233], v[46:47], v[176:177] op_sel_hi:[0,1,1]
	v_cvt_pk_bf16_f32 v196, v196, v197
	v_cvt_pk_bf16_f32 v197, v194, v195
	v_pk_fma_f32 v[194:195], v[232:233], v[138:139], v[150:151] op_sel_hi:[0,1,1]
	v_lshlrev_b32_e32 v150, 16, v38
	v_and_b32_e32 v151, 0xffff0000, v38
	v_pk_fma_f32 v[176:177], v[232:233], v[42:43], v[176:177] op_sel_hi:[0,1,1]
	v_lshlrev_b32_e32 v38, 16, v39
	v_and_b32_e32 v39, 0xffff0000, v39
	v_pk_fma_f32 v[194:195], v[232:233], v[150:151], v[194:195] op_sel_hi:[0,1,1]
	v_pk_fma_f32 v[176:177], v[232:233], v[38:39], v[176:177] op_sel_hi:[0,1,1]
	v_sub_u32_e32 v156, s10, v167
	v_add_u32_e32 v160, s10, v167
	v_pk_fma_f32 v[194:195], v[174:175], v[194:195], v[76:77] op_sel_hi:[0,1,1] neg_lo:[0,0,1] neg_hi:[0,0,1]
	v_pk_fma_f32 v[174:175], v[174:175], v[176:177], v[70:71] op_sel_hi:[0,1,1] neg_lo:[0,0,1] neg_hi:[0,0,1]
	v_max_i32_e32 v161, 0, v156
	v_min_i32_e32 v160, s9, v160
	v_cvt_pk_bf16_f32 v199, v174, v175
	v_lshl_add_u64 v[174:175], v[126:127], 0, s[0:1]
	v_cvt_pk_bf16_f32 v198, v194, v195
	global_store_dwordx4 v[174:175], v[196:199], off
	v_pk_fma_f32 v[146:147], v[232:233], v[146:147], 0 op_sel_hi:[0,1,0]
	v_pk_fma_f32 v[144:145], v[232:233], v[144:145], 0 op_sel_hi:[0,1,0]
	v_pk_fma_f32 v[142:143], v[232:233], v[142:143], 0 op_sel_hi:[0,1,0]
	v_pk_fma_f32 v[140:141], v[232:233], v[140:141], 0 op_sel_hi:[0,1,0]
	v_pk_fma_f32 v[146:147], v[232:233], v[152:153], v[146:147] op_sel_hi:[0,1,1]
	v_pk_fma_f32 v[144:145], v[232:233], v[154:155], v[144:145] op_sel_hi:[0,1,1]
	v_pk_fma_f32 v[142:143], v[232:233], v[170:171], v[142:143] op_sel_hi:[0,1,1]
	v_pk_fma_f32 v[140:141], v[232:233], v[172:173], v[140:141] op_sel_hi:[0,1,1]
	v_pk_fma_f32 v[146:147], v[232:233], v[132:133], v[146:147] op_sel_hi:[0,1,1]
	v_pk_fma_f32 v[144:145], v[232:233], v[130:131], v[144:145] op_sel_hi:[0,1,1]
	v_pk_fma_f32 v[142:143], v[232:233], v[128:129], v[142:143] op_sel_hi:[0,1,1]
	v_pk_fma_f32 v[140:141], v[232:233], v[118:119], v[140:141] op_sel_hi:[0,1,1]
	v_pk_fma_f32 v[146:147], v[232:233], v[104:105], v[146:147] op_sel_hi:[0,1,1]
	v_pk_fma_f32 v[144:145], v[232:233], v[102:103], v[144:145] op_sel_hi:[0,1,1]
	v_pk_fma_f32 v[142:143], v[232:233], v[100:101], v[142:143] op_sel_hi:[0,1,1]
	v_pk_fma_f32 v[140:141], v[232:233], v[98:99], v[140:141] op_sel_hi:[0,1,1]
	v_pk_fma_f32 v[146:147], v[230:231], v[112:113], v[146:147] op_sel_hi:[0,1,1]
	v_pk_fma_f32 v[144:145], v[230:231], v[114:115], v[144:145] op_sel_hi:[0,1,1]
	v_pk_fma_f32 v[142:143], v[230:231], v[116:117], v[142:143] op_sel_hi:[0,1,1]
	v_pk_fma_f32 v[140:141], v[230:231], v[134:135], v[140:141] op_sel_hi:[0,1,1]
	v_pk_fma_f32 v[146:147], v[230:231], v[92:93], v[146:147] op_sel_hi:[0,1,1]
	v_pk_fma_f32 v[144:145], v[230:231], v[94:95], v[144:145] op_sel_hi:[0,1,1]
	v_pk_fma_f32 v[142:143], v[230:231], v[96:97], v[142:143] op_sel_hi:[0,1,1]
	v_pk_fma_f32 v[140:141], v[230:231], v[110:111], v[140:141] op_sel_hi:[0,1,1]
	v_pk_fma_f32 v[196:197], v[228:229], v[88:89], v[146:147] op_sel_hi:[0,1,1]
	v_pk_fma_f32 v[194:195], v[228:229], v[80:81], v[144:145] op_sel_hi:[0,1,1]
	v_pk_fma_f32 v[192:193], v[228:229], v[90:91], v[142:143] op_sel_hi:[0,1,1]
	v_pk_fma_f32 v[174:175], v[228:229], v[82:83], v[140:141] op_sel_hi:[0,1,1]
	v_sub_u32_e32 v140, v160, v161
	v_cvt_f32_i32_e32 v140, v140
	s_nop 0
	v_div_scale_f32 v141, s[0:1], v140, v140, 1.0
	v_rcp_f32_e32 v142, v141
	s_or_b32 s0, s4, 7
	s_ashr_i32 s1, s0, 31
	s_lshl_b64 s[0:1], s[0:1], 11
	v_fma_f32 v143, -v141, v142, 1.0
	v_fmac_f32_e32 v142, v143, v142
	v_div_scale_f32 v143, vcc, 1.0, v140, 1.0
	v_mul_f32_e32 v144, v143, v142
	v_fma_f32 v145, -v141, v144, v143
	v_fmac_f32_e32 v144, v145, v142
	v_fma_f32 v141, -v141, v144, v143
	v_div_fmas_f32 v141, v141, v142, v144
	v_div_fixup_f32 v156, v141, v140, 1.0
	v_pk_fma_f32 v[140:141], v[234:235], v[86:87], v[196:197] op_sel_hi:[0,1,1]
	v_pk_fma_f32 v[140:141], v[234:235], v[84:85], v[140:141] op_sel_hi:[0,1,1]
	v_pk_fma_f32 v[140:141], v[228:229], v[60:61], v[140:141] op_sel_hi:[0,1,1]
	v_pk_fma_f32 v[140:141], v[230:231], v[74:75], v[140:141] op_sel_hi:[0,1,1]
	v_pk_fma_f32 v[140:141], v[230:231], v[106:107], v[140:141] op_sel_hi:[0,1,1]
	v_pk_fma_f32 v[140:141], v[232:233], v[120:121], v[140:141] op_sel_hi:[0,1,1]
	v_pk_fma_f32 v[140:141], v[232:233], v[136:137], v[140:141] op_sel_hi:[0,1,1]
	v_pk_fma_f32 v[140:141], v[232:233], v[148:149], v[140:141] op_sel_hi:[0,1,1]
	s_waitcnt vmcnt(15)
; __device__ __forceinline__ unsigned cvt_pk_bf16(float lo, float hi) { const f32x2 v = (f32x2){lo, hi}; return __builtin_bit_cast(unsigned, __builtin_convertvector(v, bf16v2)); }
; __device__ __forceinline__ float bf_lo(unsigned w) { return __uint_as_float(w << 16); }
; __device__ __forceinline__ float bf_hi(unsigned w) { return __uint_as_float(w & 0xffff0000u); }
; __device__ __forceinline__ void phase_mixer(const Params& p, LAS unsigned char* lds, int l, bool with_ctx, int G, int tid, int wave, int lane, int rep_attn, int rep_pool) {
;     ...
;         for (int o = 0; o < 16; ++o) {
;             const int t = t0 + o, st = max(t - lo, 0), en = min(t + hi + 1, len);
;             float acc[8];
; #pragma unroll
;             for (int e = 0; e < 8; ++e) acc[e] = 0.f;
; #pragma unroll
;             for (int i = 0; i < 16; ++i) { const int tt = t + i - 8; const float wt = (tt >= st && tt < en) ? 1.f : 0.f; const u32x4 ww = w[o + i];
;                 acc[0] += wt * bf_lo(ww.x); acc[1] += wt * bf_hi(ww.x); acc[2] += wt * bf_lo(ww.y); acc[3] += wt * bf_hi(ww.y);
;                 acc[4] += wt * bf_lo(ww.z); acc[5] += wt * bf_hi(ww.z); acc[6] += wt * bf_lo(ww.w); acc[7] += wt * bf_hi(ww.w); }
;             const float ic = 1.f / (float)(en - st);
;             const u32x4 sw = w[o + 8];
;             u32x4 ov; ov.x = cvt_pk_bf16(acc[0] * ic - bf_lo(sw.x), acc[1] * ic - bf_hi(sw.x)); ov.y = cvt_pk_bf16(acc[2] * ic - bf_lo(sw.y), acc[3] * ic - bf_hi(sw.y));
;             ov.z = cvt_pk_bf16(acc[4] * ic - bf_lo(sw.z), acc[5] * ic - bf_hi(sw.z)); ov.w = cvt_pk_bf16(acc[6] * ic - bf_lo(sw.w), acc[7] * ic - bf_hi(sw.w));
;             *(u32x4*)(MIX + (size_t)(tok0 + o) * DM + 8 * lane) = ov;
	v_lshlrev_b32_e32 v144, 16, v32
	v_and_b32_e32 v145, 0xffff0000, v32
	v_pk_fma_f32 v[140:141], v[232:233], v[144:145], v[140:141] op_sel_hi:[0,1,1]
	v_pk_fma_f32 v[140:141], v[156:157], v[140:141], v[84:85] op_sel_hi:[0,1,1] neg_lo:[0,0,1] neg_hi:[0,0,1]
	v_cvt_pk_bf16_f32 v196, v140, v141
	v_pk_fma_f32 v[140:141], v[234:235], v[72:73], v[194:195] op_sel_hi:[0,1,1]
	v_pk_fma_f32 v[140:141], v[234:235], v[64:65], v[140:141] op_sel_hi:[0,1,1]
	v_pk_fma_f32 v[140:141], v[228:229], v[56:57], v[140:141] op_sel_hi:[0,1,1]
	v_pk_fma_f32 v[140:141], v[230:231], v[52:53], v[140:141] op_sel_hi:[0,1,1]
	v_pk_fma_f32 v[140:141], v[230:231], v[48:49], v[140:141] op_sel_hi:[0,1,1]
	v_pk_fma_f32 v[140:141], v[232:233], v[44:45], v[140:141] op_sel_hi:[0,1,1]
	v_pk_fma_f32 v[140:141], v[232:233], v[40:41], v[140:141] op_sel_hi:[0,1,1]
	v_pk_fma_f32 v[140:141], v[232:233], v[36:37], v[140:141] op_sel_hi:[0,1,1]
	v_lshlrev_b32_e32 v142, 16, v33
	v_and_b32_e32 v143, 0xffff0000, v33
	v_pk_fma_f32 v[32:33], v[232:233], v[142:143], v[140:141] op_sel_hi:[0,1,1]
	v_pk_fma_f32 v[32:33], v[156:157], v[32:33], v[64:65] op_sel_hi:[0,1,1] neg_lo:[0,0,1] neg_hi:[0,0,1]
	v_cvt_pk_bf16_f32 v197, v32, v33
	v_pk_fma_f32 v[32:33], v[234:235], v[76:77], v[192:193] op_sel_hi:[0,1,1]
	v_pk_fma_f32 v[32:33], v[234:235], v[68:69], v[32:33] op_sel_hi:[0,1,1]
	v_pk_fma_f32 v[32:33], v[228:229], v[62:63], v[32:33] op_sel_hi:[0,1,1]
	v_pk_fma_f32 v[32:33], v[230:231], v[78:79], v[32:33] op_sel_hi:[0,1,1]
	v_pk_fma_f32 v[32:33], v[230:231], v[108:109], v[32:33] op_sel_hi:[0,1,1]
	v_pk_fma_f32 v[32:33], v[232:233], v[122:123], v[32:33] op_sel_hi:[0,1,1]
	v_pk_fma_f32 v[32:33], v[232:233], v[138:139], v[32:33] op_sel_hi:[0,1,1]
	v_pk_fma_f32 v[32:33], v[232:233], v[150:151], v[32:33] op_sel_hi:[0,1,1]
	v_lshlrev_b32_e32 v140, 16, v34
	v_and_b32_e32 v141, 0xffff0000, v34
	v_pk_fma_f32 v[32:33], v[232:233], v[140:141], v[32:33] op_sel_hi:[0,1,1]
	v_pk_fma_f32 v[32:33], v[156:157], v[32:33], v[68:69] op_sel_hi:[0,1,1] neg_lo:[0,0,1] neg_hi:[0,0,1]
	v_cvt_pk_bf16_f32 v198, v32, v33
	v_pk_fma_f32 v[32:33], v[234:235], v[70:71], v[174:175] op_sel_hi:[0,1,1]
	v_pk_fma_f32 v[32:33], v[234:235], v[66:67], v[32:33] op_sel_hi:[0,1,1]
	v_pk_fma_f32 v[32:33], v[228:229], v[58:59], v[32:33] op_sel_hi:[0,1,1]
	v_pk_fma_f32 v[32:33], v[230:231], v[54:55], v[32:33] op_sel_hi:[0,1,1]
	v_pk_fma_f32 v[32:33], v[230:231], v[50:51], v[32:33] op_sel_hi:[0,1,1]
	v_pk_fma_f32 v[32:33], v[232:233], v[46:47], v[32:33] op_sel_hi:[0,1,1]
	v_pk_fma_f32 v[32:33], v[232:233], v[42:43], v[32:33] op_sel_hi:[0,1,1]
	v_pk_fma_f32 v[174:175], v[232:233], v[38:39], v[32:33] op_sel_hi:[0,1,1]
	v_lshlrev_b32_e32 v32, 16, v35
	v_and_b32_e32 v33, 0xffff0000, v35
	v_pk_fma_f32 v[34:35], v[232:233], v[32:33], v[174:175] op_sel_hi:[0,1,1]
	v_pk_fma_f32 v[34:35], v[156:157], v[34:35], v[66:67] op_sel_hi:[0,1,1] neg_lo:[0,0,1] neg_hi:[0,0,1]
	v_cvt_pk_bf16_f32 v199, v34, v35
	v_lshl_add_u64 v[34:35], v[126:127], 0, s[0:1]
	global_store_dwordx4 v[34:35], v[196:199], off
	v_sub_u32_e32 v34, s11, v167
	v_add_u32_e32 v35, s11, v167
	v_max_i32_e32 v160, 0, v34
	v_min_i32_e32 v161, s9, v35
	v_pk_fma_f32 v[34:35], v[232:233], v[152:153], 0 op_sel_hi:[0,1,0]
	v_pk_fma_f32 v[34:35], v[232:233], v[132:133], v[34:35] op_sel_hi:[0,1,1]
	v_pk_fma_f32 v[34:35], v[232:233], v[104:105], v[34:35] op_sel_hi:[0,1,1]
	v_pk_fma_f32 v[34:35], v[232:233], v[112:113], v[34:35] op_sel_hi:[0,1,1]
	v_pk_fma_f32 v[34:35], v[230:231], v[92:93], v[34:35] op_sel_hi:[0,1,1]
	v_pk_fma_f32 v[34:35], v[230:231], v[88:89], v[34:35] op_sel_hi:[0,1,1]
	v_pk_fma_f32 v[152:153], v[228:229], v[86:87], v[34:35] op_sel_hi:[0,1,1]
	v_pk_fma_f32 v[34:35], v[232:233], v[154:155], 0 op_sel_hi:[0,1,0]
	v_pk_fma_f32 v[34:35], v[232:233], v[130:131], v[34:35] op_sel_hi:[0,1,1]
	v_pk_fma_f32 v[34:35], v[232:233], v[102:103], v[34:35] op_sel_hi:[0,1,1]
	v_pk_fma_f32 v[34:35], v[232:233], v[114:115], v[34:35] op_sel_hi:[0,1,1]
	v_pk_fma_f32 v[34:35], v[230:231], v[94:95], v[34:35] op_sel_hi:[0,1,1]
	v_pk_fma_f32 v[34:35], v[230:231], v[80:81], v[34:35] op_sel_hi:[0,1,1]
	v_pk_fma_f32 v[154:155], v[232:233], v[172:173], 0 op_sel_hi:[0,1,0]
	v_pk_fma_f32 v[146:147], v[228:229], v[72:73], v[34:35] op_sel_hi:[0,1,1]
	v_pk_fma_f32 v[34:35], v[232:233], v[170:171], 0 op_sel_hi:[0,1,0]
	v_pk_fma_f32 v[34:35], v[232:233], v[128:129], v[34:35] op_sel_hi:[0,1,1]
	v_pk_fma_f32 v[154:155], v[232:233], v[118:119], v[154:155] op_sel_hi:[0,1,1]
	v_pk_fma_f32 v[34:35], v[232:233], v[100:101], v[34:35] op_sel_hi:[0,1,1]
	v_pk_fma_f32 v[154:155], v[232:233], v[98:99], v[154:155] op_sel_hi:[0,1,1]
	v_pk_fma_f32 v[34:35], v[232:233], v[116:117], v[34:35] op_sel_hi:[0,1,1]
	v_pk_fma_f32 v[154:155], v[232:233], v[134:135], v[154:155] op_sel_hi:[0,1,1]
	v_pk_fma_f32 v[34:35], v[230:231], v[96:97], v[34:35] op_sel_hi:[0,1,1]
	v_pk_fma_f32 v[154:155], v[230:231], v[110:111], v[154:155] op_sel_hi:[0,1,1]
	v_pk_fma_f32 v[34:35], v[230:231], v[90:91], v[34:35] op_sel_hi:[0,1,1]
	v_pk_fma_f32 v[154:155], v[230:231], v[82:83], v[154:155] op_sel_hi:[0,1,1]
	v_pk_fma_f32 v[170:171], v[228:229], v[70:71], v[154:155] op_sel_hi:[0,1,1]
	v_sub_u32_e32 v155, v161, v160
	v_pk_fma_f32 v[34:35], v[228:229], v[76:77], v[34:35] op_sel_hi:[0,1,1]
	v_cvt_f32_i32_e32 v155, v155
	s_nop 0
	v_div_scale_f32 v156, s[0:1], v155, v155, 1.0
	v_rcp_f32_e32 v160, v156
	s_or_b32 s0, s4, 8
	s_ashr_i32 s1, s0, 31
	s_lshl_b64 s[0:1], s[0:1], 11
	v_fma_f32 v161, -v156, v160, 1.0
	v_fmac_f32_e32 v160, v161, v160
	v_div_scale_f32 v161, vcc, 1.0, v155, 1.0
	v_mul_f32_e32 v173, v161, v160
	v_fma_f32 v175, -v156, v173, v161
	v_fmac_f32_e32 v173, v175, v160
	v_pk_fma_f32 v[152:153], v[234:235], v[84:85], v[152:153] op_sel_hi:[0,1,1]
	v_pk_fma_f32 v[146:147], v[234:235], v[64:65], v[146:147] op_sel_hi:[0,1,1]
	v_pk_fma_f32 v[152:153], v[234:235], v[60:61], v[152:153] op_sel_hi:[0,1,1]
	v_pk_fma_f32 v[146:147], v[234:235], v[56:57], v[146:147] op_sel_hi:[0,1,1]
	v_pk_fma_f32 v[152:153], v[228:229], v[74:75], v[152:153] op_sel_hi:[0,1,1]
	v_pk_fma_f32 v[146:147], v[228:229], v[52:53], v[146:147] op_sel_hi:[0,1,1]
	v_pk_fma_f32 v[152:153], v[230:231], v[106:107], v[152:153] op_sel_hi:[0,1,1]
	v_pk_fma_f32 v[146:147], v[230:231], v[48:49], v[146:147] op_sel_hi:[0,1,1]
	v_pk_fma_f32 v[152:153], v[230:231], v[120:121], v[152:153] op_sel_hi:[0,1,1]
	v_pk_fma_f32 v[146:147], v[230:231], v[44:45], v[146:147] op_sel_hi:[0,1,1]
	v_pk_fma_f32 v[152:153], v[232:233], v[136:137], v[152:153] op_sel_hi:[0,1,1]
	v_pk_fma_f32 v[146:147], v[232:233], v[40:41], v[146:147] op_sel_hi:[0,1,1]
	v_fma_f32 v156, -v156, v173, v161
	v_pk_fma_f32 v[152:153], v[232:233], v[148:149], v[152:153] op_sel_hi:[0,1,1]
	v_pk_fma_f32 v[146:147], v[232:233], v[36:37], v[146:147] op_sel_hi:[0,1,1]
	v_div_fmas_f32 v156, v156, v160, v173
	v_pk_fma_f32 v[188:189], v[232:233], v[144:145], v[152:153] op_sel_hi:[0,1,1]
	s_waitcnt vmcnt(15)
; __device__ __forceinline__ unsigned cvt_pk_bf16(float lo, float hi) { const f32x2 v = (f32x2){lo, hi}; return __builtin_bit_cast(unsigned, __builtin_convertvector(v, bf16v2)); }
; __device__ __forceinline__ float bf_lo(unsigned w) { return __uint_as_float(w << 16); }
; __device__ __forceinline__ float bf_hi(unsigned w) { return __uint_as_float(w & 0xffff0000u); }
; __device__ __forceinline__ void phase_mixer(const Params& p, LAS unsigned char* lds, int l, bool with_ctx, int G, int tid, int wave, int lane, int rep_attn, int rep_pool) {
;     ...
;         for (int o = 0; o < 16; ++o) {
;             const int t = t0 + o, st = max(t - lo, 0), en = min(t + hi + 1, len);
;             float acc[8];
; #pragma unroll
;             for (int e = 0; e < 8; ++e) acc[e] = 0.f;
; #pragma unroll
;             for (int i = 0; i < 16; ++i) { const int tt = t + i - 8; const float wt = (tt >= st && tt < en) ? 1.f : 0.f; const u32x4 ww = w[o + i];
;                 acc[0] += wt * bf_lo(ww.x); acc[1] += wt * bf_hi(ww.x); acc[2] += wt * bf_lo(ww.y); acc[3] += wt * bf_hi(ww.y);
;                 acc[4] += wt * bf_lo(ww.z); acc[5] += wt * bf_hi(ww.z); acc[6] += wt * bf_lo(ww.w); acc[7] += wt * bf_hi(ww.w); }
;             const float ic = 1.f / (float)(en - st);
;             const u32x4 sw = w[o + 8];
;             u32x4 ov; ov.x = cvt_pk_bf16(acc[0] * ic - bf_lo(sw.x), acc[1] * ic - bf_hi(sw.x)); ov.y = cvt_pk_bf16(acc[2] * ic - bf_lo(sw.y), acc[3] * ic - bf_hi(sw.y));
;             ov.z = cvt_pk_bf16(acc[4] * ic - bf_lo(sw.z), acc[5] * ic - bf_hi(sw.z)); ov.w = cvt_pk_bf16(acc[6] * ic - bf_lo(sw.w), acc[7] * ic - bf_hi(sw.w));
;             *(u32x4*)(MIX + (size_t)(tok0 + o) * DM + 8 * lane) = ov;
	v_lshlrev_b32_e32 v152, 16, v28
	v_and_b32_e32 v153, 0xffff0000, v28
	v_pk_fma_f32 v[190:191], v[232:233], v[142:143], v[146:147] op_sel_hi:[0,1,1]
	v_lshlrev_b32_e32 v146, 16, v29
	v_and_b32_e32 v147, 0xffff0000, v29
	v_div_fixup_f32 v156, v156, v155, 1.0
	v_pk_fma_f32 v[188:189], v[232:233], v[152:153], v[188:189] op_sel_hi:[0,1,1]
	v_pk_fma_f32 v[28:29], v[232:233], v[146:147], v[190:191] op_sel_hi:[0,1,1]
	v_pk_fma_f32 v[188:189], v[156:157], v[188:189], v[60:61] op_sel_hi:[0,1,1] neg_lo:[0,0,1] neg_hi:[0,0,1]
	v_pk_fma_f32 v[28:29], v[156:157], v[28:29], v[56:57] op_sel_hi:[0,1,1] neg_lo:[0,0,1] neg_hi:[0,0,1]
	v_cvt_pk_bf16_f32 v188, v188, v189
	v_cvt_pk_bf16_f32 v189, v28, v29
	v_pk_fma_f32 v[28:29], v[234:235], v[68:69], v[34:35] op_sel_hi:[0,1,1]
	v_pk_fma_f32 v[28:29], v[234:235], v[62:63], v[28:29] op_sel_hi:[0,1,1]
	v_pk_fma_f32 v[28:29], v[228:229], v[78:79], v[28:29] op_sel_hi:[0,1,1]
	v_pk_fma_f32 v[28:29], v[230:231], v[108:109], v[28:29] op_sel_hi:[0,1,1]
	v_pk_fma_f32 v[28:29], v[230:231], v[122:123], v[28:29] op_sel_hi:[0,1,1]
	v_pk_fma_f32 v[28:29], v[232:233], v[138:139], v[28:29] op_sel_hi:[0,1,1]
	v_pk_fma_f32 v[28:29], v[232:233], v[150:151], v[28:29] op_sel_hi:[0,1,1]
	v_pk_fma_f32 v[28:29], v[232:233], v[140:141], v[28:29] op_sel_hi:[0,1,1]
	v_lshlrev_b32_e32 v34, 16, v30
	v_and_b32_e32 v35, 0xffff0000, v30
	v_pk_fma_f32 v[28:29], v[232:233], v[34:35], v[28:29] op_sel_hi:[0,1,1]
	v_pk_fma_f32 v[28:29], v[156:157], v[28:29], v[62:63] op_sel_hi:[0,1,1] neg_lo:[0,0,1] neg_hi:[0,0,1]
	v_cvt_pk_bf16_f32 v190, v28, v29
	v_pk_fma_f32 v[28:29], v[234:235], v[66:67], v[170:171] op_sel_hi:[0,1,1]
	v_pk_fma_f32 v[28:29], v[234:235], v[58:59], v[28:29] op_sel_hi:[0,1,1]
	v_pk_fma_f32 v[28:29], v[228:229], v[54:55], v[28:29] op_sel_hi:[0,1,1]
	v_pk_fma_f32 v[28:29], v[230:231], v[50:51], v[28:29] op_sel_hi:[0,1,1]
	v_pk_fma_f32 v[28:29], v[230:231], v[46:47], v[28:29] op_sel_hi:[0,1,1]
	v_pk_fma_f32 v[28:29], v[232:233], v[42:43], v[28:29] op_sel_hi:[0,1,1]
	v_pk_fma_f32 v[28:29], v[232:233], v[38:39], v[28:29] op_sel_hi:[0,1,1]
	v_pk_fma_f32 v[170:171], v[232:233], v[32:33], v[28:29] op_sel_hi:[0,1,1]
	v_lshlrev_b32_e32 v28, 16, v31
	v_and_b32_e32 v29, 0xffff0000, v31
	v_pk_fma_f32 v[30:31], v[232:233], v[28:29], v[170:171] op_sel_hi:[0,1,1]
	v_pk_fma_f32 v[30:31], v[156:157], v[30:31], v[58:59] op_sel_hi:[0,1,1] neg_lo:[0,0,1] neg_hi:[0,0,1]
	v_cvt_pk_bf16_f32 v191, v30, v31
	v_lshl_add_u64 v[30:31], v[126:127], 0, s[0:1]
	global_store_dwordx4 v[30:31], v[188:191], off
	v_sub_u32_e32 v30, s12, v167
	v_add_u32_e32 v31, s12, v167
	v_max_i32_e32 v160, 0, v30
	v_min_i32_e32 v161, s9, v31
	v_pk_fma_f32 v[30:31], v[232:233], v[132:133], 0 op_sel_hi:[0,1,0]
	v_pk_fma_f32 v[30:31], v[232:233], v[104:105], v[30:31] op_sel_hi:[0,1,1]
	v_pk_fma_f32 v[30:31], v[232:233], v[112:113], v[30:31] op_sel_hi:[0,1,1]
	v_pk_fma_f32 v[30:31], v[232:233], v[92:93], v[30:31] op_sel_hi:[0,1,1]
	v_pk_fma_f32 v[30:31], v[230:231], v[88:89], v[30:31] op_sel_hi:[0,1,1]
	v_pk_fma_f32 v[30:31], v[230:231], v[86:87], v[30:31] op_sel_hi:[0,1,1]
	v_pk_fma_f32 v[186:187], v[228:229], v[84:85], v[30:31] op_sel_hi:[0,1,1]
	v_pk_fma_f32 v[30:31], v[232:233], v[130:131], 0 op_sel_hi:[0,1,0]
	v_pk_fma_f32 v[30:31], v[232:233], v[102:103], v[30:31] op_sel_hi:[0,1,1]
	v_pk_fma_f32 v[30:31], v[232:233], v[114:115], v[30:31] op_sel_hi:[0,1,1]
	v_pk_fma_f32 v[30:31], v[232:233], v[94:95], v[30:31] op_sel_hi:[0,1,1]
	v_pk_fma_f32 v[30:31], v[230:231], v[80:81], v[30:31] op_sel_hi:[0,1,1]
	v_pk_fma_f32 v[30:31], v[230:231], v[72:73], v[30:31] op_sel_hi:[0,1,1]
	v_pk_fma_f32 v[184:185], v[228:229], v[64:65], v[30:31] op_sel_hi:[0,1,1]
	v_pk_fma_f32 v[30:31], v[232:233], v[128:129], 0 op_sel_hi:[0,1,0]
	v_pk_fma_f32 v[118:119], v[232:233], v[118:119], 0 op_sel_hi:[0,1,0]
	v_pk_fma_f32 v[30:31], v[232:233], v[100:101], v[30:31] op_sel_hi:[0,1,1]
	v_pk_fma_f32 v[118:119], v[232:233], v[98:99], v[118:119] op_sel_hi:[0,1,1]
	v_pk_fma_f32 v[30:31], v[232:233], v[116:117], v[30:31] op_sel_hi:[0,1,1]
	v_pk_fma_f32 v[118:119], v[232:233], v[134:135], v[118:119] op_sel_hi:[0,1,1]
	v_pk_fma_f32 v[30:31], v[232:233], v[96:97], v[30:31] op_sel_hi:[0,1,1]
	v_pk_fma_f32 v[118:119], v[232:233], v[110:111], v[118:119] op_sel_hi:[0,1,1]
	v_pk_fma_f32 v[30:31], v[230:231], v[90:91], v[30:31] op_sel_hi:[0,1,1]
	v_pk_fma_f32 v[118:119], v[230:231], v[82:83], v[118:119] op_sel_hi:[0,1,1]
	v_pk_fma_f32 v[30:31], v[230:231], v[76:77], v[30:31] op_sel_hi:[0,1,1]
	v_pk_fma_f32 v[118:119], v[230:231], v[70:71], v[118:119] op_sel_hi:[0,1,1]
	v_pk_fma_f32 v[30:31], v[228:229], v[68:69], v[30:31] op_sel_hi:[0,1,1]
	v_pk_fma_f32 v[154:155], v[228:229], v[66:67], v[118:119] op_sel_hi:[0,1,1]
	v_sub_u32_e32 v118, v161, v160
	v_cvt_f32_i32_e32 v118, v118
	s_nop 0
	v_div_scale_f32 v119, s[0:1], v118, v118, 1.0
	v_rcp_f32_e32 v128, v119
	s_or_b32 s0, s4, 9
	s_ashr_i32 s1, s0, 31
	s_lshl_b64 s[0:1], s[0:1], 11
	v_fma_f32 v129, -v119, v128, 1.0
	v_fmac_f32_e32 v128, v129, v128
	v_div_scale_f32 v129, vcc, 1.0, v118, 1.0
	v_mul_f32_e32 v131, v129, v128
	v_fma_f32 v132, -v119, v131, v129
	v_fmac_f32_e32 v131, v132, v128
	v_fma_f32 v119, -v119, v131, v129
	v_div_fmas_f32 v119, v119, v128, v131
	v_div_fixup_f32 v132, v119, v118, 1.0
	v_pk_fma_f32 v[118:119], v[234:235], v[60:61], v[186:187] op_sel_hi:[0,1,1]
	v_pk_fma_f32 v[118:119], v[234:235], v[74:75], v[118:119] op_sel_hi:[0,1,1]
	v_pk_fma_f32 v[118:119], v[228:229], v[106:107], v[118:119] op_sel_hi:[0,1,1]
	v_pk_fma_f32 v[118:119], v[230:231], v[120:121], v[118:119] op_sel_hi:[0,1,1]
	v_pk_fma_f32 v[118:119], v[230:231], v[136:137], v[118:119] op_sel_hi:[0,1,1]
	v_pk_fma_f32 v[118:119], v[232:233], v[148:149], v[118:119] op_sel_hi:[0,1,1]
	v_pk_fma_f32 v[118:119], v[232:233], v[144:145], v[118:119] op_sel_hi:[0,1,1]
	v_pk_fma_f32 v[118:119], v[232:233], v[152:153], v[118:119] op_sel_hi:[0,1,1]
	s_waitcnt vmcnt(15)
; __device__ __forceinline__ unsigned cvt_pk_bf16(float lo, float hi) { const f32x2 v = (f32x2){lo, hi}; return __builtin_bit_cast(unsigned, __builtin_convertvector(v, bf16v2)); }
; __device__ __forceinline__ float bf_lo(unsigned w) { return __uint_as_float(w << 16); }
; __device__ __forceinline__ float bf_hi(unsigned w) { return __uint_as_float(w & 0xffff0000u); }
; __device__ __forceinline__ void phase_mixer(const Params& p, LAS unsigned char* lds, int l, bool with_ctx, int G, int tid, int wave, int lane, int rep_attn, int rep_pool) {
;     ...
;         for (int o = 0; o < 16; ++o) {
;             const int t = t0 + o, st = max(t - lo, 0), en = min(t + hi + 1, len);
;             float acc[8];
; #pragma unroll
;             for (int e = 0; e < 8; ++e) acc[e] = 0.f;
; #pragma unroll
;             for (int i = 0; i < 16; ++i) { const int tt = t + i - 8; const float wt = (tt >= st && tt < en) ? 1.f : 0.f; const u32x4 ww = w[o + i];
;                 acc[0] += wt * bf_lo(ww.x); acc[1] += wt * bf_hi(ww.x); acc[2] += wt * bf_lo(ww.y); acc[3] += wt * bf_hi(ww.y);
;                 acc[4] += wt * bf_lo(ww.z); acc[5] += wt * bf_hi(ww.z); acc[6] += wt * bf_lo(ww.w); acc[7] += wt * bf_hi(ww.w); }
;             const float ic = 1.f / (float)(en - st);
;             const u32x4 sw = w[o + 8];
;             u32x4 ov; ov.x = cvt_pk_bf16(acc[0] * ic - bf_lo(sw.x), acc[1] * ic - bf_hi(sw.x)); ov.y = cvt_pk_bf16(acc[2] * ic - bf_lo(sw.y), acc[3] * ic - bf_hi(sw.y));
;             ov.z = cvt_pk_bf16(acc[4] * ic - bf_lo(sw.z), acc[5] * ic - bf_hi(sw.z)); ov.w = cvt_pk_bf16(acc[6] * ic - bf_lo(sw.w), acc[7] * ic - bf_hi(sw.w));
;             *(u32x4*)(MIX + (size_t)(tok0 + o) * DM + 8 * lane) = ov;
	v_and_b32_e32 v24, v242, v24
	v_and_b32_e32 v25, v242, v25
	v_and_b32_e32 v26, v242, v26
	v_and_b32_e32 v27, v242, v27
	v_lshlrev_b32_e32 v128, 16, v24
	v_and_b32_e32 v129, 0xffff0000, v24
	v_pk_fma_f32 v[118:119], v[232:233], v[128:129], v[118:119] op_sel_hi:[0,1,1]
	v_pk_fma_f32 v[118:119], v[132:133], v[118:119], v[74:75] op_sel_hi:[0,1,1] neg_lo:[0,0,1] neg_hi:[0,0,1]
	v_cvt_pk_bf16_f32 v186, v118, v119
	v_pk_fma_f32 v[118:119], v[234:235], v[56:57], v[184:185] op_sel_hi:[0,1,1]
	v_pk_fma_f32 v[118:119], v[234:235], v[52:53], v[118:119] op_sel_hi:[0,1,1]
	v_pk_fma_f32 v[118:119], v[228:229], v[48:49], v[118:119] op_sel_hi:[0,1,1]
	v_pk_fma_f32 v[118:119], v[230:231], v[44:45], v[118:119] op_sel_hi:[0,1,1]
	v_pk_fma_f32 v[118:119], v[230:231], v[40:41], v[118:119] op_sel_hi:[0,1,1]
	v_pk_fma_f32 v[118:119], v[232:233], v[36:37], v[118:119] op_sel_hi:[0,1,1]
	v_pk_fma_f32 v[118:119], v[232:233], v[142:143], v[118:119] op_sel_hi:[0,1,1]
	v_pk_fma_f32 v[184:185], v[232:233], v[146:147], v[118:119] op_sel_hi:[0,1,1]
	v_lshlrev_b32_e32 v118, 16, v25
	v_and_b32_e32 v119, 0xffff0000, v25
	v_pk_fma_f32 v[24:25], v[232:233], v[118:119], v[184:185] op_sel_hi:[0,1,1]
	v_pk_fma_f32 v[24:25], v[132:133], v[24:25], v[52:53] op_sel_hi:[0,1,1] neg_lo:[0,0,1] neg_hi:[0,0,1]
	v_cvt_pk_bf16_f32 v187, v24, v25
	v_pk_fma_f32 v[24:25], v[234:235], v[62:63], v[30:31] op_sel_hi:[0,1,1]
	v_pk_fma_f32 v[24:25], v[234:235], v[78:79], v[24:25] op_sel_hi:[0,1,1]
	v_pk_fma_f32 v[24:25], v[228:229], v[108:109], v[24:25] op_sel_hi:[0,1,1]
	v_pk_fma_f32 v[24:25], v[230:231], v[122:123], v[24:25] op_sel_hi:[0,1,1]
	v_pk_fma_f32 v[24:25], v[230:231], v[138:139], v[24:25] op_sel_hi:[0,1,1]
	v_pk_fma_f32 v[24:25], v[232:233], v[150:151], v[24:25] op_sel_hi:[0,1,1]
	v_pk_fma_f32 v[24:25], v[232:233], v[140:141], v[24:25] op_sel_hi:[0,1,1]
	v_pk_fma_f32 v[24:25], v[232:233], v[34:35], v[24:25] op_sel_hi:[0,1,1]
	v_lshlrev_b32_e32 v30, 16, v26
	v_and_b32_e32 v31, 0xffff0000, v26
	v_pk_fma_f32 v[24:25], v[232:233], v[30:31], v[24:25] op_sel_hi:[0,1,1]
	v_pk_fma_f32 v[24:25], v[132:133], v[24:25], v[78:79] op_sel_hi:[0,1,1] neg_lo:[0,0,1] neg_hi:[0,0,1]
	v_cvt_pk_bf16_f32 v188, v24, v25
	v_pk_fma_f32 v[24:25], v[234:235], v[58:59], v[154:155] op_sel_hi:[0,1,1]
	v_pk_fma_f32 v[24:25], v[234:235], v[54:55], v[24:25] op_sel_hi:[0,1,1]
	v_pk_fma_f32 v[24:25], v[228:229], v[50:51], v[24:25] op_sel_hi:[0,1,1]
	v_pk_fma_f32 v[24:25], v[230:231], v[46:47], v[24:25] op_sel_hi:[0,1,1]
	v_pk_fma_f32 v[24:25], v[230:231], v[42:43], v[24:25] op_sel_hi:[0,1,1]
	v_pk_fma_f32 v[24:25], v[232:233], v[38:39], v[24:25] op_sel_hi:[0,1,1]
	v_pk_fma_f32 v[24:25], v[232:233], v[32:33], v[24:25] op_sel_hi:[0,1,1]
	v_pk_fma_f32 v[154:155], v[232:233], v[28:29], v[24:25] op_sel_hi:[0,1,1]
	v_lshlrev_b32_e32 v24, 16, v27
	v_and_b32_e32 v25, 0xffff0000, v27
	v_pk_fma_f32 v[26:27], v[232:233], v[24:25], v[154:155] op_sel_hi:[0,1,1]
	v_pk_fma_f32 v[26:27], v[132:133], v[26:27], v[54:55] op_sel_hi:[0,1,1] neg_lo:[0,0,1] neg_hi:[0,0,1]
	v_cvt_pk_bf16_f32 v189, v26, v27
	v_lshl_add_u64 v[26:27], v[126:127], 0, s[0:1]
	global_store_dwordx4 v[26:27], v[186:189], off
	v_sub_u32_e32 v26, s13, v167
	v_add_u32_e32 v27, s13, v167
	v_max_i32_e32 v133, 0, v26
	v_min_i32_e32 v155, s9, v27
	v_pk_fma_f32 v[26:27], v[232:233], v[104:105], 0 op_sel_hi:[0,1,0]
	v_pk_fma_f32 v[26:27], v[232:233], v[112:113], v[26:27] op_sel_hi:[0,1,1]
	v_pk_fma_f32 v[26:27], v[232:233], v[92:93], v[26:27] op_sel_hi:[0,1,1]
	v_pk_fma_f32 v[26:27], v[232:233], v[88:89], v[26:27] op_sel_hi:[0,1,1]
	v_pk_fma_f32 v[26:27], v[230:231], v[86:87], v[26:27] op_sel_hi:[0,1,1]
	v_pk_fma_f32 v[26:27], v[230:231], v[84:85], v[26:27] op_sel_hi:[0,1,1]
	v_pk_fma_f32 v[182:183], v[228:229], v[60:61], v[26:27] op_sel_hi:[0,1,1]
	v_pk_fma_f32 v[26:27], v[232:233], v[102:103], 0 op_sel_hi:[0,1,0]
	v_pk_fma_f32 v[26:27], v[232:233], v[114:115], v[26:27] op_sel_hi:[0,1,1]
	v_pk_fma_f32 v[26:27], v[232:233], v[94:95], v[26:27] op_sel_hi:[0,1,1]
	v_pk_fma_f32 v[26:27], v[232:233], v[80:81], v[26:27] op_sel_hi:[0,1,1]
	v_pk_fma_f32 v[26:27], v[230:231], v[72:73], v[26:27] op_sel_hi:[0,1,1]
	v_pk_fma_f32 v[26:27], v[230:231], v[64:65], v[26:27] op_sel_hi:[0,1,1]
	v_pk_fma_f32 v[180:181], v[228:229], v[56:57], v[26:27] op_sel_hi:[0,1,1]
	v_pk_fma_f32 v[26:27], v[232:233], v[100:101], 0 op_sel_hi:[0,1,0]
	v_pk_fma_f32 v[98:99], v[232:233], v[98:99], 0 op_sel_hi:[0,1,0]
	v_pk_fma_f32 v[26:27], v[232:233], v[116:117], v[26:27] op_sel_hi:[0,1,1]
	v_pk_fma_f32 v[98:99], v[232:233], v[134:135], v[98:99] op_sel_hi:[0,1,1]
	v_pk_fma_f32 v[26:27], v[232:233], v[96:97], v[26:27] op_sel_hi:[0,1,1]
	v_pk_fma_f32 v[98:99], v[232:233], v[110:111], v[98:99] op_sel_hi:[0,1,1]
	v_pk_fma_f32 v[26:27], v[232:233], v[90:91], v[26:27] op_sel_hi:[0,1,1]
	v_pk_fma_f32 v[98:99], v[232:233], v[82:83], v[98:99] op_sel_hi:[0,1,1]
	v_pk_fma_f32 v[26:27], v[230:231], v[76:77], v[26:27] op_sel_hi:[0,1,1]
	v_pk_fma_f32 v[98:99], v[230:231], v[70:71], v[98:99] op_sel_hi:[0,1,1]
	v_pk_fma_f32 v[26:27], v[230:231], v[68:69], v[26:27] op_sel_hi:[0,1,1]
	v_pk_fma_f32 v[98:99], v[230:231], v[66:67], v[98:99] op_sel_hi:[0,1,1]
	v_pk_fma_f32 v[26:27], v[228:229], v[62:63], v[26:27] op_sel_hi:[0,1,1]
	v_pk_fma_f32 v[130:131], v[228:229], v[58:59], v[98:99] op_sel_hi:[0,1,1]
	v_sub_u32_e32 v98, v155, v133
	v_cvt_f32_i32_e32 v98, v98
	s_add_i32 s23, s8, 17
	s_nop 0
	v_div_scale_f32 v99, s[0:1], v98, v98, 1.0
	v_rcp_f32_e32 v100, v99
	s_or_b32 s0, s4, 10
	s_ashr_i32 s1, s0, 31
	s_lshl_b64 s[0:1], s[0:1], 11
	v_fma_f32 v101, -v99, v100, 1.0
	v_fmac_f32_e32 v100, v101, v100
	v_div_scale_f32 v101, vcc, 1.0, v98, 1.0
	v_mul_f32_e32 v103, v101, v100
	v_fma_f32 v104, -v99, v103, v101
	v_fmac_f32_e32 v103, v104, v100
	v_fma_f32 v99, -v99, v103, v101
	v_div_fmas_f32 v99, v99, v100, v103
	v_div_fixup_f32 v104, v99, v98, 1.0
	v_pk_fma_f32 v[98:99], v[234:235], v[74:75], v[182:183] op_sel_hi:[0,1,1]
	v_pk_fma_f32 v[98:99], v[234:235], v[106:107], v[98:99] op_sel_hi:[0,1,1]
	v_pk_fma_f32 v[98:99], v[228:229], v[120:121], v[98:99] op_sel_hi:[0,1,1]
	v_pk_fma_f32 v[98:99], v[230:231], v[136:137], v[98:99] op_sel_hi:[0,1,1]
	v_pk_fma_f32 v[98:99], v[230:231], v[148:149], v[98:99] op_sel_hi:[0,1,1]
	v_pk_fma_f32 v[98:99], v[232:233], v[144:145], v[98:99] op_sel_hi:[0,1,1]
	v_pk_fma_f32 v[98:99], v[232:233], v[152:153], v[98:99] op_sel_hi:[0,1,1]
	v_pk_fma_f32 v[98:99], v[232:233], v[128:129], v[98:99] op_sel_hi:[0,1,1]
	s_waitcnt vmcnt(15)
; __device__ __forceinline__ unsigned cvt_pk_bf16(float lo, float hi) { const f32x2 v = (f32x2){lo, hi}; return __builtin_bit_cast(unsigned, __builtin_convertvector(v, bf16v2)); }
; __device__ __forceinline__ float bf_lo(unsigned w) { return __uint_as_float(w << 16); }
; __device__ __forceinline__ float bf_hi(unsigned w) { return __uint_as_float(w & 0xffff0000u); }
; __device__ __forceinline__ void phase_mixer(const Params& p, LAS unsigned char* lds, int l, bool with_ctx, int G, int tid, int wave, int lane, int rep_attn, int rep_pool) {
;     ...
;         for (int o = 0; o < 16; ++o) {
;             const int t = t0 + o, st = max(t - lo, 0), en = min(t + hi + 1, len);
;             float acc[8];
; #pragma unroll
;             for (int e = 0; e < 8; ++e) acc[e] = 0.f;
; #pragma unroll
;             for (int i = 0; i < 16; ++i) { const int tt = t + i - 8; const float wt = (tt >= st && tt < en) ? 1.f : 0.f; const u32x4 ww = w[o + i];
;                 acc[0] += wt * bf_lo(ww.x); acc[1] += wt * bf_hi(ww.x); acc[2] += wt * bf_lo(ww.y); acc[3] += wt * bf_hi(ww.y);
;                 acc[4] += wt * bf_lo(ww.z); acc[5] += wt * bf_hi(ww.z); acc[6] += wt * bf_lo(ww.w); acc[7] += wt * bf_hi(ww.w); }
;             const float ic = 1.f / (float)(en - st);
;             const u32x4 sw = w[o + 8];
;             u32x4 ov; ov.x = cvt_pk_bf16(acc[0] * ic - bf_lo(sw.x), acc[1] * ic - bf_hi(sw.x)); ov.y = cvt_pk_bf16(acc[2] * ic - bf_lo(sw.y), acc[3] * ic - bf_hi(sw.y));
;             ov.z = cvt_pk_bf16(acc[4] * ic - bf_lo(sw.z), acc[5] * ic - bf_hi(sw.z)); ov.w = cvt_pk_bf16(acc[6] * ic - bf_lo(sw.w), acc[7] * ic - bf_hi(sw.w));
;             *(u32x4*)(MIX + (size_t)(tok0 + o) * DM + 8 * lane) = ov;
	v_and_b32_e32 v20, v242, v20
	v_and_b32_e32 v21, v242, v21
	v_and_b32_e32 v22, v242, v22
	v_and_b32_e32 v23, v242, v23
	v_lshlrev_b32_e32 v100, 16, v20
	v_and_b32_e32 v101, 0xffff0000, v20
	v_pk_fma_f32 v[98:99], v[232:233], v[100:101], v[98:99] op_sel_hi:[0,1,1]
	v_pk_fma_f32 v[98:99], v[104:105], v[98:99], v[106:107] op_sel_hi:[0,1,1] neg_lo:[0,0,1] neg_hi:[0,0,1]
	v_cvt_pk_bf16_f32 v182, v98, v99
	v_pk_fma_f32 v[98:99], v[234:235], v[52:53], v[180:181] op_sel_hi:[0,1,1]
	v_pk_fma_f32 v[98:99], v[234:235], v[48:49], v[98:99] op_sel_hi:[0,1,1]
	v_pk_fma_f32 v[98:99], v[228:229], v[44:45], v[98:99] op_sel_hi:[0,1,1]
	v_pk_fma_f32 v[98:99], v[230:231], v[40:41], v[98:99] op_sel_hi:[0,1,1]
	v_pk_fma_f32 v[98:99], v[230:231], v[36:37], v[98:99] op_sel_hi:[0,1,1]
	v_pk_fma_f32 v[98:99], v[232:233], v[142:143], v[98:99] op_sel_hi:[0,1,1]
	v_pk_fma_f32 v[98:99], v[232:233], v[146:147], v[98:99] op_sel_hi:[0,1,1]
	v_pk_fma_f32 v[180:181], v[232:233], v[118:119], v[98:99] op_sel_hi:[0,1,1]
	v_lshlrev_b32_e32 v98, 16, v21
	v_and_b32_e32 v99, 0xffff0000, v21
	v_pk_fma_f32 v[20:21], v[232:233], v[98:99], v[180:181] op_sel_hi:[0,1,1]
	v_pk_fma_f32 v[20:21], v[104:105], v[20:21], v[48:49] op_sel_hi:[0,1,1] neg_lo:[0,0,1] neg_hi:[0,0,1]
	v_cvt_pk_bf16_f32 v183, v20, v21
	v_pk_fma_f32 v[20:21], v[234:235], v[78:79], v[26:27] op_sel_hi:[0,1,1]
	v_pk_fma_f32 v[20:21], v[234:235], v[108:109], v[20:21] op_sel_hi:[0,1,1]
	v_pk_fma_f32 v[20:21], v[228:229], v[122:123], v[20:21] op_sel_hi:[0,1,1]
	v_pk_fma_f32 v[20:21], v[230:231], v[138:139], v[20:21] op_sel_hi:[0,1,1]
	v_pk_fma_f32 v[20:21], v[230:231], v[150:151], v[20:21] op_sel_hi:[0,1,1]
	v_pk_fma_f32 v[20:21], v[232:233], v[140:141], v[20:21] op_sel_hi:[0,1,1]
	v_pk_fma_f32 v[20:21], v[232:233], v[34:35], v[20:21] op_sel_hi:[0,1,1]
	v_pk_fma_f32 v[20:21], v[232:233], v[30:31], v[20:21] op_sel_hi:[0,1,1]
	v_lshlrev_b32_e32 v26, 16, v22
	v_and_b32_e32 v27, 0xffff0000, v22
	v_pk_fma_f32 v[20:21], v[232:233], v[26:27], v[20:21] op_sel_hi:[0,1,1]
	v_pk_fma_f32 v[20:21], v[104:105], v[20:21], v[108:109] op_sel_hi:[0,1,1] neg_lo:[0,0,1] neg_hi:[0,0,1]
	v_cvt_pk_bf16_f32 v184, v20, v21
	v_pk_fma_f32 v[20:21], v[234:235], v[54:55], v[130:131] op_sel_hi:[0,1,1]
	v_pk_fma_f32 v[20:21], v[234:235], v[50:51], v[20:21] op_sel_hi:[0,1,1]
	v_pk_fma_f32 v[20:21], v[228:229], v[46:47], v[20:21] op_sel_hi:[0,1,1]
	v_pk_fma_f32 v[20:21], v[230:231], v[42:43], v[20:21] op_sel_hi:[0,1,1]
	v_pk_fma_f32 v[20:21], v[230:231], v[38:39], v[20:21] op_sel_hi:[0,1,1]
	v_pk_fma_f32 v[20:21], v[232:233], v[32:33], v[20:21] op_sel_hi:[0,1,1]
	v_pk_fma_f32 v[20:21], v[232:233], v[28:29], v[20:21] op_sel_hi:[0,1,1]
	v_pk_fma_f32 v[130:131], v[232:233], v[24:25], v[20:21] op_sel_hi:[0,1,1]
	v_lshlrev_b32_e32 v20, 16, v23
	v_and_b32_e32 v21, 0xffff0000, v23
	v_pk_fma_f32 v[22:23], v[232:233], v[20:21], v[130:131] op_sel_hi:[0,1,1]
	v_pk_fma_f32 v[22:23], v[104:105], v[22:23], v[50:51] op_sel_hi:[0,1,1] neg_lo:[0,0,1] neg_hi:[0,0,1]
	v_cvt_pk_bf16_f32 v185, v22, v23
	v_lshl_add_u64 v[22:23], v[126:127], 0, s[0:1]
	global_store_dwordx4 v[22:23], v[182:185], off
	v_sub_u32_e32 v22, s14, v167
	v_add_u32_e32 v23, s14, v167
	v_max_i32_e32 v131, 0, v22
	v_min_i32_e32 v133, s9, v23
	v_pk_fma_f32 v[22:23], v[232:233], v[112:113], 0 op_sel_hi:[0,1,0]
	v_pk_fma_f32 v[22:23], v[232:233], v[92:93], v[22:23] op_sel_hi:[0,1,1]
	v_pk_fma_f32 v[22:23], v[232:233], v[88:89], v[22:23] op_sel_hi:[0,1,1]
	v_pk_fma_f32 v[22:23], v[232:233], v[86:87], v[22:23] op_sel_hi:[0,1,1]
	v_pk_fma_f32 v[22:23], v[230:231], v[84:85], v[22:23] op_sel_hi:[0,1,1]
	v_pk_fma_f32 v[22:23], v[230:231], v[60:61], v[22:23] op_sel_hi:[0,1,1]
	v_pk_fma_f32 v[176:177], v[228:229], v[74:75], v[22:23] op_sel_hi:[0,1,1]
	v_pk_fma_f32 v[22:23], v[232:233], v[114:115], 0 op_sel_hi:[0,1,0]
	v_pk_fma_f32 v[22:23], v[232:233], v[94:95], v[22:23] op_sel_hi:[0,1,1]
	v_pk_fma_f32 v[22:23], v[232:233], v[80:81], v[22:23] op_sel_hi:[0,1,1]
	v_pk_fma_f32 v[22:23], v[232:233], v[72:73], v[22:23] op_sel_hi:[0,1,1]
	v_pk_fma_f32 v[22:23], v[230:231], v[64:65], v[22:23] op_sel_hi:[0,1,1]
	v_pk_fma_f32 v[22:23], v[230:231], v[56:57], v[22:23] op_sel_hi:[0,1,1]
	v_pk_fma_f32 v[102:103], v[228:229], v[52:53], v[22:23] op_sel_hi:[0,1,1]
	v_pk_fma_f32 v[22:23], v[232:233], v[116:117], 0 op_sel_hi:[0,1,0]
	v_pk_fma_f32 v[104:105], v[232:233], v[134:135], 0 op_sel_hi:[0,1,0]
	v_pk_fma_f32 v[22:23], v[232:233], v[96:97], v[22:23] op_sel_hi:[0,1,1]
	v_pk_fma_f32 v[104:105], v[232:233], v[110:111], v[104:105] op_sel_hi:[0,1,1]
	v_pk_fma_f32 v[22:23], v[232:233], v[90:91], v[22:23] op_sel_hi:[0,1,1]
	v_pk_fma_f32 v[104:105], v[232:233], v[82:83], v[104:105] op_sel_hi:[0,1,1]
	v_pk_fma_f32 v[22:23], v[232:233], v[76:77], v[22:23] op_sel_hi:[0,1,1]
	v_pk_fma_f32 v[104:105], v[232:233], v[70:71], v[104:105] op_sel_hi:[0,1,1]
	v_pk_fma_f32 v[22:23], v[230:231], v[68:69], v[22:23] op_sel_hi:[0,1,1]
	v_pk_fma_f32 v[104:105], v[230:231], v[66:67], v[104:105] op_sel_hi:[0,1,1]
	v_pk_fma_f32 v[22:23], v[230:231], v[62:63], v[22:23] op_sel_hi:[0,1,1]
	v_pk_fma_f32 v[104:105], v[230:231], v[58:59], v[104:105] op_sel_hi:[0,1,1]
	v_pk_fma_f32 v[116:117], v[228:229], v[54:55], v[104:105] op_sel_hi:[0,1,1]
	v_sub_u32_e32 v104, v133, v131
	v_pk_fma_f32 v[22:23], v[228:229], v[78:79], v[22:23] op_sel_hi:[0,1,1]
	v_cvt_f32_i32_e32 v104, v104
	s_add_i32 s22, s8, 18
	s_nop 0
	v_div_scale_f32 v105, s[0:1], v104, v104, 1.0
	v_rcp_f32_e32 v113, v105
	s_or_b32 s0, s4, 11
	s_ashr_i32 s1, s0, 31
	s_lshl_b64 s[0:1], s[0:1], 11
	v_fma_f32 v114, -v105, v113, 1.0
	v_fmac_f32_e32 v113, v114, v113
	v_div_scale_f32 v114, vcc, 1.0, v104, 1.0
; __device__ __forceinline__ unsigned cvt_pk_bf16(float lo, float hi) { const f32x2 v = (f32x2){lo, hi}; return __builtin_bit_cast(unsigned, __builtin_convertvector(v, bf16v2)); }
; __device__ __forceinline__ float bf_lo(unsigned w) { return __uint_as_float(w << 16); }
; __device__ __forceinline__ float bf_hi(unsigned w) { return __uint_as_float(w & 0xffff0000u); }
; __device__ __forceinline__ void phase_mixer(const Params& p, LAS unsigned char* lds, int l, bool with_ctx, int G, int tid, int wave, int lane, int rep_attn, int rep_pool) {
;     ...
;         for (int o = 0; o < 16; ++o) {
;             const int t = t0 + o, st = max(t - lo, 0), en = min(t + hi + 1, len);
;             float acc[8];
; #pragma unroll
;             for (int e = 0; e < 8; ++e) acc[e] = 0.f;
; #pragma unroll
;             for (int i = 0; i < 16; ++i) { const int tt = t + i - 8; const float wt = (tt >= st && tt < en) ? 1.f : 0.f; const u32x4 ww = w[o + i];
;                 acc[0] += wt * bf_lo(ww.x); acc[1] += wt * bf_hi(ww.x); acc[2] += wt * bf_lo(ww.y); acc[3] += wt * bf_hi(ww.y);
;                 acc[4] += wt * bf_lo(ww.z); acc[5] += wt * bf_hi(ww.z); acc[6] += wt * bf_lo(ww.w); acc[7] += wt * bf_hi(ww.w); }
;             const float ic = 1.f / (float)(en - st);
;             const u32x4 sw = w[o + 8];
;             u32x4 ov; ov.x = cvt_pk_bf16(acc[0] * ic - bf_lo(sw.x), acc[1] * ic - bf_hi(sw.x)); ov.y = cvt_pk_bf16(acc[2] * ic - bf_lo(sw.y), acc[3] * ic - bf_hi(sw.y));
;             ov.z = cvt_pk_bf16(acc[4] * ic - bf_lo(sw.z), acc[5] * ic - bf_hi(sw.z)); ov.w = cvt_pk_bf16(acc[6] * ic - bf_lo(sw.w), acc[7] * ic - bf_hi(sw.w));
;             *(u32x4*)(MIX + (size_t)(tok0 + o) * DM + 8 * lane) = ov;
	v_mul_f32_e32 v115, v114, v113
	v_fma_f32 v131, -v105, v115, v114
	v_fmac_f32_e32 v115, v131, v113
	v_fma_f32 v105, -v105, v115, v114
	v_div_fmas_f32 v105, v105, v113, v115
	v_div_fixup_f32 v114, v105, v104, 1.0
	v_pk_fma_f32 v[104:105], v[234:235], v[106:107], v[176:177] op_sel_hi:[0,1,1]
	v_pk_fma_f32 v[102:103], v[234:235], v[48:49], v[102:103] op_sel_hi:[0,1,1]
	v_pk_fma_f32 v[104:105], v[234:235], v[120:121], v[104:105] op_sel_hi:[0,1,1]
	v_pk_fma_f32 v[102:103], v[234:235], v[44:45], v[102:103] op_sel_hi:[0,1,1]
	v_pk_fma_f32 v[104:105], v[228:229], v[136:137], v[104:105] op_sel_hi:[0,1,1]
	v_pk_fma_f32 v[102:103], v[228:229], v[40:41], v[102:103] op_sel_hi:[0,1,1]
	v_pk_fma_f32 v[104:105], v[230:231], v[148:149], v[104:105] op_sel_hi:[0,1,1]
	v_pk_fma_f32 v[102:103], v[230:231], v[36:37], v[102:103] op_sel_hi:[0,1,1]
	v_pk_fma_f32 v[104:105], v[230:231], v[144:145], v[104:105] op_sel_hi:[0,1,1]
	v_pk_fma_f32 v[102:103], v[230:231], v[142:143], v[102:103] op_sel_hi:[0,1,1]
	v_pk_fma_f32 v[104:105], v[232:233], v[152:153], v[104:105] op_sel_hi:[0,1,1]
	v_pk_fma_f32 v[102:103], v[232:233], v[146:147], v[102:103] op_sel_hi:[0,1,1]
	v_pk_fma_f32 v[104:105], v[232:233], v[128:129], v[104:105] op_sel_hi:[0,1,1]
	v_pk_fma_f32 v[102:103], v[232:233], v[118:119], v[102:103] op_sel_hi:[0,1,1]
	v_pk_fma_f32 v[176:177], v[232:233], v[100:101], v[104:105] op_sel_hi:[0,1,1]
	s_waitcnt vmcnt(15)
	v_and_b32_e32 v16, v242, v16
	v_and_b32_e32 v17, v242, v17
	v_and_b32_e32 v18, v242, v18
	v_and_b32_e32 v19, v242, v19
	v_lshlrev_b32_e32 v104, 16, v16
	v_and_b32_e32 v105, 0xffff0000, v16
	v_pk_fma_f32 v[178:179], v[232:233], v[98:99], v[102:103] op_sel_hi:[0,1,1]
	v_lshlrev_b32_e32 v102, 16, v17
	v_and_b32_e32 v103, 0xffff0000, v17
	v_pk_fma_f32 v[176:177], v[232:233], v[104:105], v[176:177] op_sel_hi:[0,1,1]
	v_pk_fma_f32 v[16:17], v[232:233], v[102:103], v[178:179] op_sel_hi:[0,1,1]
	v_pk_fma_f32 v[176:177], v[114:115], v[176:177], v[120:121] op_sel_hi:[0,1,1] neg_lo:[0,0,1] neg_hi:[0,0,1]
	v_pk_fma_f32 v[16:17], v[114:115], v[16:17], v[44:45] op_sel_hi:[0,1,1] neg_lo:[0,0,1] neg_hi:[0,0,1]
	v_cvt_pk_bf16_f32 v176, v176, v177
	v_cvt_pk_bf16_f32 v177, v16, v17
	v_pk_fma_f32 v[16:17], v[234:235], v[108:109], v[22:23] op_sel_hi:[0,1,1]
	v_pk_fma_f32 v[16:17], v[234:235], v[122:123], v[16:17] op_sel_hi:[0,1,1]
	v_pk_fma_f32 v[16:17], v[228:229], v[138:139], v[16:17] op_sel_hi:[0,1,1]
	v_pk_fma_f32 v[16:17], v[230:231], v[150:151], v[16:17] op_sel_hi:[0,1,1]
	v_pk_fma_f32 v[16:17], v[230:231], v[140:141], v[16:17] op_sel_hi:[0,1,1]
	v_pk_fma_f32 v[16:17], v[232:233], v[34:35], v[16:17] op_sel_hi:[0,1,1]
	v_pk_fma_f32 v[16:17], v[232:233], v[30:31], v[16:17] op_sel_hi:[0,1,1]
	v_pk_fma_f32 v[16:17], v[232:233], v[26:27], v[16:17] op_sel_hi:[0,1,1]
	v_lshlrev_b32_e32 v22, 16, v18
	v_and_b32_e32 v23, 0xffff0000, v18
	v_pk_fma_f32 v[16:17], v[232:233], v[22:23], v[16:17] op_sel_hi:[0,1,1]
	v_pk_fma_f32 v[16:17], v[114:115], v[16:17], v[122:123] op_sel_hi:[0,1,1] neg_lo:[0,0,1] neg_hi:[0,0,1]
	v_cvt_pk_bf16_f32 v178, v16, v17
	v_pk_fma_f32 v[16:17], v[234:235], v[50:51], v[116:117] op_sel_hi:[0,1,1]
	v_pk_fma_f32 v[16:17], v[234:235], v[46:47], v[16:17] op_sel_hi:[0,1,1]
	v_pk_fma_f32 v[16:17], v[228:229], v[42:43], v[16:17] op_sel_hi:[0,1,1]
	v_pk_fma_f32 v[16:17], v[230:231], v[38:39], v[16:17] op_sel_hi:[0,1,1]
	v_pk_fma_f32 v[16:17], v[230:231], v[32:33], v[16:17] op_sel_hi:[0,1,1]
	v_pk_fma_f32 v[16:17], v[232:233], v[28:29], v[16:17] op_sel_hi:[0,1,1]
	v_pk_fma_f32 v[16:17], v[232:233], v[24:25], v[16:17] op_sel_hi:[0,1,1]
	v_pk_fma_f32 v[116:117], v[232:233], v[20:21], v[16:17] op_sel_hi:[0,1,1]
	v_lshlrev_b32_e32 v16, 16, v19
	v_and_b32_e32 v17, 0xffff0000, v19
	v_pk_fma_f32 v[18:19], v[232:233], v[16:17], v[116:117] op_sel_hi:[0,1,1]
	v_pk_fma_f32 v[18:19], v[114:115], v[18:19], v[46:47] op_sel_hi:[0,1,1] neg_lo:[0,0,1] neg_hi:[0,0,1]
	v_cvt_pk_bf16_f32 v179, v18, v19
	v_lshl_add_u64 v[18:19], v[126:127], 0, s[0:1]
	global_store_dwordx4 v[18:19], v[176:179], off
	v_sub_u32_e32 v18, s15, v167
	v_add_u32_e32 v19, s15, v167
	v_max_i32_e32 v115, 0, v18
	v_min_i32_e32 v117, s9, v19
	v_pk_fma_f32 v[18:19], v[232:233], v[92:93], 0 op_sel_hi:[0,1,0]
	v_pk_fma_f32 v[18:19], v[232:233], v[88:89], v[18:19] op_sel_hi:[0,1,1]
	v_pk_fma_f32 v[18:19], v[232:233], v[86:87], v[18:19] op_sel_hi:[0,1,1]
	v_pk_fma_f32 v[18:19], v[232:233], v[84:85], v[18:19] op_sel_hi:[0,1,1]
	v_pk_fma_f32 v[18:19], v[230:231], v[60:61], v[18:19] op_sel_hi:[0,1,1]
	v_pk_fma_f32 v[18:19], v[230:231], v[74:75], v[18:19] op_sel_hi:[0,1,1]
	v_pk_fma_f32 v[172:173], v[228:229], v[106:107], v[18:19] op_sel_hi:[0,1,1]
	v_pk_fma_f32 v[18:19], v[232:233], v[94:95], 0 op_sel_hi:[0,1,0]
	v_pk_fma_f32 v[18:19], v[232:233], v[80:81], v[18:19] op_sel_hi:[0,1,1]
	v_pk_fma_f32 v[18:19], v[232:233], v[72:73], v[18:19] op_sel_hi:[0,1,1]
	v_pk_fma_f32 v[18:19], v[232:233], v[64:65], v[18:19] op_sel_hi:[0,1,1]
	v_pk_fma_f32 v[18:19], v[230:231], v[56:57], v[18:19] op_sel_hi:[0,1,1]
	v_pk_fma_f32 v[18:19], v[230:231], v[52:53], v[18:19] op_sel_hi:[0,1,1]
	v_pk_fma_f32 v[92:93], v[228:229], v[48:49], v[18:19] op_sel_hi:[0,1,1]
	v_pk_fma_f32 v[18:19], v[232:233], v[96:97], 0 op_sel_hi:[0,1,0]
	v_pk_fma_f32 v[94:95], v[232:233], v[110:111], 0 op_sel_hi:[0,1,0]
	v_pk_fma_f32 v[18:19], v[232:233], v[90:91], v[18:19] op_sel_hi:[0,1,1]
	v_pk_fma_f32 v[94:95], v[232:233], v[82:83], v[94:95] op_sel_hi:[0,1,1]
	v_pk_fma_f32 v[18:19], v[232:233], v[76:77], v[18:19] op_sel_hi:[0,1,1]
	v_pk_fma_f32 v[94:95], v[232:233], v[70:71], v[94:95] op_sel_hi:[0,1,1]
	v_pk_fma_f32 v[18:19], v[232:233], v[68:69], v[18:19] op_sel_hi:[0,1,1]
; __device__ __forceinline__ unsigned cvt_pk_bf16(float lo, float hi) { const f32x2 v = (f32x2){lo, hi}; return __builtin_bit_cast(unsigned, __builtin_convertvector(v, bf16v2)); }
; __device__ __forceinline__ float bf_lo(unsigned w) { return __uint_as_float(w << 16); }
; __device__ __forceinline__ float bf_hi(unsigned w) { return __uint_as_float(w & 0xffff0000u); }
; __device__ __forceinline__ void phase_mixer(const Params& p, LAS unsigned char* lds, int l, bool with_ctx, int G, int tid, int wave, int lane, int rep_attn, int rep_pool) {
;     ...
;         for (int o = 0; o < 16; ++o) {
;             const int t = t0 + o, st = max(t - lo, 0), en = min(t + hi + 1, len);
;             float acc[8];
; #pragma unroll
;             for (int e = 0; e < 8; ++e) acc[e] = 0.f;
; #pragma unroll
;             for (int i = 0; i < 16; ++i) { const int tt = t + i - 8; const float wt = (tt >= st && tt < en) ? 1.f : 0.f; const u32x4 ww = w[o + i];
;                 acc[0] += wt * bf_lo(ww.x); acc[1] += wt * bf_hi(ww.x); acc[2] += wt * bf_lo(ww.y); acc[3] += wt * bf_hi(ww.y);
;                 acc[4] += wt * bf_lo(ww.z); acc[5] += wt * bf_hi(ww.z); acc[6] += wt * bf_lo(ww.w); acc[7] += wt * bf_hi(ww.w); }
;             const float ic = 1.f / (float)(en - st);
;             const u32x4 sw = w[o + 8];
;             u32x4 ov; ov.x = cvt_pk_bf16(acc[0] * ic - bf_lo(sw.x), acc[1] * ic - bf_hi(sw.x)); ov.y = cvt_pk_bf16(acc[2] * ic - bf_lo(sw.y), acc[3] * ic - bf_hi(sw.y));
;             ov.z = cvt_pk_bf16(acc[4] * ic - bf_lo(sw.z), acc[5] * ic - bf_hi(sw.z)); ov.w = cvt_pk_bf16(acc[6] * ic - bf_lo(sw.w), acc[7] * ic - bf_hi(sw.w));
;             *(u32x4*)(MIX + (size_t)(tok0 + o) * DM + 8 * lane) = ov;
	v_pk_fma_f32 v[94:95], v[232:233], v[66:67], v[94:95] op_sel_hi:[0,1,1]
	v_pk_fma_f32 v[18:19], v[230:231], v[62:63], v[18:19] op_sel_hi:[0,1,1]
	v_pk_fma_f32 v[94:95], v[230:231], v[58:59], v[94:95] op_sel_hi:[0,1,1]
	v_pk_fma_f32 v[18:19], v[230:231], v[78:79], v[18:19] op_sel_hi:[0,1,1]
	v_pk_fma_f32 v[94:95], v[230:231], v[54:55], v[94:95] op_sel_hi:[0,1,1]
	v_pk_fma_f32 v[18:19], v[228:229], v[108:109], v[18:19] op_sel_hi:[0,1,1]
	v_pk_fma_f32 v[112:113], v[228:229], v[50:51], v[94:95] op_sel_hi:[0,1,1]
	v_sub_u32_e32 v94, v117, v115
	v_cvt_f32_i32_e32 v94, v94
	s_add_i32 s21, s8, 19
	s_nop 0
	v_div_scale_f32 v95, s[0:1], v94, v94, 1.0
	v_rcp_f32_e32 v97, v95
	s_or_b32 s0, s4, 12
	s_ashr_i32 s1, s0, 31
	s_lshl_b64 s[0:1], s[0:1], 11
	v_fma_f32 v110, -v95, v97, 1.0
	v_fmac_f32_e32 v97, v110, v97
	v_div_scale_f32 v110, vcc, 1.0, v94, 1.0
	v_mul_f32_e32 v111, v110, v97
	v_fma_f32 v115, -v95, v111, v110
	v_fmac_f32_e32 v111, v115, v97
	v_fma_f32 v95, -v95, v111, v110
	v_div_fmas_f32 v95, v95, v97, v111
	v_div_fixup_f32 v110, v95, v94, 1.0
	v_pk_fma_f32 v[94:95], v[234:235], v[120:121], v[172:173] op_sel_hi:[0,1,1]
	v_pk_fma_f32 v[92:93], v[234:235], v[44:45], v[92:93] op_sel_hi:[0,1,1]
	v_pk_fma_f32 v[94:95], v[234:235], v[136:137], v[94:95] op_sel_hi:[0,1,1]
	v_pk_fma_f32 v[92:93], v[234:235], v[40:41], v[92:93] op_sel_hi:[0,1,1]
	v_pk_fma_f32 v[94:95], v[228:229], v[148:149], v[94:95] op_sel_hi:[0,1,1]
	v_pk_fma_f32 v[92:93], v[228:229], v[36:37], v[92:93] op_sel_hi:[0,1,1]
	v_pk_fma_f32 v[94:95], v[230:231], v[144:145], v[94:95] op_sel_hi:[0,1,1]
	v_pk_fma_f32 v[92:93], v[230:231], v[142:143], v[92:93] op_sel_hi:[0,1,1]
	v_pk_fma_f32 v[94:95], v[230:231], v[152:153], v[94:95] op_sel_hi:[0,1,1]
	v_pk_fma_f32 v[92:93], v[230:231], v[146:147], v[92:93] op_sel_hi:[0,1,1]
	v_pk_fma_f32 v[94:95], v[232:233], v[128:129], v[94:95] op_sel_hi:[0,1,1]
	v_pk_fma_f32 v[92:93], v[232:233], v[118:119], v[92:93] op_sel_hi:[0,1,1]
	v_pk_fma_f32 v[94:95], v[232:233], v[100:101], v[94:95] op_sel_hi:[0,1,1]
	v_pk_fma_f32 v[92:93], v[232:233], v[98:99], v[92:93] op_sel_hi:[0,1,1]
	v_pk_fma_f32 v[172:173], v[232:233], v[104:105], v[94:95] op_sel_hi:[0,1,1]
	s_waitcnt vmcnt(15)
	v_and_b32_e32 v12, v242, v12
	v_and_b32_e32 v13, v242, v13
	v_and_b32_e32 v14, v242, v14
	v_and_b32_e32 v15, v242, v15
	v_lshlrev_b32_e32 v94, 16, v12
	v_and_b32_e32 v95, 0xffff0000, v12
	v_pk_fma_f32 v[174:175], v[232:233], v[102:103], v[92:93] op_sel_hi:[0,1,1]
	v_lshlrev_b32_e32 v92, 16, v13
	v_and_b32_e32 v93, 0xffff0000, v13
	v_pk_fma_f32 v[172:173], v[232:233], v[94:95], v[172:173] op_sel_hi:[0,1,1]
	v_pk_fma_f32 v[12:13], v[232:233], v[92:93], v[174:175] op_sel_hi:[0,1,1]
	v_pk_fma_f32 v[172:173], v[110:111], v[172:173], v[136:137] op_sel_hi:[0,1,1] neg_lo:[0,0,1] neg_hi:[0,0,1]
	v_pk_fma_f32 v[12:13], v[110:111], v[12:13], v[40:41] op_sel_hi:[0,1,1] neg_lo:[0,0,1] neg_hi:[0,0,1]
	v_cvt_pk_bf16_f32 v172, v172, v173
	v_cvt_pk_bf16_f32 v173, v12, v13
	v_pk_fma_f32 v[12:13], v[234:235], v[122:123], v[18:19] op_sel_hi:[0,1,1]
	v_pk_fma_f32 v[12:13], v[234:235], v[138:139], v[12:13] op_sel_hi:[0,1,1]
	v_pk_fma_f32 v[12:13], v[228:229], v[150:151], v[12:13] op_sel_hi:[0,1,1]
	v_pk_fma_f32 v[12:13], v[230:231], v[140:141], v[12:13] op_sel_hi:[0,1,1]
	v_pk_fma_f32 v[12:13], v[230:231], v[34:35], v[12:13] op_sel_hi:[0,1,1]
	v_pk_fma_f32 v[12:13], v[232:233], v[30:31], v[12:13] op_sel_hi:[0,1,1]
	v_pk_fma_f32 v[12:13], v[232:233], v[26:27], v[12:13] op_sel_hi:[0,1,1]
	v_pk_fma_f32 v[12:13], v[232:233], v[22:23], v[12:13] op_sel_hi:[0,1,1]
	v_lshlrev_b32_e32 v18, 16, v14
	v_and_b32_e32 v19, 0xffff0000, v14
	v_pk_fma_f32 v[12:13], v[232:233], v[18:19], v[12:13] op_sel_hi:[0,1,1]
	v_pk_fma_f32 v[12:13], v[110:111], v[12:13], v[138:139] op_sel_hi:[0,1,1] neg_lo:[0,0,1] neg_hi:[0,0,1]
	v_cvt_pk_bf16_f32 v174, v12, v13
	v_pk_fma_f32 v[12:13], v[234:235], v[46:47], v[112:113] op_sel_hi:[0,1,1]
	v_pk_fma_f32 v[12:13], v[234:235], v[42:43], v[12:13] op_sel_hi:[0,1,1]
	v_pk_fma_f32 v[12:13], v[228:229], v[38:39], v[12:13] op_sel_hi:[0,1,1]
	v_pk_fma_f32 v[12:13], v[230:231], v[32:33], v[12:13] op_sel_hi:[0,1,1]
	v_pk_fma_f32 v[12:13], v[230:231], v[28:29], v[12:13] op_sel_hi:[0,1,1]
	v_pk_fma_f32 v[12:13], v[232:233], v[24:25], v[12:13] op_sel_hi:[0,1,1]
	v_pk_fma_f32 v[12:13], v[232:233], v[20:21], v[12:13] op_sel_hi:[0,1,1]
	v_pk_fma_f32 v[112:113], v[232:233], v[16:17], v[12:13] op_sel_hi:[0,1,1]
	v_lshlrev_b32_e32 v12, 16, v15
	v_and_b32_e32 v13, 0xffff0000, v15
	v_pk_fma_f32 v[14:15], v[232:233], v[12:13], v[112:113] op_sel_hi:[0,1,1]
	v_pk_fma_f32 v[14:15], v[110:111], v[14:15], v[42:43] op_sel_hi:[0,1,1] neg_lo:[0,0,1] neg_hi:[0,0,1]
	v_cvt_pk_bf16_f32 v175, v14, v15
	v_lshl_add_u64 v[14:15], v[126:127], 0, s[0:1]
	global_store_dwordx4 v[14:15], v[172:175], off
	v_sub_u32_e32 v14, s17, v167
	v_add_u32_e32 v15, s17, v167
	v_max_i32_e32 v111, 0, v14
	v_min_i32_e32 v113, s9, v15
	v_pk_fma_f32 v[14:15], v[232:233], v[88:89], 0 op_sel_hi:[0,1,0]
	v_pk_fma_f32 v[14:15], v[232:233], v[86:87], v[14:15] op_sel_hi:[0,1,1]
	v_pk_fma_f32 v[14:15], v[232:233], v[84:85], v[14:15] op_sel_hi:[0,1,1]
	v_pk_fma_f32 v[14:15], v[232:233], v[60:61], v[14:15] op_sel_hi:[0,1,1]
	v_pk_fma_f32 v[14:15], v[230:231], v[74:75], v[14:15] op_sel_hi:[0,1,1]
	v_pk_fma_f32 v[14:15], v[230:231], v[106:107], v[14:15] op_sel_hi:[0,1,1]
	v_pk_fma_f32 v[170:171], v[228:229], v[120:121], v[14:15] op_sel_hi:[0,1,1]
	v_pk_fma_f32 v[14:15], v[232:233], v[80:81], 0 op_sel_hi:[0,1,0]
	v_pk_fma_f32 v[14:15], v[232:233], v[72:73], v[14:15] op_sel_hi:[0,1,1]
	v_pk_fma_f32 v[14:15], v[232:233], v[64:65], v[14:15] op_sel_hi:[0,1,1]
; __device__ __forceinline__ unsigned cvt_pk_bf16(float lo, float hi) { const f32x2 v = (f32x2){lo, hi}; return __builtin_bit_cast(unsigned, __builtin_convertvector(v, bf16v2)); }
; __device__ __forceinline__ float bf_lo(unsigned w) { return __uint_as_float(w << 16); }
; __device__ __forceinline__ float bf_hi(unsigned w) { return __uint_as_float(w & 0xffff0000u); }
; __device__ __forceinline__ void phase_mixer(const Params& p, LAS unsigned char* lds, int l, bool with_ctx, int G, int tid, int wave, int lane, int rep_attn, int rep_pool) {
;     ...
;         for (int o = 0; o < 16; ++o) {
;             const int t = t0 + o, st = max(t - lo, 0), en = min(t + hi + 1, len);
;             float acc[8];
; #pragma unroll
;             for (int e = 0; e < 8; ++e) acc[e] = 0.f;
; #pragma unroll
;             for (int i = 0; i < 16; ++i) { const int tt = t + i - 8; const float wt = (tt >= st && tt < en) ? 1.f : 0.f; const u32x4 ww = w[o + i];
;                 acc[0] += wt * bf_lo(ww.x); acc[1] += wt * bf_hi(ww.x); acc[2] += wt * bf_lo(ww.y); acc[3] += wt * bf_hi(ww.y);
;                 acc[4] += wt * bf_lo(ww.z); acc[5] += wt * bf_hi(ww.z); acc[6] += wt * bf_lo(ww.w); acc[7] += wt * bf_hi(ww.w); }
;             const float ic = 1.f / (float)(en - st);
;             const u32x4 sw = w[o + 8];
;             u32x4 ov; ov.x = cvt_pk_bf16(acc[0] * ic - bf_lo(sw.x), acc[1] * ic - bf_hi(sw.x)); ov.y = cvt_pk_bf16(acc[2] * ic - bf_lo(sw.y), acc[3] * ic - bf_hi(sw.y));
;             ov.z = cvt_pk_bf16(acc[4] * ic - bf_lo(sw.z), acc[5] * ic - bf_hi(sw.z)); ov.w = cvt_pk_bf16(acc[6] * ic - bf_lo(sw.w), acc[7] * ic - bf_hi(sw.w));
;             *(u32x4*)(MIX + (size_t)(tok0 + o) * DM + 8 * lane) = ov;
	v_pk_fma_f32 v[14:15], v[232:233], v[56:57], v[14:15] op_sel_hi:[0,1,1]
	v_pk_fma_f32 v[14:15], v[230:231], v[52:53], v[14:15] op_sel_hi:[0,1,1]
	v_pk_fma_f32 v[14:15], v[230:231], v[48:49], v[14:15] op_sel_hi:[0,1,1]
	v_pk_fma_f32 v[80:81], v[228:229], v[44:45], v[14:15] op_sel_hi:[0,1,1]
	v_pk_fma_f32 v[14:15], v[232:233], v[90:91], 0 op_sel_hi:[0,1,0]
	v_pk_fma_f32 v[82:83], v[232:233], v[82:83], 0 op_sel_hi:[0,1,0]
	v_pk_fma_f32 v[14:15], v[232:233], v[76:77], v[14:15] op_sel_hi:[0,1,1]
	v_pk_fma_f32 v[82:83], v[232:233], v[70:71], v[82:83] op_sel_hi:[0,1,1]
	v_pk_fma_f32 v[14:15], v[232:233], v[68:69], v[14:15] op_sel_hi:[0,1,1]
	v_pk_fma_f32 v[82:83], v[232:233], v[66:67], v[82:83] op_sel_hi:[0,1,1]
	v_pk_fma_f32 v[14:15], v[232:233], v[62:63], v[14:15] op_sel_hi:[0,1,1]
	v_pk_fma_f32 v[82:83], v[232:233], v[58:59], v[82:83] op_sel_hi:[0,1,1]
	v_pk_fma_f32 v[14:15], v[230:231], v[78:79], v[14:15] op_sel_hi:[0,1,1]
	v_pk_fma_f32 v[82:83], v[230:231], v[54:55], v[82:83] op_sel_hi:[0,1,1]
	v_pk_fma_f32 v[14:15], v[230:231], v[108:109], v[14:15] op_sel_hi:[0,1,1]
	v_pk_fma_f32 v[82:83], v[230:231], v[50:51], v[82:83] op_sel_hi:[0,1,1]
	v_pk_fma_f32 v[14:15], v[228:229], v[122:123], v[14:15] op_sel_hi:[0,1,1]
	v_pk_fma_f32 v[96:97], v[228:229], v[46:47], v[82:83] op_sel_hi:[0,1,1]
	v_sub_u32_e32 v82, v113, v111
	v_cvt_f32_i32_e32 v82, v82
	s_add_i32 s20, s8, 20
	s_nop 0
	v_div_scale_f32 v83, s[0:1], v82, v82, 1.0
	v_rcp_f32_e32 v89, v83
	s_or_b32 s0, s4, 13
	s_ashr_i32 s1, s0, 31
	s_lshl_b64 s[0:1], s[0:1], 11
	v_fma_f32 v90, -v83, v89, 1.0
	v_fmac_f32_e32 v89, v90, v89
	v_div_scale_f32 v90, vcc, 1.0, v82, 1.0
	v_mul_f32_e32 v91, v90, v89
	v_fma_f32 v111, -v83, v91, v90
	v_fmac_f32_e32 v91, v111, v89
	v_fma_f32 v83, -v83, v91, v90
	v_div_fmas_f32 v83, v83, v89, v91
	v_div_fixup_f32 v90, v83, v82, 1.0
	v_pk_fma_f32 v[82:83], v[234:235], v[136:137], v[170:171] op_sel_hi:[0,1,1]
	v_pk_fma_f32 v[80:81], v[234:235], v[40:41], v[80:81] op_sel_hi:[0,1,1]
	v_pk_fma_f32 v[82:83], v[234:235], v[148:149], v[82:83] op_sel_hi:[0,1,1]
	v_pk_fma_f32 v[80:81], v[234:235], v[36:37], v[80:81] op_sel_hi:[0,1,1]
	v_pk_fma_f32 v[82:83], v[228:229], v[144:145], v[82:83] op_sel_hi:[0,1,1]
	v_pk_fma_f32 v[80:81], v[228:229], v[142:143], v[80:81] op_sel_hi:[0,1,1]
	v_pk_fma_f32 v[82:83], v[230:231], v[152:153], v[82:83] op_sel_hi:[0,1,1]
	v_pk_fma_f32 v[80:81], v[230:231], v[146:147], v[80:81] op_sel_hi:[0,1,1]
	v_pk_fma_f32 v[82:83], v[230:231], v[128:129], v[82:83] op_sel_hi:[0,1,1]
	v_pk_fma_f32 v[80:81], v[230:231], v[118:119], v[80:81] op_sel_hi:[0,1,1]
	v_pk_fma_f32 v[82:83], v[232:233], v[100:101], v[82:83] op_sel_hi:[0,1,1]
	v_pk_fma_f32 v[80:81], v[232:233], v[98:99], v[80:81] op_sel_hi:[0,1,1]
	v_pk_fma_f32 v[82:83], v[232:233], v[104:105], v[82:83] op_sel_hi:[0,1,1]
	v_pk_fma_f32 v[80:81], v[232:233], v[102:103], v[80:81] op_sel_hi:[0,1,1]
	v_pk_fma_f32 v[170:171], v[232:233], v[94:95], v[82:83] op_sel_hi:[0,1,1]
	s_waitcnt vmcnt(15)
	v_and_b32_e32 v8, v242, v8
	v_and_b32_e32 v9, v242, v9
	v_and_b32_e32 v10, v242, v10
	v_and_b32_e32 v11, v242, v11
	v_lshlrev_b32_e32 v82, 16, v8
	v_and_b32_e32 v83, 0xffff0000, v8
	v_pk_fma_f32 v[172:173], v[232:233], v[92:93], v[80:81] op_sel_hi:[0,1,1]
	v_lshlrev_b32_e32 v80, 16, v9
	v_and_b32_e32 v81, 0xffff0000, v9
	v_pk_fma_f32 v[170:171], v[232:233], v[82:83], v[170:171] op_sel_hi:[0,1,1]
	v_pk_fma_f32 v[8:9], v[232:233], v[80:81], v[172:173] op_sel_hi:[0,1,1]
	v_pk_fma_f32 v[170:171], v[90:91], v[170:171], v[148:149] op_sel_hi:[0,1,1] neg_lo:[0,0,1] neg_hi:[0,0,1]
	v_pk_fma_f32 v[8:9], v[90:91], v[8:9], v[36:37] op_sel_hi:[0,1,1] neg_lo:[0,0,1] neg_hi:[0,0,1]
	v_cvt_pk_bf16_f32 v170, v170, v171
	v_cvt_pk_bf16_f32 v171, v8, v9
	v_pk_fma_f32 v[8:9], v[234:235], v[138:139], v[14:15] op_sel_hi:[0,1,1]
	v_pk_fma_f32 v[8:9], v[234:235], v[150:151], v[8:9] op_sel_hi:[0,1,1]
	v_pk_fma_f32 v[8:9], v[228:229], v[140:141], v[8:9] op_sel_hi:[0,1,1]
	v_pk_fma_f32 v[8:9], v[230:231], v[34:35], v[8:9] op_sel_hi:[0,1,1]
	v_pk_fma_f32 v[8:9], v[230:231], v[30:31], v[8:9] op_sel_hi:[0,1,1]
	v_pk_fma_f32 v[8:9], v[232:233], v[26:27], v[8:9] op_sel_hi:[0,1,1]
	v_pk_fma_f32 v[8:9], v[232:233], v[22:23], v[8:9] op_sel_hi:[0,1,1]
	v_pk_fma_f32 v[8:9], v[232:233], v[18:19], v[8:9] op_sel_hi:[0,1,1]
	v_lshlrev_b32_e32 v14, 16, v10
	v_and_b32_e32 v15, 0xffff0000, v10
	v_pk_fma_f32 v[8:9], v[232:233], v[14:15], v[8:9] op_sel_hi:[0,1,1]
	v_pk_fma_f32 v[8:9], v[90:91], v[8:9], v[150:151] op_sel_hi:[0,1,1] neg_lo:[0,0,1] neg_hi:[0,0,1]
	v_cvt_pk_bf16_f32 v172, v8, v9
	v_pk_fma_f32 v[8:9], v[234:235], v[42:43], v[96:97] op_sel_hi:[0,1,1]
	v_pk_fma_f32 v[8:9], v[234:235], v[38:39], v[8:9] op_sel_hi:[0,1,1]
	v_pk_fma_f32 v[8:9], v[228:229], v[32:33], v[8:9] op_sel_hi:[0,1,1]
	v_pk_fma_f32 v[8:9], v[230:231], v[28:29], v[8:9] op_sel_hi:[0,1,1]
	v_pk_fma_f32 v[8:9], v[230:231], v[24:25], v[8:9] op_sel_hi:[0,1,1]
	v_pk_fma_f32 v[8:9], v[232:233], v[20:21], v[8:9] op_sel_hi:[0,1,1]
	v_pk_fma_f32 v[8:9], v[232:233], v[16:17], v[8:9] op_sel_hi:[0,1,1]
	v_pk_fma_f32 v[96:97], v[232:233], v[12:13], v[8:9] op_sel_hi:[0,1,1]
	v_lshlrev_b32_e32 v8, 16, v11
	v_and_b32_e32 v9, 0xffff0000, v11
	v_pk_fma_f32 v[10:11], v[232:233], v[8:9], v[96:97] op_sel_hi:[0,1,1]
	v_pk_fma_f32 v[10:11], v[90:91], v[10:11], v[38:39] op_sel_hi:[0,1,1] neg_lo:[0,0,1] neg_hi:[0,0,1]
	v_cvt_pk_bf16_f32 v173, v10, v11
	v_lshl_add_u64 v[10:11], v[126:127], 0, s[0:1]
	global_store_dwordx4 v[10:11], v[170:173], off
	v_sub_u32_e32 v10, s16, v167
	v_add_u32_e32 v11, s16, v167
	v_max_i32_e32 v89, 0, v10
	v_min_i32_e32 v91, s9, v11
	v_pk_fma_f32 v[86:87], v[232:233], v[86:87], 0 op_sel_hi:[0,1,0]
; __device__ __forceinline__ unsigned cvt_pk_bf16(float lo, float hi) { const f32x2 v = (f32x2){lo, hi}; return __builtin_bit_cast(unsigned, __builtin_convertvector(v, bf16v2)); }
; __device__ __forceinline__ float bf_lo(unsigned w) { return __uint_as_float(w << 16); }
; __device__ __forceinline__ float bf_hi(unsigned w) { return __uint_as_float(w & 0xffff0000u); }
; __device__ __forceinline__ void phase_mixer(const Params& p, LAS unsigned char* lds, int l, bool with_ctx, int G, int tid, int wave, int lane, int rep_attn, int rep_pool) {
;     ...
;         for (int o = 0; o < 16; ++o) {
;             const int t = t0 + o, st = max(t - lo, 0), en = min(t + hi + 1, len);
;             float acc[8];
; #pragma unroll
;             for (int e = 0; e < 8; ++e) acc[e] = 0.f;
; #pragma unroll
;             for (int i = 0; i < 16; ++i) { const int tt = t + i - 8; const float wt = (tt >= st && tt < en) ? 1.f : 0.f; const u32x4 ww = w[o + i];
;                 acc[0] += wt * bf_lo(ww.x); acc[1] += wt * bf_hi(ww.x); acc[2] += wt * bf_lo(ww.y); acc[3] += wt * bf_hi(ww.y);
;                 acc[4] += wt * bf_lo(ww.z); acc[5] += wt * bf_hi(ww.z); acc[6] += wt * bf_lo(ww.w); acc[7] += wt * bf_hi(ww.w); }
;             const float ic = 1.f / (float)(en - st);
;             const u32x4 sw = w[o + 8];
;             u32x4 ov; ov.x = cvt_pk_bf16(acc[0] * ic - bf_lo(sw.x), acc[1] * ic - bf_hi(sw.x)); ov.y = cvt_pk_bf16(acc[2] * ic - bf_lo(sw.y), acc[3] * ic - bf_hi(sw.y));
;             ov.z = cvt_pk_bf16(acc[4] * ic - bf_lo(sw.z), acc[5] * ic - bf_hi(sw.z)); ov.w = cvt_pk_bf16(acc[6] * ic - bf_lo(sw.w), acc[7] * ic - bf_hi(sw.w));
;             *(u32x4*)(MIX + (size_t)(tok0 + o) * DM + 8 * lane) = ov;
	v_pk_fma_f32 v[72:73], v[232:233], v[72:73], 0 op_sel_hi:[0,1,0]
	v_pk_fma_f32 v[76:77], v[232:233], v[76:77], 0 op_sel_hi:[0,1,0]
	v_pk_fma_f32 v[10:11], v[232:233], v[70:71], 0 op_sel_hi:[0,1,0]
	v_pk_fma_f32 v[86:87], v[232:233], v[84:85], v[86:87] op_sel_hi:[0,1,1]
	v_pk_fma_f32 v[72:73], v[232:233], v[64:65], v[72:73] op_sel_hi:[0,1,1]
	v_pk_fma_f32 v[76:77], v[232:233], v[68:69], v[76:77] op_sel_hi:[0,1,1]
	v_pk_fma_f32 v[10:11], v[232:233], v[66:67], v[10:11] op_sel_hi:[0,1,1]
	v_pk_fma_f32 v[86:87], v[232:233], v[60:61], v[86:87] op_sel_hi:[0,1,1]
	v_pk_fma_f32 v[72:73], v[232:233], v[56:57], v[72:73] op_sel_hi:[0,1,1]
	v_pk_fma_f32 v[76:77], v[232:233], v[62:63], v[76:77] op_sel_hi:[0,1,1]
	v_pk_fma_f32 v[10:11], v[232:233], v[58:59], v[10:11] op_sel_hi:[0,1,1]
	v_pk_fma_f32 v[86:87], v[232:233], v[74:75], v[86:87] op_sel_hi:[0,1,1]
	v_pk_fma_f32 v[72:73], v[232:233], v[52:53], v[72:73] op_sel_hi:[0,1,1]
	v_pk_fma_f32 v[76:77], v[232:233], v[78:79], v[76:77] op_sel_hi:[0,1,1]
	v_pk_fma_f32 v[10:11], v[232:233], v[54:55], v[10:11] op_sel_hi:[0,1,1]
	v_pk_fma_f32 v[86:87], v[230:231], v[106:107], v[86:87] op_sel_hi:[0,1,1]
	v_pk_fma_f32 v[72:73], v[230:231], v[48:49], v[72:73] op_sel_hi:[0,1,1]
	v_pk_fma_f32 v[76:77], v[230:231], v[108:109], v[76:77] op_sel_hi:[0,1,1]
	v_pk_fma_f32 v[10:11], v[230:231], v[50:51], v[10:11] op_sel_hi:[0,1,1]
	v_pk_fma_f32 v[86:87], v[230:231], v[120:121], v[86:87] op_sel_hi:[0,1,1]
	v_pk_fma_f32 v[72:73], v[230:231], v[44:45], v[72:73] op_sel_hi:[0,1,1]
	v_pk_fma_f32 v[76:77], v[230:231], v[122:123], v[76:77] op_sel_hi:[0,1,1]
	v_pk_fma_f32 v[10:11], v[230:231], v[46:47], v[10:11] op_sel_hi:[0,1,1]
	v_pk_fma_f32 v[134:135], v[228:229], v[136:137], v[86:87] op_sel_hi:[0,1,1]
	v_pk_fma_f32 v[72:73], v[228:229], v[40:41], v[72:73] op_sel_hi:[0,1,1]
	v_pk_fma_f32 v[132:133], v[228:229], v[138:139], v[76:77] op_sel_hi:[0,1,1]
	v_pk_fma_f32 v[10:11], v[228:229], v[42:43], v[10:11] op_sel_hi:[0,1,1]
	v_sub_u32_e32 v70, v91, v89
	v_cvt_f32_i32_e32 v70, v70
	s_add_i32 s19, s8, 21
	s_add_i32 s8, s8, 22
	v_div_scale_f32 v71, s[0:1], v70, v70, 1.0
	v_rcp_f32_e32 v77, v71
	s_or_b32 s0, s4, 14
	s_ashr_i32 s1, s0, 31
	s_lshl_b64 s[0:1], s[0:1], 11
	v_fma_f32 v86, -v71, v77, 1.0
	v_fmac_f32_e32 v77, v86, v77
	v_div_scale_f32 v86, vcc, 1.0, v70, 1.0
	v_mul_f32_e32 v87, v86, v77
	v_fma_f32 v89, -v71, v87, v86
	v_fmac_f32_e32 v87, v89, v77
	v_fma_f32 v71, -v71, v87, v86
	v_div_fmas_f32 v71, v71, v77, v87
	v_div_fixup_f32 v86, v71, v70, 1.0
	v_pk_fma_f32 v[70:71], v[234:235], v[148:149], v[134:135] op_sel_hi:[0,1,1]
	v_pk_fma_f32 v[70:71], v[234:235], v[144:145], v[70:71] op_sel_hi:[0,1,1]
	v_pk_fma_f32 v[70:71], v[228:229], v[152:153], v[70:71] op_sel_hi:[0,1,1]
	v_pk_fma_f32 v[70:71], v[230:231], v[128:129], v[70:71] op_sel_hi:[0,1,1]
	v_pk_fma_f32 v[70:71], v[230:231], v[100:101], v[70:71] op_sel_hi:[0,1,1]
	v_pk_fma_f32 v[70:71], v[232:233], v[104:105], v[70:71] op_sel_hi:[0,1,1]
	v_pk_fma_f32 v[70:71], v[232:233], v[94:95], v[70:71] op_sel_hi:[0,1,1]
	v_pk_fma_f32 v[70:71], v[232:233], v[82:83], v[70:71] op_sel_hi:[0,1,1]
	s_waitcnt vmcnt(15)
	v_and_b32_e32 v4, v242, v4
	v_and_b32_e32 v5, v242, v5
	v_and_b32_e32 v6, v242, v6
	v_and_b32_e32 v7, v242, v7
	v_lshlrev_b32_e32 v134, 16, v4
	v_and_b32_e32 v135, 0xffff0000, v4
	v_pk_fma_f32 v[70:71], v[232:233], v[134:135], v[70:71] op_sel_hi:[0,1,1]
	v_pk_fma_f32 v[70:71], v[86:87], v[70:71], v[144:145] op_sel_hi:[0,1,1] neg_lo:[0,0,1] neg_hi:[0,0,1]
	v_cvt_pk_bf16_f32 v4, v70, v71
	v_pk_fma_f32 v[70:71], v[234:235], v[36:37], v[72:73] op_sel_hi:[0,1,1]
	v_pk_fma_f32 v[70:71], v[234:235], v[142:143], v[70:71] op_sel_hi:[0,1,1]
	v_pk_fma_f32 v[70:71], v[228:229], v[146:147], v[70:71] op_sel_hi:[0,1,1]
	v_pk_fma_f32 v[70:71], v[230:231], v[118:119], v[70:71] op_sel_hi:[0,1,1]
	v_pk_fma_f32 v[70:71], v[230:231], v[98:99], v[70:71] op_sel_hi:[0,1,1]
	v_pk_fma_f32 v[70:71], v[232:233], v[102:103], v[70:71] op_sel_hi:[0,1,1]
	v_pk_fma_f32 v[70:71], v[232:233], v[92:93], v[70:71] op_sel_hi:[0,1,1]
	v_pk_fma_f32 v[70:71], v[232:233], v[80:81], v[70:71] op_sel_hi:[0,1,1]
	v_lshlrev_b32_e32 v72, 16, v5
	v_and_b32_e32 v73, 0xffff0000, v5
	v_pk_fma_f32 v[70:71], v[232:233], v[72:73], v[70:71] op_sel_hi:[0,1,1]
	v_pk_fma_f32 v[70:71], v[86:87], v[70:71], v[142:143] op_sel_hi:[0,1,1] neg_lo:[0,0,1] neg_hi:[0,0,1]
	v_cvt_pk_bf16_f32 v5, v70, v71
	v_pk_fma_f32 v[70:71], v[234:235], v[150:151], v[132:133] op_sel_hi:[0,1,1]
	v_pk_fma_f32 v[10:11], v[234:235], v[38:39], v[10:11] op_sel_hi:[0,1,1]
	v_pk_fma_f32 v[70:71], v[234:235], v[140:141], v[70:71] op_sel_hi:[0,1,1]
	v_pk_fma_f32 v[10:11], v[234:235], v[32:33], v[10:11] op_sel_hi:[0,1,1]
	v_pk_fma_f32 v[70:71], v[228:229], v[34:35], v[70:71] op_sel_hi:[0,1,1]
	v_pk_fma_f32 v[10:11], v[228:229], v[28:29], v[10:11] op_sel_hi:[0,1,1]
	v_pk_fma_f32 v[70:71], v[230:231], v[30:31], v[70:71] op_sel_hi:[0,1,1]
	v_pk_fma_f32 v[10:11], v[230:231], v[24:25], v[10:11] op_sel_hi:[0,1,1]
	v_pk_fma_f32 v[70:71], v[230:231], v[26:27], v[70:71] op_sel_hi:[0,1,1]
	v_pk_fma_f32 v[10:11], v[230:231], v[20:21], v[10:11] op_sel_hi:[0,1,1]
	v_pk_fma_f32 v[70:71], v[232:233], v[22:23], v[70:71] op_sel_hi:[0,1,1]
	v_pk_fma_f32 v[10:11], v[232:233], v[16:17], v[10:11] op_sel_hi:[0,1,1]
	v_pk_fma_f32 v[70:71], v[232:233], v[18:19], v[70:71] op_sel_hi:[0,1,1]
	v_pk_fma_f32 v[10:11], v[232:233], v[12:13], v[10:11] op_sel_hi:[0,1,1]
	v_pk_fma_f32 v[132:133], v[232:233], v[14:15], v[70:71] op_sel_hi:[0,1,1]
	v_lshlrev_b32_e32 v70, 16, v6
	v_and_b32_e32 v71, 0xffff0000, v6
	v_pk_fma_f32 v[88:89], v[232:233], v[8:9], v[10:11] op_sel_hi:[0,1,1]
	v_lshlrev_b32_e32 v10, 16, v7
; __device__ __forceinline__ unsigned cvt_pk_bf16(float lo, float hi) { const f32x2 v = (f32x2){lo, hi}; return __builtin_bit_cast(unsigned, __builtin_convertvector(v, bf16v2)); }
; __device__ __forceinline__ float bf_lo(unsigned w) { return __uint_as_float(w << 16); }
; __device__ __forceinline__ float bf_hi(unsigned w) { return __uint_as_float(w & 0xffff0000u); }
; __device__ __forceinline__ void phase_mixer(const Params& p, LAS unsigned char* lds, int l, bool with_ctx, int G, int tid, int wave, int lane, int rep_attn, int rep_pool) {
;     ...
;         for (int o = 0; o < 16; ++o) {
;             const int t = t0 + o, st = max(t - lo, 0), en = min(t + hi + 1, len);
;             float acc[8];
; #pragma unroll
;             for (int e = 0; e < 8; ++e) acc[e] = 0.f;
; #pragma unroll
;             for (int i = 0; i < 16; ++i) { const int tt = t + i - 8; const float wt = (tt >= st && tt < en) ? 1.f : 0.f; const u32x4 ww = w[o + i];
;                 acc[0] += wt * bf_lo(ww.x); acc[1] += wt * bf_hi(ww.x); acc[2] += wt * bf_lo(ww.y); acc[3] += wt * bf_hi(ww.y);
;                 acc[4] += wt * bf_lo(ww.z); acc[5] += wt * bf_hi(ww.z); acc[6] += wt * bf_lo(ww.w); acc[7] += wt * bf_hi(ww.w); }
;             const float ic = 1.f / (float)(en - st);
;             const u32x4 sw = w[o + 8];
;             u32x4 ov; ov.x = cvt_pk_bf16(acc[0] * ic - bf_lo(sw.x), acc[1] * ic - bf_hi(sw.x)); ov.y = cvt_pk_bf16(acc[2] * ic - bf_lo(sw.y), acc[3] * ic - bf_hi(sw.y));
;             ov.z = cvt_pk_bf16(acc[4] * ic - bf_lo(sw.z), acc[5] * ic - bf_hi(sw.z)); ov.w = cvt_pk_bf16(acc[6] * ic - bf_lo(sw.w), acc[7] * ic - bf_hi(sw.w));
;             *(u32x4*)(MIX + (size_t)(tok0 + o) * DM + 8 * lane) = ov;
	v_and_b32_e32 v11, 0xffff0000, v7
	v_pk_fma_f32 v[132:133], v[232:233], v[70:71], v[132:133] op_sel_hi:[0,1,1]
	v_pk_fma_f32 v[76:77], v[232:233], v[10:11], v[88:89] op_sel_hi:[0,1,1]
	v_pk_fma_f32 v[132:133], v[86:87], v[132:133], v[140:141] op_sel_hi:[0,1,1] neg_lo:[0,0,1] neg_hi:[0,0,1]
	v_pk_fma_f32 v[76:77], v[86:87], v[76:77], v[32:33] op_sel_hi:[0,1,1] neg_lo:[0,0,1] neg_hi:[0,0,1]
	v_cvt_pk_bf16_f32 v6, v132, v133
	v_cvt_pk_bf16_f32 v7, v76, v77
	v_lshl_add_u64 v[76:77], v[126:127], 0, s[0:1]
	global_store_dwordx4 v[76:77], v[4:7], off
	s_nop 1
	v_sub_u32_e32 v4, s18, v167
	v_add_u32_e32 v5, s18, v167
	v_max_i32_e32 v7, 0, v4
	v_min_i32_e32 v77, s9, v5
	v_pk_fma_f32 v[84:85], v[232:233], v[84:85], 0 op_sel_hi:[0,1,0]
	v_pk_fma_f32 v[60:61], v[232:233], v[60:61], v[84:85] op_sel_hi:[0,1,1]
	v_pk_fma_f32 v[60:61], v[232:233], v[74:75], v[60:61] op_sel_hi:[0,1,1]
	v_pk_fma_f32 v[60:61], v[232:233], v[106:107], v[60:61] op_sel_hi:[0,1,1]
	v_pk_fma_f32 v[60:61], v[230:231], v[120:121], v[60:61] op_sel_hi:[0,1,1]
	v_pk_fma_f32 v[60:61], v[230:231], v[136:137], v[60:61] op_sel_hi:[0,1,1]
	v_pk_fma_f32 v[74:75], v[228:229], v[148:149], v[60:61] op_sel_hi:[0,1,1]
	v_pk_fma_f32 v[60:61], v[232:233], v[64:65], 0 op_sel_hi:[0,1,0]
	v_pk_fma_f32 v[56:57], v[232:233], v[56:57], v[60:61] op_sel_hi:[0,1,1]
	v_pk_fma_f32 v[52:53], v[232:233], v[52:53], v[56:57] op_sel_hi:[0,1,1]
	v_pk_fma_f32 v[48:49], v[232:233], v[48:49], v[52:53] op_sel_hi:[0,1,1]
	v_pk_fma_f32 v[44:45], v[230:231], v[44:45], v[48:49] op_sel_hi:[0,1,1]
	v_pk_fma_f32 v[40:41], v[230:231], v[40:41], v[44:45] op_sel_hi:[0,1,1]
	v_pk_fma_f32 v[60:61], v[228:229], v[36:37], v[40:41] op_sel_hi:[0,1,1]
	v_pk_fma_f32 v[36:37], v[232:233], v[68:69], 0 op_sel_hi:[0,1,0]
	v_pk_fma_f32 v[4:5], v[232:233], v[66:67], 0 op_sel_hi:[0,1,0]
	v_pk_fma_f32 v[36:37], v[232:233], v[62:63], v[36:37] op_sel_hi:[0,1,1]
	v_pk_fma_f32 v[4:5], v[232:233], v[58:59], v[4:5] op_sel_hi:[0,1,1]
	v_pk_fma_f32 v[36:37], v[232:233], v[78:79], v[36:37] op_sel_hi:[0,1,1]
	v_pk_fma_f32 v[4:5], v[232:233], v[54:55], v[4:5] op_sel_hi:[0,1,1]
	v_pk_fma_f32 v[36:37], v[232:233], v[108:109], v[36:37] op_sel_hi:[0,1,1]
	v_pk_fma_f32 v[4:5], v[232:233], v[50:51], v[4:5] op_sel_hi:[0,1,1]
	v_pk_fma_f32 v[36:37], v[230:231], v[122:123], v[36:37] op_sel_hi:[0,1,1]
	v_pk_fma_f32 v[4:5], v[230:231], v[46:47], v[4:5] op_sel_hi:[0,1,1]
	v_pk_fma_f32 v[36:37], v[230:231], v[138:139], v[36:37] op_sel_hi:[0,1,1]
	v_pk_fma_f32 v[4:5], v[230:231], v[42:43], v[4:5] op_sel_hi:[0,1,1]
	v_pk_fma_f32 v[56:57], v[228:229], v[150:151], v[36:37] op_sel_hi:[0,1,1]
	v_pk_fma_f32 v[36:37], v[228:229], v[38:39], v[4:5] op_sel_hi:[0,1,1]
	v_sub_u32_e32 v5, v77, v7
	v_cvt_f32_i32_e32 v5, v5
	s_waitcnt vmcnt(15)
	v_and_b32_e32 v0, v242, v0
	v_and_b32_e32 v1, v242, v1
	v_and_b32_e32 v2, v242, v2
	v_and_b32_e32 v3, v242, v3
	v_lshlrev_b32_e32 v58, 16, v0
	v_div_scale_f32 v6, s[0:1], v5, v5, 1.0
	v_rcp_f32_e32 v7, v6
	v_and_b32_e32 v59, 0xffff0000, v0
	s_or_b32 s0, s4, 15
	s_ashr_i32 s1, s0, 31
	v_fma_f32 v39, -v6, v7, 1.0
	v_fmac_f32_e32 v7, v39, v7
	v_div_scale_f32 v39, vcc, 1.0, v5, 1.0
	v_mul_f32_e32 v41, v39, v7
	v_fma_f32 v43, -v6, v41, v39
	v_fmac_f32_e32 v41, v43, v7
	v_pk_fma_f32 v[54:55], v[234:235], v[144:145], v[74:75] op_sel_hi:[0,1,1]
	v_pk_fma_f32 v[54:55], v[234:235], v[152:153], v[54:55] op_sel_hi:[0,1,1]
	v_pk_fma_f32 v[54:55], v[228:229], v[128:129], v[54:55] op_sel_hi:[0,1,1]
	v_pk_fma_f32 v[54:55], v[230:231], v[100:101], v[54:55] op_sel_hi:[0,1,1]
	v_pk_fma_f32 v[54:55], v[230:231], v[104:105], v[54:55] op_sel_hi:[0,1,1]
	v_pk_fma_f32 v[54:55], v[232:233], v[94:95], v[54:55] op_sel_hi:[0,1,1]
	v_fma_f32 v6, -v6, v41, v39
	v_pk_fma_f32 v[54:55], v[232:233], v[82:83], v[54:55] op_sel_hi:[0,1,1]
	v_div_fmas_f32 v6, v6, v7, v41
	v_pk_fma_f32 v[54:55], v[232:233], v[134:135], v[54:55] op_sel_hi:[0,1,1]
	v_div_fixup_f32 v6, v6, v5, 1.0
	v_pk_fma_f32 v[54:55], v[232:233], v[58:59], v[54:55] op_sel_hi:[0,1,1]
	v_pk_fma_f32 v[54:55], v[6:7], v[54:55], v[152:153] op_sel_hi:[0,1,1] neg_lo:[0,0,1] neg_hi:[0,0,1]
	v_cvt_pk_bf16_f32 v0, v54, v55
	v_pk_fma_f32 v[54:55], v[234:235], v[142:143], v[60:61] op_sel_hi:[0,1,1]
	v_pk_fma_f32 v[54:55], v[234:235], v[146:147], v[54:55] op_sel_hi:[0,1,1]
	v_pk_fma_f32 v[54:55], v[228:229], v[118:119], v[54:55] op_sel_hi:[0,1,1]
	v_pk_fma_f32 v[54:55], v[230:231], v[98:99], v[54:55] op_sel_hi:[0,1,1]
	v_pk_fma_f32 v[54:55], v[230:231], v[102:103], v[54:55] op_sel_hi:[0,1,1]
	v_pk_fma_f32 v[54:55], v[232:233], v[92:93], v[54:55] op_sel_hi:[0,1,1]
	v_pk_fma_f32 v[54:55], v[232:233], v[80:81], v[54:55] op_sel_hi:[0,1,1]
	v_pk_fma_f32 v[54:55], v[232:233], v[72:73], v[54:55] op_sel_hi:[0,1,1]
	v_lshlrev_b32_e32 v58, 16, v1
	v_and_b32_e32 v59, 0xffff0000, v1
	v_pk_fma_f32 v[54:55], v[232:233], v[58:59], v[54:55] op_sel_hi:[0,1,1]
	v_pk_fma_f32 v[54:55], v[6:7], v[54:55], v[146:147] op_sel_hi:[0,1,1] neg_lo:[0,0,1] neg_hi:[0,0,1]
	v_cvt_pk_bf16_f32 v1, v54, v55
	v_pk_fma_f32 v[54:55], v[234:235], v[140:141], v[56:57] op_sel_hi:[0,1,1]
	v_pk_fma_f32 v[54:55], v[234:235], v[34:35], v[54:55] op_sel_hi:[0,1,1]
	v_pk_fma_f32 v[30:31], v[228:229], v[30:31], v[54:55] op_sel_hi:[0,1,1]
	v_pk_fma_f32 v[26:27], v[230:231], v[26:27], v[30:31] op_sel_hi:[0,1,1]
	v_pk_fma_f32 v[22:23], v[230:231], v[22:23], v[26:27] op_sel_hi:[0,1,1]
	v_pk_fma_f32 v[18:19], v[232:233], v[18:19], v[22:23] op_sel_hi:[0,1,1]
	v_pk_fma_f32 v[14:15], v[232:233], v[14:15], v[18:19] op_sel_hi:[0,1,1]
	v_pk_fma_f32 v[14:15], v[232:233], v[70:71], v[14:15] op_sel_hi:[0,1,1]
	v_lshlrev_b32_e32 v18, 16, v2
	v_and_b32_e32 v19, 0xffff0000, v2
	v_pk_fma_f32 v[14:15], v[232:233], v[18:19], v[14:15] op_sel_hi:[0,1,1]
	v_pk_fma_f32 v[14:15], v[6:7], v[14:15], v[34:35] op_sel_hi:[0,1,1] neg_lo:[0,0,1] neg_hi:[0,0,1]
	v_cvt_pk_bf16_f32 v2, v14, v15
	v_pk_fma_f32 v[14:15], v[234:235], v[32:33], v[36:37] op_sel_hi:[0,1,1]
	v_pk_fma_f32 v[14:15], v[234:235], v[28:29], v[14:15] op_sel_hi:[0,1,1]
	v_pk_fma_f32 v[14:15], v[228:229], v[24:25], v[14:15] op_sel_hi:[0,1,1]
	v_pk_fma_f32 v[14:15], v[230:231], v[20:21], v[14:15] op_sel_hi:[0,1,1]
	v_pk_fma_f32 v[14:15], v[230:231], v[16:17], v[14:15] op_sel_hi:[0,1,1]
	v_pk_fma_f32 v[12:13], v[232:233], v[12:13], v[14:15] op_sel_hi:[0,1,1]
	v_pk_fma_f32 v[8:9], v[232:233], v[8:9], v[12:13] op_sel_hi:[0,1,1]
	v_pk_fma_f32 v[8:9], v[232:233], v[10:11], v[8:9] op_sel_hi:[0,1,1]
	v_lshlrev_b32_e32 v10, 16, v3
	v_and_b32_e32 v11, 0xffff0000, v3
	v_pk_fma_f32 v[4:5], v[232:233], v[10:11], v[8:9] op_sel_hi:[0,1,1]
	v_pk_fma_f32 v[4:5], v[6:7], v[4:5], v[28:29] op_sel_hi:[0,1,1] neg_lo:[0,0,1] neg_hi:[0,0,1]
	s_lshl_b64 s[0:1], s[0:1], 11
	v_cvt_pk_bf16_f32 v3, v4, v5
	v_lshl_add_u64 v[4:5], v[126:127], 0, s[0:1]
	s_cmp_lt_i32 s6, s7
	global_store_dwordx4 v[4:5], v[0:3], off
	s_cbranch_scc1 .LBB0_308
